# P0 mod GEMV loop: 16 loads in flight; plus rcp-based sigmoid, lean log in logsig, L2 prefetch of next gla unit
# speedup vs baseline: 1.0457x; 1.0126x over previous
.LBB0_22:
	v_and_b32_e32 v0, 0x3ff, v8
	v_lshlrev_b32_e32 v0, 2, v0
	v_lshl_add_u64 v[10:11], s[70:71], 0, v[0:1]
	v_cmp_gt_u32_e32 vcc, s17, v8
	v_add_u32_e32 v9, 0x200, v8
	s_nop 0
	v_cndmask_b32_e32 v11, v11, v7, vcc
	v_cndmask_b32_e32 v10, v10, v6, vcc
	global_load_dword v0, v[10:11], off
	v_cmp_lt_u32_e32 vcc, s18, v8
	v_mov_b32_e32 v8, v9
	s_or_b64 s[10:11], vcc, s[10:11]
	v_lshl_add_u64 v[6:7], v[6:7], 0, s[8:9]
	s_waitcnt vmcnt(0)
	v_mul_f32_e32 v9, 0xbfb8aa3b, v0
	v_exp_f32_e32 v9, v9
	s_nop 0
	v_add_f32_e32 v9, 1.0, v9
	v_div_scale_f32 v10, s[12:13], v9, v9, v0
	v_rcp_f32_e32 v11, v10
	v_div_scale_f32 v12, vcc, v0, v9, v0
	v_fma_f32 v13, -v10, v11, 1.0
	v_fmac_f32_e32 v11, v13, v11
	v_mul_f32_e32 v13, v12, v11
	v_fma_f32 v14, -v10, v13, v12
	v_fmac_f32_e32 v13, v14, v11
	v_fma_f32 v10, -v10, v13, v12
	v_div_fmas_f32 v10, v10, v11, v13
	v_div_fixup_f32 v0, v10, v9, v0
	ds_write_b32 v5, v0
	v_add_u32_e32 v5, 0x800, v5
	s_andn2_b64 exec, exec, s[10:11]
	s_cbranch_execnz .LBB0_22
	s_or_b64 exec, exec, s[10:11]
	v_ashrrev_i32_e32 v5, 31, v4
	v_mov_b32_e32 v8, 0
	v_lshl_add_u64 v[6:7], v[4:5], 2, s[6:7]
	v_lshlrev_b32_e32 v68, 2, v4
	s_mov_b64 s[10:11], 0
	s_mov_b32 s12, s16
	v_mov_b32_e32 v9, v8
	v_mov_b32_e32 v10, v8
	v_mov_b32_e32 v11, v8
	v_mov_b32_e32 v12, v8
	v_mov_b32_e32 v13, v8
	v_mov_b32_e32 v14, v8
	v_mov_b32_e32 v15, v8
	v_mov_b32_e32 v0, v8
	s_waitcnt lgkmcnt(0)
	s_barrier
.LBB0_24:
	s_add_u32 s24, s6, s10
	s_addc_u32 s25, s7, s11
	global_load_dword v100, v68, s[24:25]
	s_add_u32 s24, s24, 0x6000
	s_addc_u32 s25, s25, 0
	global_load_dword v101, v68, s[24:25]
	s_add_u32 s24, s24, 0x6000
	s_addc_u32 s25, s25, 0
	global_load_dword v102, v68, s[24:25]
	s_add_u32 s24, s24, 0x6000
	s_addc_u32 s25, s25, 0
	global_load_dword v103, v68, s[24:25]
	s_add_u32 s24, s24, 0x6000
	s_addc_u32 s25, s25, 0
	global_load_dword v104, v68, s[24:25]
	s_add_u32 s24, s24, 0x6000
	s_addc_u32 s25, s25, 0
	global_load_dword v105, v68, s[24:25]
	s_add_u32 s24, s24, 0x6000
	s_addc_u32 s25, s25, 0
	global_load_dword v106, v68, s[24:25]
	s_add_u32 s24, s24, 0x6000
	s_addc_u32 s25, s25, 0
	global_load_dword v107, v68, s[24:25]
	s_add_u32 s24, s24, 0x6000
	s_addc_u32 s25, s25, 0
	global_load_dword v108, v68, s[24:25]
	s_add_u32 s24, s24, 0x6000
	s_addc_u32 s25, s25, 0
	global_load_dword v109, v68, s[24:25]
	s_add_u32 s24, s24, 0x6000
	s_addc_u32 s25, s25, 0
	global_load_dword v110, v68, s[24:25]
	s_add_u32 s24, s24, 0x6000
	s_addc_u32 s25, s25, 0
	global_load_dword v111, v68, s[24:25]
	s_add_u32 s24, s24, 0x6000
	s_addc_u32 s25, s25, 0
	global_load_dword v112, v68, s[24:25]
	s_add_u32 s24, s24, 0x6000
	s_addc_u32 s25, s25, 0
	global_load_dword v113, v68, s[24:25]
	s_add_u32 s24, s24, 0x6000
	s_addc_u32 s25, s25, 0
	global_load_dword v114, v68, s[24:25]
	s_add_u32 s24, s24, 0x6000
	s_addc_u32 s25, s25, 0
	global_load_dword v115, v68, s[24:25]
	v_mov_b32_e32 v5, s12
	ds_read_b128 v[50:53], v5
	ds_read_b128 v[22:25], v5 offset:4096
	ds_read_b128 v[26:29], v5 offset:8192
	ds_read_b128 v[30:33], v5 offset:12288
	ds_read_b128 v[34:37], v5 offset:16384
	ds_read_b128 v[38:41], v5 offset:20480
	ds_read_b128 v[42:45], v5 offset:24576
	ds_read_b128 v[46:49], v5 offset:28672
	ds_read_b128 v[54:57], v5 offset:32768
	s_waitcnt vmcnt(12) lgkmcnt(0)
	v_fmac_f32_e32 v8, v100, v50
	v_fmac_f32_e32 v9, v100, v22
	v_fmac_f32_e32 v10, v100, v26
	v_fmac_f32_e32 v11, v100, v30
	v_fmac_f32_e32 v12, v100, v34
	v_fmac_f32_e32 v13, v100, v38
	v_fmac_f32_e32 v14, v100, v42
	v_fmac_f32_e32 v15, v100, v46
	v_fmac_f32_e32 v0, v100, v54
	v_fmac_f32_e32 v8, v101, v51
	v_fmac_f32_e32 v9, v101, v23
	v_fmac_f32_e32 v10, v101, v27
	v_fmac_f32_e32 v11, v101, v31
	v_fmac_f32_e32 v12, v101, v35
	v_fmac_f32_e32 v13, v101, v39
	v_fmac_f32_e32 v14, v101, v43
	v_fmac_f32_e32 v15, v101, v47
	v_fmac_f32_e32 v0, v101, v55
	v_fmac_f32_e32 v8, v102, v52
	v_fmac_f32_e32 v9, v102, v24
	v_fmac_f32_e32 v10, v102, v28
	v_fmac_f32_e32 v11, v102, v32
	v_fmac_f32_e32 v12, v102, v36
	v_fmac_f32_e32 v13, v102, v40
	v_fmac_f32_e32 v14, v102, v44
	v_fmac_f32_e32 v15, v102, v48
	v_fmac_f32_e32 v0, v102, v56
	v_fmac_f32_e32 v8, v103, v53
	v_fmac_f32_e32 v9, v103, v25
	v_fmac_f32_e32 v10, v103, v29
	v_fmac_f32_e32 v11, v103, v33
	v_fmac_f32_e32 v12, v103, v37
	v_fmac_f32_e32 v13, v103, v41
	v_fmac_f32_e32 v14, v103, v45
	v_fmac_f32_e32 v15, v103, v49
	v_fmac_f32_e32 v0, v103, v57
	ds_read_b128 v[50:53], v5 offset:16
	ds_read_b128 v[22:25], v5 offset:4112
	ds_read_b128 v[26:29], v5 offset:8208
	ds_read_b128 v[30:33], v5 offset:12304
	ds_read_b128 v[34:37], v5 offset:16400
	ds_read_b128 v[38:41], v5 offset:20496
	ds_read_b128 v[42:45], v5 offset:24592
	ds_read_b128 v[46:49], v5 offset:28688
	ds_read_b128 v[54:57], v5 offset:32784
	s_waitcnt vmcnt(8) lgkmcnt(0)
	v_fmac_f32_e32 v8, v104, v50
	v_fmac_f32_e32 v9, v104, v22
	v_fmac_f32_e32 v10, v104, v26
	v_fmac_f32_e32 v11, v104, v30
	v_fmac_f32_e32 v12, v104, v34
	v_fmac_f32_e32 v13, v104, v38
	v_fmac_f32_e32 v14, v104, v42
	v_fmac_f32_e32 v15, v104, v46
	v_fmac_f32_e32 v0, v104, v54
	v_fmac_f32_e32 v8, v105, v51
	v_fmac_f32_e32 v9, v105, v23
	v_fmac_f32_e32 v10, v105, v27
	v_fmac_f32_e32 v11, v105, v31
	v_fmac_f32_e32 v12, v105, v35
	v_fmac_f32_e32 v13, v105, v39
	v_fmac_f32_e32 v14, v105, v43
	v_fmac_f32_e32 v15, v105, v47
	v_fmac_f32_e32 v0, v105, v55
	v_fmac_f32_e32 v8, v106, v52
	v_fmac_f32_e32 v9, v106, v24
	v_fmac_f32_e32 v10, v106, v28
	v_fmac_f32_e32 v11, v106, v32
	v_fmac_f32_e32 v12, v106, v36
	v_fmac_f32_e32 v13, v106, v40
	v_fmac_f32_e32 v14, v106, v44
	v_fmac_f32_e32 v15, v106, v48
	v_fmac_f32_e32 v0, v106, v56
	v_fmac_f32_e32 v8, v107, v53
	v_fmac_f32_e32 v9, v107, v25
	v_fmac_f32_e32 v10, v107, v29
	v_fmac_f32_e32 v11, v107, v33
	v_fmac_f32_e32 v12, v107, v37
	v_fmac_f32_e32 v13, v107, v41
	v_fmac_f32_e32 v14, v107, v45
	v_fmac_f32_e32 v15, v107, v49
	v_fmac_f32_e32 v0, v107, v57
	ds_read_b128 v[50:53], v5 offset:32
	ds_read_b128 v[22:25], v5 offset:4128
	ds_read_b128 v[26:29], v5 offset:8224
	ds_read_b128 v[30:33], v5 offset:12320
	ds_read_b128 v[34:37], v5 offset:16416
	ds_read_b128 v[38:41], v5 offset:20512
	ds_read_b128 v[42:45], v5 offset:24608
	ds_read_b128 v[46:49], v5 offset:28704
	ds_read_b128 v[54:57], v5 offset:32800
	s_waitcnt vmcnt(4) lgkmcnt(0)
	v_fmac_f32_e32 v8, v108, v50
	v_fmac_f32_e32 v9, v108, v22
	v_fmac_f32_e32 v10, v108, v26
	v_fmac_f32_e32 v11, v108, v30
	v_fmac_f32_e32 v12, v108, v34
	v_fmac_f32_e32 v13, v108, v38
	v_fmac_f32_e32 v14, v108, v42
	v_fmac_f32_e32 v15, v108, v46
	v_fmac_f32_e32 v0, v108, v54
	v_fmac_f32_e32 v8, v109, v51
	v_fmac_f32_e32 v9, v109, v23
	v_fmac_f32_e32 v10, v109, v27
	v_fmac_f32_e32 v11, v109, v31
	v_fmac_f32_e32 v12, v109, v35
	v_fmac_f32_e32 v13, v109, v39
	v_fmac_f32_e32 v14, v109, v43
	v_fmac_f32_e32 v15, v109, v47
	v_fmac_f32_e32 v0, v109, v55
	v_fmac_f32_e32 v8, v110, v52
	v_fmac_f32_e32 v9, v110, v24
	v_fmac_f32_e32 v10, v110, v28
	v_fmac_f32_e32 v11, v110, v32
	v_fmac_f32_e32 v12, v110, v36
	v_fmac_f32_e32 v13, v110, v40
	v_fmac_f32_e32 v14, v110, v44
	v_fmac_f32_e32 v15, v110, v48
	v_fmac_f32_e32 v0, v110, v56
	v_fmac_f32_e32 v8, v111, v53
	v_fmac_f32_e32 v9, v111, v25
	v_fmac_f32_e32 v10, v111, v29
	v_fmac_f32_e32 v11, v111, v33
	v_fmac_f32_e32 v12, v111, v37
	v_fmac_f32_e32 v13, v111, v41
	v_fmac_f32_e32 v14, v111, v45
	v_fmac_f32_e32 v15, v111, v49
	v_fmac_f32_e32 v0, v111, v57
	ds_read_b128 v[50:53], v5 offset:48
	ds_read_b128 v[22:25], v5 offset:4144
	ds_read_b128 v[26:29], v5 offset:8240
	ds_read_b128 v[30:33], v5 offset:12336
	ds_read_b128 v[34:37], v5 offset:16432
	ds_read_b128 v[38:41], v5 offset:20528
	ds_read_b128 v[42:45], v5 offset:24624
	ds_read_b128 v[46:49], v5 offset:28720
	ds_read_b128 v[54:57], v5 offset:32816
	s_waitcnt vmcnt(0) lgkmcnt(0)
	v_fmac_f32_e32 v8, v112, v50
	v_fmac_f32_e32 v9, v112, v22
	v_fmac_f32_e32 v10, v112, v26
	v_fmac_f32_e32 v11, v112, v30
	v_fmac_f32_e32 v12, v112, v34
	v_fmac_f32_e32 v13, v112, v38
	v_fmac_f32_e32 v14, v112, v42
	v_fmac_f32_e32 v15, v112, v46
	v_fmac_f32_e32 v0, v112, v54
	v_fmac_f32_e32 v8, v113, v51
	v_fmac_f32_e32 v9, v113, v23
	v_fmac_f32_e32 v10, v113, v27
	v_fmac_f32_e32 v11, v113, v31
	v_fmac_f32_e32 v12, v113, v35
	v_fmac_f32_e32 v13, v113, v39
	v_fmac_f32_e32 v14, v113, v43
	v_fmac_f32_e32 v15, v113, v47
	v_fmac_f32_e32 v0, v113, v55
	v_fmac_f32_e32 v8, v114, v52
	v_fmac_f32_e32 v9, v114, v24
	v_fmac_f32_e32 v10, v114, v28
	v_fmac_f32_e32 v11, v114, v32
	v_fmac_f32_e32 v12, v114, v36
	v_fmac_f32_e32 v13, v114, v40
	v_fmac_f32_e32 v14, v114, v44
	v_fmac_f32_e32 v15, v114, v48
	v_fmac_f32_e32 v0, v114, v56
	v_fmac_f32_e32 v8, v115, v53
	v_fmac_f32_e32 v9, v115, v25
	v_fmac_f32_e32 v10, v115, v29
	v_fmac_f32_e32 v11, v115, v33
	v_fmac_f32_e32 v12, v115, v37
	v_fmac_f32_e32 v13, v115, v41
	v_fmac_f32_e32 v14, v115, v45
	v_fmac_f32_e32 v15, v115, v49
	v_fmac_f32_e32 v0, v115, v57
	s_add_u32 s10, s10, 0x60000
	s_addc_u32 s11, s11, 0
	s_add_i32 s12, s12, 64
	s_cmp_eq_u32 s10, 0x300000
	s_cbranch_scc0 .LBB0_24
	ds_write2st64_b32 v20, v8, v9 offset0:144 offset1:145
	ds_write2st64_b32 v20, v10, v11 offset0:146 offset1:147
	ds_write2st64_b32 v20, v12, v13 offset0:148 offset1:149
	ds_write2st64_b32 v20, v14, v15 offset0:150 offset1:151
	ds_write_b32 v20, v0 offset:38912
	s_waitcnt lgkmcnt(0)
	s_barrier
	s_and_saveexec_b64 s[10:11], s[2:3]
	s_cbranch_execz .LBB0_20
	v_lshl_or_b32 v6, s21, 6, v144
	v_ashrrev_i32_e32 v7, 31, v6
	v_lshl_add_u64 v[6:7], v[6:7], 2, s[74:75]
	s_mov_b64 s[12:13], 0
	v_mov_b32_e32 v0, v19
	v_mov_b32_e32 v8, v18
	v_mov_b32_e32 v5, v17

.LBB0_653:
	s_or_b64 exec, exec, s[0:1]
	s_lshl_b32 s22, s44, 7
	s_or_b32 s45, s22, s34
	v_or_b32_e32 v6, s45, v34
	v_mov_b32_e32 v7, v31
	v_lshl_add_u64 v[6:7], v[6:7], 2, s[90:91]
	global_load_dword v5, v[6:7], off
	s_waitcnt vmcnt(0)
	v_mfma_f32_16x16x32_bf16 v[42:45], v[16:19], v[20:23], 0
	v_add_u32_e32 v28, 0x400, v126
	v_mfma_f32_16x16x32_bf16 v[46:49], v[12:15], v[20:23], 0
	s_nop 5
	v_add_f32_e32 v6, v5, v42
	v_add_f32_e32 v7, v5, v43
	v_min_f32_e32 v43, 0, v6
	v_mul_f32_e64 v6, |v6|, s38
	v_add_f32_e32 v27, v5, v44
	v_min_f32_e32 v44, 0, v7
	v_mul_f32_e64 v7, |v7|, s38
	v_exp_f32_e32 v6, v6
	v_add_f32_e32 v29, v5, v45
	v_min_f32_e32 v45, 0, v27
	v_mul_f32_e64 v27, |v27|, s38
	v_exp_f32_e32 v7, v7
	v_add_f32_e32 v41, v5, v46
	v_min_f32_e32 v46, 0, v29
	v_mul_f32_e64 v29, |v29|, s38
	v_exp_f32_e32 v27, v27
	v_exp_f32_e32 v29, v29
	v_add_f32_e32 v6, 1.0, v6
	v_add_f32_e32 v7, 1.0, v7
	v_add_f32_e32 v42, v5, v47
	v_min_f32_e32 v47, 0, v41
	v_mul_f32_e64 v41, |v41|, s38
	v_add_f32_e32 v27, 1.0, v27
	v_exp_f32_e32 v41, v41
	v_add_f32_e32 v29, 1.0, v29
	v_log_f32_e32 v6, v6
	v_log_f32_e32 v7, v7
	v_log_f32_e32 v27, v27
	v_add_f32_e32 v41, 1.0, v41
	v_log_f32_e32 v29, v29
	v_cmp_gt_f32_e64 s[16:17], s39, v41
	v_cndmask_b32_e64 v55, 0, 32, s[16:17]
	v_ldexp_f32 v41, v41, v55
	v_log_f32_e32 v41, v41
	v_mul_f32_e64 v50, |v42|, s38
	v_exp_f32_e32 v50, v50
	v_mul_f32_e32 v60, 0x3f317217, v41
	v_fma_f32 v60, v41, s40, -v60
	v_fma_f32 v6, -v6, s40, v43
	v_fma_f32 v7, -v7, s40, v44
	v_fmac_f32_e32 v60, 0x3377d1cf, v41
	v_fma_f32 v27, -v27, s40, v45
	v_fma_f32 v29, -v29, s40, v46
	v_mul_f32_e32 v6, 0x3d800000, v6
	v_mul_f32_e32 v7, 0x3d800000, v7
	v_fmac_f32_e32 v60, 0x3f317217, v41
	v_cmp_lt_f32_e64 vcc, |v41|, s41
	v_mul_f32_e32 v27, 0x3d800000, v27
	v_mul_f32_e32 v29, 0x3d800000, v29
	ds_write2_b32 v126, v6, v7 offset1:129
	ds_write2_b32 v28, v27, v29 offset0:2 offset1:131
	v_add_f32_e32 v7, 1.0, v50
	v_cndmask_b32_e32 v41, v41, v60, vcc
	v_cndmask_b32_e64 v55, 0, v125, s[16:17]
	v_sub_f32_e32 v6, v41, v55
	v_log_f32_e32 v7, v7
	v_add_f32_e32 v41, v5, v48
	v_min_f32_e32 v27, 0, v42
	v_mul_f32_e64 v42, |v41|, s38
	v_exp_f32_e32 v42, v42
	v_sub_f32_e32 v6, v47, v6
	v_mul_f32_e32 v6, 0x3d800000, v6
	v_fma_f32 v7, -v7, s40, v27
	v_add_f32_e32 v27, 1.0, v42
	v_cmp_gt_f32_e32 vcc, s39, v27
	v_mul_f32_e32 v7, 0x3d800000, v7
	s_nop 0
	v_cndmask_b32_e64 v29, 0, 32, vcc
	v_ldexp_f32 v27, v27, v29
	v_log_f32_e32 v27, v27
	v_add_u32_e32 v29, 0x2000, v126
	ds_write2_b32 v29, v6, v7 offset0:16 offset1:145
	v_min_f32_e32 v6, 0, v41
	v_add_f32_e32 v41, v5, v49
	v_mul_f32_e32 v7, 0x3f317217, v27
	v_mul_f32_e64 v42, |v41|, s38
	v_fma_f32 v7, v27, s40, -v7
	v_exp_f32_e32 v42, v42
	v_fmac_f32_e32 v7, 0x3377d1cf, v27
	v_fmac_f32_e32 v7, 0x3f317217, v27
	v_cmp_lt_f32_e64 s[0:1], |v27|, s41
	s_nop 1
	v_cndmask_b32_e64 v7, v27, v7, s[0:1]
	v_cndmask_b32_e32 v27, 0, v125, vcc
	v_sub_f32_e32 v7, v7, v27
	v_add_f32_e32 v27, 1.0, v42
	v_sub_f32_e32 v6, v6, v7
	v_min_f32_e32 v7, 0, v41
	v_log_f32_e32 v27, v27
	v_mfma_f32_16x16x32_bf16 v[42:45], v[8:11], v[20:23], 0
	v_mul_f32_e32 v6, 0x3d800000, v6
	s_nop 3
	s_nop 2
	v_add_f32_e32 v42, v5, v42
	v_mul_f32_e64 v46, |v42|, s38
	v_exp_f32_e32 v46, v46
	v_mfma_f32_16x16x32_bf16 v[20:23], v[0:3], v[20:23], 0
	s_nop 0
	v_fma_f32 v7, -v27, s40, v7
	v_add_f32_e32 v27, 1.0, v46
	v_cmp_gt_f32_e32 vcc, s39, v27
	v_mul_f32_e32 v7, 0x3d800000, v7
	s_nop 2
	v_add_f32_e32 v21, v5, v21
	v_cndmask_b32_e64 v41, 0, 32, vcc
	v_ldexp_f32 v27, v27, v41
	v_log_f32_e32 v27, v27
	v_add_u32_e32 v41, 0x2400, v126
	ds_write2_b32 v41, v6, v7 offset0:18 offset1:147
	v_min_f32_e32 v6, 0, v42
	v_add_f32_e32 v42, v5, v43
	v_mul_f32_e32 v7, 0x3f317217, v27
	v_mul_f32_e64 v43, |v42|, s38
	v_fma_f32 v7, v27, s40, -v7
	v_exp_f32_e32 v43, v43
	v_fmac_f32_e32 v7, 0x3377d1cf, v27
	v_fmac_f32_e32 v7, 0x3f317217, v27
	v_cmp_lt_f32_e64 s[0:1], |v27|, s41
	v_add_f32_e32 v22, v5, v22
	s_nop 0
	v_cndmask_b32_e64 v7, v27, v7, s[0:1]
	v_cndmask_b32_e32 v27, 0, v125, vcc
	v_sub_f32_e32 v7, v7, v27
	v_add_f32_e32 v27, 1.0, v43
	v_sub_f32_e32 v6, v6, v7
	v_min_f32_e32 v7, 0, v42
	v_log_f32_e32 v27, v27
	v_add_f32_e32 v43, v5, v44
	v_mul_f32_e64 v44, |v43|, s38
	v_exp_f32_e32 v44, v44
	v_mul_f32_e32 v6, 0x3d800000, v6
	s_nop 0
	v_fma_f32 v7, -v27, s40, v7
	v_add_f32_e32 v27, 1.0, v44
	v_cmp_gt_f32_e32 vcc, s39, v27
	v_mul_f32_e32 v7, 0x3d800000, v7
	s_nop 0
	v_cndmask_b32_e64 v42, 0, 32, vcc
	v_ldexp_f32 v27, v27, v42
	v_log_f32_e32 v27, v27
	v_add_u32_e32 v42, 0x4000, v126
	ds_write2_b32 v42, v6, v7 offset0:32 offset1:161
	v_min_f32_e32 v6, 0, v43
	v_add_f32_e32 v43, v5, v45
	v_mul_f32_e32 v7, 0x3f317217, v27
	v_mul_f32_e64 v44, |v43|, s38
	v_fma_f32 v7, v27, s40, -v7
	v_exp_f32_e32 v44, v44
	v_fmac_f32_e32 v7, 0x3377d1cf, v27
	v_fmac_f32_e32 v7, 0x3f317217, v27
	v_cmp_lt_f32_e64 s[0:1], |v27|, s41
	s_nop 1
	v_cndmask_b32_e64 v7, v27, v7, s[0:1]
	v_cndmask_b32_e32 v27, 0, v125, vcc
	v_sub_f32_e32 v7, v7, v27
	v_add_f32_e32 v27, 1.0, v44
	v_sub_f32_e32 v6, v6, v7
	v_min_f32_e32 v7, 0, v43
	v_log_f32_e32 v27, v27
	v_add_f32_e32 v44, v5, v20
	v_mul_f32_e64 v20, |v44|, s38
	v_exp_f32_e32 v20, v20
	s_nop 0
	v_add_f32_e32 v20, 1.0, v20
	v_mul_f32_e32 v6, 0x3d800000, v6
	v_cmp_gt_f32_e32 vcc, s39, v20
	v_fma_f32 v7, -v27, s40, v7
	v_mul_f32_e32 v7, 0x3d800000, v7
	v_cndmask_b32_e64 v27, 0, 32, vcc
	v_ldexp_f32 v20, v20, v27
	v_log_f32_e32 v27, v20
	v_add_u32_e32 v20, 0x4400, v126
	ds_write2_b32 v20, v6, v7 offset0:34 offset1:163
	v_mul_f32_e64 v43, |v21|, s38
	v_mul_f32_e32 v7, 0x3f317217, v27
	v_fma_f32 v7, v27, s40, -v7
	v_exp_f32_e32 v43, v43
	v_fmac_f32_e32 v7, 0x3377d1cf, v27
	v_fmac_f32_e32 v7, 0x3f317217, v27
	v_cmp_lt_f32_e64 s[0:1], |v27|, s41
	v_min_f32_e32 v6, 0, v44
	v_add_f32_e32 v5, v5, v23
	v_cndmask_b32_e64 v7, v27, v7, s[0:1]
	v_cndmask_b32_e32 v27, 0, v125, vcc
	v_sub_f32_e32 v7, v7, v27
	v_add_f32_e32 v27, 1.0, v43
	v_sub_f32_e32 v6, v6, v7
	v_min_f32_e32 v7, 0, v21
	v_log_f32_e32 v27, v27
	v_mul_f32_e64 v43, |v22|, s38
	v_exp_f32_e32 v43, v43
	v_mul_f32_e32 v6, 0x3d800000, v6
	s_nop 1
	v_fma_f32 v7, -v27, s40, v7
	v_add_f32_e32 v21, 1.0, v43
	v_mul_f32_e32 v7, 0x3d800000, v7
	s_nop 0
	v_log_f32_e32 v27, v21
	v_add_u32_e32 v21, 0x6000, v126
	ds_write2_b32 v21, v6, v7 offset0:48 offset1:177
	v_min_f32_e32 v6, 0, v22
	v_mul_f32_e64 v22, |v5|, s38
	v_exp_f32_e32 v22, v22
	s_nop 0
	v_add_f32_e32 v22, 1.0, v22
	v_fma_f32 v6, -v27, s40, v6
	v_log_f32_e32 v22, v22
	v_min_f32_e32 v5, 0, v5
	v_mul_f32_e32 v6, 0x3d800000, v6
	s_nop 1
	v_fma_f32 v5, -v22, s40, v5
	v_mul_f32_e32 v5, 0x3d800000, v5
	v_add_u32_e32 v22, 0x6400, v126
	ds_write2_b32 v22, v6, v5 offset0:50 offset1:179
	v_mov_b32_e32 v5, 0
	v_mov_b32_e32 v6, 0
	v_mov_b32_e32 v7, 0
	s_and_saveexec_b64 s[0:1], s[2:3]
	s_cbranch_execz .LBB0_655
	v_mov_b32_e32 v27, v31
	v_lshl_add_u64 v[4:5], v[24:25], 0, v[26:27]
	v_add_co_u32_e32 v6, vcc, 0x1000, v4
	s_nop 1
	v_addc_co_u32_e32 v7, vcc, 0, v5, vcc
	v_add_co_u32_e32 v24, vcc, 0x2000, v4
	s_nop 1
	v_addc_co_u32_e32 v25, vcc, 0, v5, vcc
	v_add_co_u32_e32 v26, vcc, 0x3000, v4
	s_nop 1
	v_addc_co_u32_e32 v27, vcc, 0, v5, vcc
	global_load_dword v23, v[4:5], off offset:64
	s_nop 0
	global_load_dword v4, v[4:5], off offset:2112
	s_nop 0
	global_load_dword v5, v[6:7], off offset:64
	s_nop 0
	global_load_dword v6, v[6:7], off offset:2112
	s_nop 0
	global_load_dword v7, v[24:25], off offset:64
	s_nop 0
	global_load_dword v24, v[24:25], off offset:2112
	s_nop 0
	global_load_dword v25, v[26:27], off offset:64
	s_nop 0
	global_load_dword v26, v[26:27], off offset:2112
	s_waitcnt vmcnt(6)
	v_cvt_pk_bf16_f32 v4, v23, v4
	s_waitcnt vmcnt(4)
	v_cvt_pk_bf16_f32 v5, v5, v6
	s_waitcnt vmcnt(2)
	v_cvt_pk_bf16_f32 v6, v7, v24
	s_waitcnt vmcnt(0)
	v_cvt_pk_bf16_f32 v7, v25, v26
.LBB0_655:
	s_or_b64 exec, exec, s[0:1]
	v_add_u32_e32 v24, s45, v34
	v_mov_b32_e32 v25, v31
	v_lshl_add_u64 v[24:25], v[24:25], 2, s[90:91]
	global_load_dword v23, v[24:25], off offset:64
	v_mfma_f32_16x16x32_bf16 v[16:19], v[16:19], v[4:7], 0
	v_add_u32_e32 v129, 0x800, v127
	v_add_u32_e32 v130, 0xc00, v127
	v_add_u32_e32 v132, 0x1000, v127
	v_mfma_f32_16x16x32_bf16 v[12:15], v[12:15], v[4:7], 0
	v_add_u32_e32 v135, 0x1400, v127
	v_add_u32_e32 v138, 0x1800, v127
	v_add_u32_e32 v133, 0x1c00, v127
	v_mfma_f32_16x16x32_bf16 v[8:11], v[8:11], v[4:7], 0
	v_add_u32_e32 v136, 0x2000, v127
	v_add_u32_e32 v139, 0x2400, v127
	v_add_u32_e32 v141, 0x2800, v127
	v_mfma_f32_16x16x32_bf16 v[0:3], v[0:3], v[4:7], 0
	v_add_u32_e32 v142, 0x2c00, v127
	v_add_u32_e32 v140, 0x3000, v127
	v_add_u32_e32 v137, 0x3400, v127
	v_add_u32_e32 v134, 0x3800, v127
	v_add_u32_e32 v131, 0x3c00, v127
	s_waitcnt vmcnt(0)
	s_add_i32 s98, s30, s72
	s_cmpk_lt_i32 s98, 0x880
	s_cbranch_scc0 .Lpf_a_skip
	s_cmpk_gt_i32 s98, 0x7ff
	s_cbranch_scc1 .Lpf_a_ctx
	s_lshr_b32 s99, s98, 8
	s_bfe_u32 s100, s98, 0x20006
	s_and_b32 s101, s98, 63
	s_lshl_b32 s99, s99, 12
	s_branch .Lpf_a_go
.Lpf_a_ctx:
	s_addk_i32 s98, 0xf800
	s_lshr_b32 s99, s98, 4
	s_bfe_u32 s100, s98, 0x20002
	s_and_b32 s101, s98, 3
	s_lshl_b32 s99, s99, 8
	s_add_i32 s99, s99, 0x8000
.Lpf_a_go:
	s_lshl_b32 s101, s101, 6
	s_add_i32 s99, s99, s101
	s_lshl_b32 s100, s100, 8
	v_add_u32_e32 v245, s99, v144
	v_mul_u32_u24_e32 v245, 0x2600, v245
	v_lshrrev_b32_e32 v246, 6, v145
	v_lshlrev_b32_e32 v247, 6, v246
	v_lshrrev_b32_e32 v246, 2, v246
	v_mul_u32_u24_e32 v246, 0x300, v246
	v_add3_u32 v247, v247, v246, s100
	v_add_u32_e32 v247, v247, v245
	s_add_u32 s98, s54, 0x6800000
	s_addc_u32 s99, s55, 0
	global_load_dword v240, v247, s[98:99] offset:2368
	v_add_u32_e32 v245, 0x1540, v245
	global_load_dword v240, v245, s[98:99]
.Lpf_a_skip:
	v_add_f32_e32 v16, v23, v16
	v_add_f32_e32 v17, v23, v17
	v_min_f32_e32 v24, 0, v16
	v_mul_f32_e64 v16, |v16|, s38
	v_add_f32_e32 v18, v23, v18
	v_min_f32_e32 v25, 0, v17
	v_mul_f32_e64 v17, |v17|, s38
	v_exp_f32_e32 v16, v16
	v_add_f32_e32 v19, v23, v19
	v_min_f32_e32 v26, 0, v18
	v_mul_f32_e64 v18, |v18|, s38
	v_exp_f32_e32 v17, v17
	v_min_f32_e32 v27, 0, v19
	v_mul_f32_e64 v19, |v19|, s38
	v_exp_f32_e32 v18, v18
	v_exp_f32_e32 v19, v19
	v_add_f32_e32 v16, 1.0, v16
	v_add_f32_e32 v12, v23, v12
	v_add_f32_e32 v17, 1.0, v17
	v_min_f32_e32 v43, 0, v12
	v_mul_f32_e64 v12, |v12|, s38
	v_add_f32_e32 v18, 1.0, v18
	v_exp_f32_e32 v12, v12
	v_add_f32_e32 v19, 1.0, v19
	v_log_f32_e32 v16, v16
	v_log_f32_e32 v17, v17
	v_log_f32_e32 v18, v18
	v_add_f32_e32 v12, 1.0, v12
	v_log_f32_e32 v19, v19
	v_log_f32_e32 v12, v12
	v_add_f32_e32 v13, v23, v13
	v_mul_f32_e64 v44, |v13|, s38
	v_exp_f32_e32 v44, v44
	v_fma_f32 v16, -v16, s40, v24
	v_fma_f32 v17, -v17, s40, v25
	v_fma_f32 v18, -v18, s40, v26
	v_fma_f32 v19, -v19, s40, v27
	v_mul_f32_e32 v16, 0x3d800000, v16
	v_mul_f32_e32 v17, 0x3d800000, v17
	v_mul_f32_e32 v18, 0x3d800000, v18
	v_mul_f32_e32 v19, 0x3d800000, v19
	ds_write2_b32 v126, v16, v17 offset0:16 offset1:145
	ds_write2_b32 v28, v18, v19 offset0:18 offset1:147
	v_add_f32_e32 v16, 1.0, v44
	v_add_f32_e32 v14, v23, v14
	v_min_f32_e32 v13, 0, v13
	v_log_f32_e32 v16, v16
	v_fma_f32 v12, -v12, s40, v43
	v_mul_f32_e32 v12, 0x3d800000, v12
	v_mul_f32_e64 v17, |v14|, s38
	v_exp_f32_e32 v17, v17
	v_fma_f32 v13, -v16, s40, v13
	v_mul_f32_e32 v13, 0x3d800000, v13
	v_add_f32_e32 v16, 1.0, v17
	ds_write2_b32 v29, v12, v13 offset0:32 offset1:161
	v_min_f32_e32 v12, 0, v14
	v_log_f32_e32 v16, v16
	v_add_f32_e32 v14, v23, v15
	v_mul_f32_e64 v15, |v14|, s38
	v_exp_f32_e32 v15, v15
	s_nop 0
	v_add_f32_e32 v15, 1.0, v15
	v_add_f32_e32 v8, v23, v8
	v_cmp_gt_f32_e32 vcc, s39, v15
	v_fma_f32 v12, -v16, s40, v12
	v_cndmask_b32_e64 v16, 0, 32, vcc
	v_ldexp_f32 v15, v15, v16
	v_log_f32_e32 v15, v15
	v_min_f32_e32 v13, 0, v14
	v_cndmask_b32_e32 v16, 0, v125, vcc
	v_mul_f32_e32 v12, 0x3d800000, v12
	v_mul_f32_e32 v14, 0x3f317217, v15
	v_fma_f32 v14, v15, s40, -v14
	v_fmac_f32_e32 v14, 0x3377d1cf, v15
	v_fmac_f32_e32 v14, 0x3f317217, v15
	v_cmp_lt_f32_e64 s[0:1], |v15|, s41
	v_add_f32_e32 v9, v23, v9
	v_add_f32_e32 v10, v23, v10
	v_cndmask_b32_e64 v14, v15, v14, s[0:1]
	v_mul_f32_e64 v15, |v8|, s38
	v_exp_f32_e32 v15, v15
	v_sub_f32_e32 v14, v14, v16
	v_sub_f32_e32 v13, v13, v14
	v_mul_f32_e32 v13, 0x3d800000, v13
	v_add_f32_e32 v14, 1.0, v15
	ds_write2_b32 v41, v12, v13 offset0:34 offset1:163
	v_mul_f32_e64 v13, |v9|, s38
	v_log_f32_e32 v14, v14
	v_exp_f32_e32 v13, v13
	v_min_f32_e32 v8, 0, v8
	v_min_f32_e32 v9, 0, v9
	v_add_f32_e32 v13, 1.0, v13
	v_add_f32_e32 v0, v23, v0
	v_cmp_gt_f32_e32 vcc, s39, v13
	v_fma_f32 v8, -v14, s40, v8
	v_cndmask_b32_e64 v14, 0, 32, vcc
	v_ldexp_f32 v13, v13, v14
	v_log_f32_e32 v13, v13
	v_cndmask_b32_e32 v14, 0, v125, vcc
	v_mul_f32_e32 v8, 0x3d800000, v8
	v_mul_f32_e64 v4, |v0|, s38
	v_mul_f32_e32 v12, 0x3f317217, v13
	v_fma_f32 v12, v13, s40, -v12
	v_fmac_f32_e32 v12, 0x3377d1cf, v13
	v_fmac_f32_e32 v12, 0x3f317217, v13
	v_cmp_lt_f32_e64 s[0:1], |v13|, s41
	v_exp_f32_e32 v4, v4
	v_add_f32_e32 v1, v23, v1
	v_cndmask_b32_e64 v12, v13, v12, s[0:1]
	v_mul_f32_e64 v13, |v10|, s38
	v_exp_f32_e32 v13, v13
	v_sub_f32_e32 v12, v12, v14
	v_sub_f32_e32 v9, v9, v12
	v_mul_f32_e32 v9, 0x3d800000, v9
	v_add_f32_e32 v12, 1.0, v13
	ds_write2_b32 v42, v8, v9 offset0:48 offset1:177
	v_min_f32_e32 v8, 0, v10
	v_log_f32_e32 v12, v12
	v_add_f32_e32 v10, v23, v11
	v_mul_f32_e64 v11, |v10|, s38
	v_exp_f32_e32 v11, v11
	s_nop 0
	v_add_f32_e32 v11, 1.0, v11
	v_add_f32_e32 v4, 1.0, v4
	v_fma_f32 v8, -v12, s40, v8
	v_log_f32_e32 v11, v11
	v_min_f32_e32 v9, 0, v10
	v_log_f32_e32 v4, v4
	v_fma_f32 v5, -v11, s40, v9
	v_mul_f32_e32 v8, 0x3d800000, v8
	v_mul_f32_e32 v5, 0x3d800000, v5
	ds_write2_b32 v20, v8, v5 offset0:50 offset1:179
	v_mul_f32_e64 v6, |v1|, s38
	v_exp_f32_e32 v6, v6
	v_min_f32_e32 v0, 0, v0
	v_add_f32_e32 v2, v23, v2
	v_add_f32_e32 v5, 1.0, v6
	v_cmp_gt_f32_e32 vcc, s39, v5
	v_fma_f32 v0, -v4, s40, v0
	v_min_f32_e32 v1, 0, v1
	v_cndmask_b32_e64 v6, 0, 32, vcc
	v_ldexp_f32 v5, v5, v6
	v_log_f32_e32 v5, v5
	v_cndmask_b32_e32 v6, 0, v125, vcc
	v_mul_f32_e32 v0, 0x3d800000, v0
	v_add_u32_e32 v41, 0x400, v127
	v_mul_f32_e32 v4, 0x3f317217, v5
	v_fma_f32 v4, v5, s40, -v4
	v_fmac_f32_e32 v4, 0x3377d1cf, v5
	v_fmac_f32_e32 v4, 0x3f317217, v5
	v_cmp_lt_f32_e64 s[0:1], |v5|, s41
	s_nop 1
	v_cndmask_b32_e64 v4, v5, v4, s[0:1]
	v_mul_f32_e64 v5, |v2|, s38
	v_exp_f32_e32 v5, v5
	v_sub_f32_e32 v4, v4, v6
	v_sub_f32_e32 v1, v1, v4
	v_mul_f32_e32 v1, 0x3d800000, v1
	v_add_f32_e32 v4, 1.0, v5
	ds_write2_b32 v21, v0, v1 offset0:64 offset1:193
	v_min_f32_e32 v0, 0, v2
	v_log_f32_e32 v4, v4
	v_add_f32_e32 v2, v23, v3
	v_mul_f32_e64 v3, |v2|, s38
	v_exp_f32_e32 v3, v3
	s_nop 0
	v_add_f32_e32 v3, 1.0, v3
	s_nop 0
	v_fma_f32 v0, -v4, s40, v0
	v_log_f32_e32 v3, v3
	v_min_f32_e32 v1, 0, v2
	v_mul_f32_e32 v0, 0x3d800000, v0
	s_nop 1
	v_fma_f32 v1, -v3, s40, v1
	v_mul_f32_e32 v1, 0x3d800000, v1
	ds_write2_b32 v22, v0, v1 offset0:66 offset1:195
	s_waitcnt lgkmcnt(0)
	s_barrier
	ds_read2_b32 v[0:1], v127 offset1:129
	ds_read2_b32 v[70:71], v41 offset0:2 offset1:131
	ds_read2_b32 v[68:69], v129 offset0:4 offset1:133
	ds_read2_b32 v[66:67], v130 offset0:6 offset1:135
	ds_read2_b32 v[64:65], v132 offset0:8 offset1:137
	ds_read2_b32 v[62:63], v135 offset0:10 offset1:139
	ds_read2_b32 v[60:61], v138 offset0:12 offset1:141
	ds_read2_b32 v[58:59], v133 offset0:14 offset1:143
	ds_read2_b32 v[56:57], v136 offset0:16 offset1:145
	ds_read2_b32 v[54:55], v139 offset0:18 offset1:147
	ds_read2_b32 v[52:53], v141 offset0:20 offset1:149
	ds_read2_b32 v[50:51], v142 offset0:22 offset1:151
	ds_read2_b32 v[48:49], v140 offset0:24 offset1:153
	ds_read2_b32 v[46:47], v137 offset0:26 offset1:155
	ds_read2_b32 v[44:45], v134 offset0:28 offset1:157
	ds_read2_b32 v[42:43], v131 offset0:30 offset1:159
	s_mov_b64 s[0:1], exec
	s_and_b64 s[12:13], s[0:1], s[6:7]
	s_xor_b64 s[0:1], s[12:13], s[0:1]
	s_mov_b64 exec, s[12:13]
	s_cbranch_execz .LBB0_657
	s_waitcnt lgkmcnt(0)
	v_add_f32_e32 v42, v42, v43
	v_add_f32_e32 v29, v45, v42
	v_add_f32_e32 v28, v44, v29
	v_add_f32_e32 v27, v47, v28
	v_add_f32_e32 v26, v46, v27
	v_add_f32_e32 v25, v49, v26
	v_add_f32_e32 v24, v48, v25
	v_add_f32_e32 v23, v51, v24
	v_add_f32_e32 v22, v50, v23
	v_add_f32_e32 v21, v53, v22
	v_add_f32_e32 v20, v52, v21
	v_add_f32_e32 v19, v55, v20
	v_add_f32_e32 v18, v54, v19
	v_add_f32_e32 v17, v57, v18
	v_add_f32_e32 v16, v56, v17
	v_add_f32_e32 v15, v59, v16
	v_add_f32_e32 v14, v58, v15
	v_add_f32_e32 v13, v61, v14
	v_add_f32_e32 v12, v60, v13
	v_add_f32_e32 v11, v63, v12
	v_add_f32_e32 v10, v62, v11
	v_add_f32_e32 v9, v65, v10
	v_add_f32_e32 v8, v64, v9
	v_add_f32_e32 v7, v67, v8
	v_add_f32_e32 v6, v66, v7
	v_add_f32_e32 v5, v69, v6
	v_add_f32_e32 v4, v68, v5
	v_add_f32_e32 v3, v71, v4
	v_add_f32_e32 v2, v70, v3
	v_add_f32_e32 v1, v1, v2
	v_add_f32_e32 v0, v0, v1
	v_mov_b32_e32 v143, v0

.LBB0_819:
	s_or_b64 exec, exec, s[0:1]
	v_or_b32_e32 v16, s44, v97
	v_mov_b64_e32 v[18:19], s[68:69]
	v_mad_i64_i32 v[18:19], s[0:1], v16, s79, v[18:19]
	v_lshl_add_u64 v[18:19], v[18:19], 0, s[70:71]
	v_lshl_add_u64 v[20:21], v[18:19], 0, s[76:77]
	v_mov_b32_e32 v51, v31
	v_lshl_add_u64 v[24:25], v[20:21], 0, v[50:51]
	s_waitcnt lgkmcnt(0)
	s_barrier
	global_load_dwordx2 v[54:55], v[24:25], off
	global_load_dwordx4 v[26:29], v[44:45], off
	ds_read2st64_b32 v[18:19], v100 offset0:108 offset1:109
	v_ashrrev_i32_e32 v17, 31, v16
	v_lshlrev_b64 v[16:17], 10, v[16:17]
	v_lshl_add_u64 v[16:17], s[72:73], 0, v[16:17]
	v_lshl_add_u64 v[16:17], v[16:17], 0, s[70:71]
	s_waitcnt lgkmcnt(0)
	v_add_f32_e32 v18, v18, v19
	v_fmamk_f32 v18, v18, 0x3c000000, v109
	v_rsq_f32_e32 v18, v18
	v_lshl_add_u64 v[22:23], v[16:17], 0, v[50:51]
	global_load_dwordx2 v[56:57], v[24:25], off offset:32
	s_nop 0
	global_load_dwordx2 v[24:25], v[24:25], off offset:64
	v_pk_mul_f32 v[12:13], v[12:13], v[18:19] op_sel_hi:[1,0]
	v_pk_mul_f32 v[14:15], v[14:15], v[18:19] op_sel_hi:[1,0]
	s_waitcnt vmcnt(3)
	v_lshlrev_b32_e32 v58, 16, v54
	v_and_b32_e32 v59, 0xffff0000, v54
	v_mul_f32_e32 v19, 0xbfb8aa3b, v58
	v_mul_f32_e32 v49, 0xbfb8aa3b, v59
	v_lshlrev_b32_e32 v54, 16, v55
	v_and_b32_e32 v55, 0xffff0000, v55
	v_exp_f32_e32 v60, v19
	v_exp_f32_e32 v61, v49
	v_mul_f32_e32 v51, 0xbfb8aa3b, v54
	v_mul_f32_e32 v53, 0xbfb8aa3b, v55
	v_exp_f32_e32 v62, v51
	v_exp_f32_e32 v63, v53
	s_waitcnt vmcnt(2)
	v_pk_mul_f32 v[12:13], v[26:27], v[12:13]
	v_pk_add_f32 v[26:27], v[60:61], 1.0 op_sel_hi:[1,0]
	v_pk_mul_f32 v[14:15], v[28:29], v[14:15]
	v_pk_add_f32 v[28:29], v[62:63], 1.0 op_sel_hi:[1,0]
	s_mov_b64 vcc, s[0:1]
	v_rcp_f32_e32 v27, v27
	s_mov_b64 vcc, s[46:47]
	v_rcp_f32_e32 v26, v26
	s_mov_b64 vcc, s[48:49]
	v_rcp_f32_e32 v29, v29
	v_pk_mul_f32 v[26:27], v[26:27], v[58:59]
	v_rcp_f32_e32 v28, v28
	v_pk_mul_f32 v[12:13], v[12:13], v[26:27]
	v_pk_mul_f32 v[26:27], v[28:29], v[54:55]
	v_cvt_pk_bf16_f32 v12, v12, v13
	v_pk_mul_f32 v[14:15], v[14:15], v[26:27]
	s_waitcnt vmcnt(1)
	v_lshlrev_b32_e32 v26, 16, v56
	v_cvt_pk_bf16_f32 v13, v14, v15
	global_store_dwordx2 v[22:23], v[12:13], off
	global_load_dwordx4 v[12:15], v[44:45], off offset:64
	v_and_b32_e32 v27, 0xffff0000, v56
	v_mul_f32_e32 v19, 0xbfb8aa3b, v26
	v_mul_f32_e32 v49, 0xbfb8aa3b, v27
	v_lshlrev_b32_e32 v28, 16, v57
	v_and_b32_e32 v29, 0xffff0000, v57
	v_exp_f32_e32 v54, v19
	v_exp_f32_e32 v55, v49
	v_mul_f32_e32 v51, 0xbfb8aa3b, v28
	v_mul_f32_e32 v53, 0xbfb8aa3b, v29
	v_exp_f32_e32 v56, v51
	v_exp_f32_e32 v57, v53
	v_pk_add_f32 v[54:55], v[54:55], 1.0 op_sel_hi:[1,0]
	v_pk_mul_f32 v[8:9], v[8:9], v[18:19] op_sel_hi:[1,0]
	v_pk_mul_f32 v[10:11], v[10:11], v[18:19] op_sel_hi:[1,0]
	v_pk_add_f32 v[56:57], v[56:57], 1.0 op_sel_hi:[1,0]
	s_mov_b64 vcc, s[0:1]
	v_rcp_f32_e32 v55, v55
	s_mov_b64 vcc, s[46:47]
	v_rcp_f32_e32 v54, v54
	s_mov_b64 vcc, s[48:49]
	v_pk_mul_f32 v[26:27], v[54:55], v[26:27]
	v_rcp_f32_e32 v55, v57
	s_nop 0
	v_rcp_f32_e32 v54, v56
	s_nop 0
	v_pk_mul_f32 v[28:29], v[54:55], v[28:29]
	v_mov_b32_e32 v53, v31
	s_waitcnt vmcnt(0)
	v_pk_mul_f32 v[8:9], v[12:13], v[8:9]
	v_pk_mul_f32 v[10:11], v[14:15], v[10:11]
	v_pk_mul_f32 v[8:9], v[8:9], v[26:27]
	v_pk_mul_f32 v[10:11], v[10:11], v[28:29]
	v_cvt_pk_bf16_f32 v8, v8, v9
	v_cvt_pk_bf16_f32 v9, v10, v11
	global_store_dwordx2 v[22:23], v[8:9], off offset:32
	global_load_dwordx4 v[8:11], v[44:45], off offset:128
	v_lshlrev_b32_e32 v14, 16, v24
	v_and_b32_e32 v15, 0xffff0000, v24
	v_lshl_add_u64 v[12:13], v[20:21], 0, v[52:53]
	v_lshlrev_b32_e32 v20, 16, v25
	v_and_b32_e32 v21, 0xffff0000, v25
	v_mul_f32_e32 v19, 0xbfb8aa3b, v14
	v_mul_f32_e32 v25, 0xbfb8aa3b, v15
	v_exp_f32_e32 v24, v19
	v_exp_f32_e32 v25, v25
	v_mul_f32_e32 v26, 0xbfb8aa3b, v20
	v_mul_f32_e32 v27, 0xbfb8aa3b, v21
	v_exp_f32_e32 v26, v26
	v_exp_f32_e32 v27, v27
	v_pk_add_f32 v[24:25], v[24:25], 1.0 op_sel_hi:[1,0]
	v_pk_mul_f32 v[4:5], v[4:5], v[18:19] op_sel_hi:[1,0]
	v_pk_mul_f32 v[6:7], v[6:7], v[18:19] op_sel_hi:[1,0]
	v_pk_add_f32 v[26:27], v[26:27], 1.0 op_sel_hi:[1,0]
	v_div_scale_f32 v55, s[44:45], v26, v26, 1.0
	v_rcp_f32_e32 v60, v55
	s_nop 0
	v_fma_f32 v64, -v55, v60, 1.0
	v_div_scale_f32 v56, s[48:49], 1.0, v26, 1.0
	v_fmac_f32_e32 v60, v64, v60
	v_mul_f32_e32 v64, v56, v60
	v_fma_f32 v68, -v55, v64, v56
	s_mov_b64 vcc, s[0:1]
	v_fmac_f32_e32 v64, v68, v60
	v_rcp_f32_e32 v25, v25
	s_mov_b64 vcc, s[46:47]
	v_fma_f32 v49, -v55, v64, v56
	v_rcp_f32_e32 v24, v24
	s_mov_b64 vcc, s[48:49]
	v_pk_mul_f32 v[14:15], v[24:25], v[14:15]
	v_rcp_f32_e32 v25, v27
	v_div_fmas_f32 v19, v49, v60, v64
	v_div_fixup_f32 v24, v19, v26, 1.0
	v_pk_mul_f32 v[20:21], v[24:25], v[20:21]
	v_readlane_b32 s0, v244, 4
	v_pk_mul_f32 v[0:1], v[0:1], v[18:19] op_sel_hi:[1,0]
	v_readlane_b32 s1, v244, 5
	s_add_i32 s84, s84, s0
	v_pk_mul_f32 v[2:3], v[2:3], v[18:19] op_sel_hi:[1,0]
	s_waitcnt vmcnt(0)
	v_pk_mul_f32 v[4:5], v[4:5], v[8:9]
	v_pk_mul_f32 v[6:7], v[6:7], v[10:11]
	v_pk_mul_f32 v[4:5], v[4:5], v[14:15]
	v_pk_mul_f32 v[6:7], v[6:7], v[20:21]
	v_cvt_pk_bf16_f32 v4, v4, v5
	v_cvt_pk_bf16_f32 v5, v6, v7
	global_store_dwordx2 v[22:23], v[4:5], off offset:64
	global_load_dwordx2 v[8:9], v[12:13], off
	s_nop 0
	global_load_dwordx4 v[4:7], v[46:47], off
	v_lshl_add_u64 v[10:11], v[16:17], 0, v[52:53]
	s_cmpk_gt_i32 s84, 0x7ff
	s_waitcnt vmcnt(1)
	v_lshlrev_b32_e32 v12, 16, v8
	v_and_b32_e32 v13, 0xffff0000, v8
	v_mul_f32_e32 v14, 0xbfb8aa3b, v12
	v_mul_f32_e32 v15, 0xbfb8aa3b, v13
	v_lshlrev_b32_e32 v8, 16, v9
	v_and_b32_e32 v9, 0xffff0000, v9
	v_exp_f32_e32 v14, v14
	v_exp_f32_e32 v15, v15
	v_mul_f32_e32 v16, 0xbfb8aa3b, v8
	v_mul_f32_e32 v17, 0xbfb8aa3b, v9
	v_exp_f32_e32 v16, v16
	v_exp_f32_e32 v17, v17
	s_waitcnt vmcnt(0)
	v_pk_mul_f32 v[0:1], v[0:1], v[4:5]
	v_pk_add_f32 v[4:5], v[14:15], 1.0 op_sel_hi:[1,0]
	v_pk_mul_f32 v[2:3], v[2:3], v[6:7]
	v_pk_add_f32 v[6:7], v[16:17], 1.0 op_sel_hi:[1,0]
	s_mov_b64 vcc, s[0:1]
	v_rcp_f32_e32 v5, v5
	s_mov_b64 vcc, s[46:47]
	v_rcp_f32_e32 v4, v4
	s_mov_b64 vcc, s[48:49]
	v_pk_mul_f32 v[4:5], v[4:5], v[12:13]
	v_rcp_f32_e32 v7, v7
	s_nop 0
	v_rcp_f32_e32 v6, v6
	v_pk_mul_f32 v[0:1], v[0:1], v[4:5]
	v_pk_mul_f32 v[4:5], v[6:7], v[8:9]
	v_cvt_pk_bf16_f32 v0, v0, v1
	v_pk_mul_f32 v[2:3], v[2:3], v[4:5]
	s_nop 0
	v_cvt_pk_bf16_f32 v1, v2, v3
	global_store_dwordx2 v[10:11], v[0:1], off
	s_barrier
	s_cbranch_scc1 .LBB0_832

.LBB0_822:
	s_or_b64 exec, exec, s[0:1]
	s_lshl_b32 s70, s86, 7
	s_or_b32 s60, s70, s78
	v_or_b32_e32 v24, s60, v34
	v_mov_b32_e32 v25, v31
	v_lshl_add_u64 v[24:25], v[24:25], 2, s[90:91]
	global_load_dword v23, v[24:25], off
	s_waitcnt vmcnt(0)
	v_mfma_f32_16x16x32_bf16 v[26:29], v[12:15], v[16:19], 0
	v_add_u32_e32 v24, 0x400, v111
	v_mfma_f32_16x16x32_bf16 v[54:57], v[8:11], v[16:19], 0
	s_nop 5
	v_add_f32_e32 v25, v23, v26
	v_add_f32_e32 v26, v23, v27
	v_min_f32_e32 v51, 0, v25
	v_mul_f32_e64 v25, |v25|, s80
	v_add_f32_e32 v27, v23, v28
	v_min_f32_e32 v53, 0, v26
	v_mul_f32_e64 v26, |v26|, s80
	v_exp_f32_e32 v25, v25
	v_add_f32_e32 v28, v23, v29
	v_add_f32_e32 v29, v23, v54
	v_min_f32_e32 v54, 0, v27
	v_mul_f32_e64 v27, |v27|, s80
	v_exp_f32_e32 v26, v26
	v_add_f32_e32 v49, v23, v55
	v_min_f32_e32 v55, 0, v28
	v_mul_f32_e64 v28, |v28|, s80
	v_exp_f32_e32 v27, v27
	v_exp_f32_e32 v28, v28
	v_add_f32_e32 v25, 1.0, v25
	v_add_f32_e32 v26, 1.0, v26
	v_min_f32_e32 v58, 0, v29
	v_mul_f32_e64 v29, |v29|, s80
	v_add_f32_e32 v27, 1.0, v27
	v_exp_f32_e32 v29, v29
	v_add_f32_e32 v28, 1.0, v28
	v_log_f32_e32 v25, v25
	v_log_f32_e32 v26, v26
	v_log_f32_e32 v27, v27
	v_add_f32_e32 v29, 1.0, v29
	v_log_f32_e32 v28, v28
	v_log_f32_e32 v29, v29
	v_mul_f32_e64 v59, |v49|, s80
	v_exp_f32_e32 v59, v59
	v_fma_f32 v25, -v25, s82, v51
	v_fma_f32 v26, -v26, s82, v53
	v_fma_f32 v27, -v27, s82, v54
	v_fma_f32 v28, -v28, s82, v55
	v_mul_f32_e32 v25, 0x3d800000, v25
	v_mul_f32_e32 v26, 0x3d800000, v26
	v_mul_f32_e32 v27, 0x3d800000, v27
	v_mul_f32_e32 v28, 0x3d800000, v28
	ds_write2_b32 v111, v25, v26 offset1:129
	ds_write2_b32 v24, v27, v28 offset0:2 offset1:131
	v_add_f32_e32 v26, 1.0, v59
	v_log_f32_e32 v26, v26
	v_fma_f32 v25, -v29, s82, v58
	v_add_f32_e32 v29, v23, v56
	v_mul_f32_e32 v27, 0x3d800000, v25
	v_min_f32_e32 v25, 0, v49
	v_mul_f32_e64 v49, |v29|, s80
	v_exp_f32_e32 v49, v49
	s_nop 0
	v_fma_f32 v25, -v26, s82, v25
	v_mul_f32_e32 v26, 0x3d800000, v25
	v_add_f32_e32 v25, 1.0, v49
	v_cmp_gt_f32_e32 vcc, s81, v25
	s_nop 1
	v_cndmask_b32_e64 v28, 0, 32, vcc
	v_ldexp_f32 v25, v25, v28
	v_log_f32_e32 v28, v25
	v_add_u32_e32 v25, 0x2000, v111
	ds_write2_b32 v25, v27, v26 offset0:16 offset1:145
	v_min_f32_e32 v26, 0, v29
	v_add_f32_e32 v29, v23, v57
	v_mul_f32_e32 v27, 0x3f317217, v28
	v_mul_f32_e64 v49, |v29|, s80
	v_fma_f32 v27, v28, s82, -v27
	v_exp_f32_e32 v49, v49
	v_fmac_f32_e32 v27, 0x3377d1cf, v28
	v_fmac_f32_e32 v27, 0x3f317217, v28
	v_cmp_lt_f32_e64 s[0:1], |v28|, s83
	v_min_f32_e32 v51, 0, v29
	s_nop 0
	v_cndmask_b32_e64 v27, v28, v27, s[0:1]
	v_cndmask_b32_e32 v28, 0, v110, vcc
	v_sub_f32_e32 v27, v27, v28
	v_add_f32_e32 v28, 1.0, v49
	v_cmp_gt_f32_e32 vcc, s81, v28
	v_sub_f32_e32 v26, v26, v27
	s_nop 0
	v_cndmask_b32_e64 v49, 0, 32, vcc
	v_ldexp_f32 v28, v28, v49
	v_log_f32_e32 v28, v28
	v_mul_f32_e32 v49, 0x3d800000, v26
	v_cndmask_b32_e32 v54, 0, v110, vcc
	v_mul_f32_e32 v26, 0x3f317217, v28
	v_fma_f32 v26, v28, s82, -v26
	v_fmac_f32_e32 v26, 0x3377d1cf, v28
	v_fmac_f32_e32 v26, 0x3f317217, v28
	v_cmp_lt_f32_e64 s[0:1], |v28|, s83
	s_nop 1
	v_cndmask_b32_e64 v53, v28, v26, s[0:1]
	v_mfma_f32_16x16x32_bf16 v[26:29], v[4:7], v[16:19], 0
	v_sub_f32_e32 v53, v53, v54
	v_sub_f32_e32 v51, v51, v53
	v_mul_f32_e32 v51, 0x3d800000, v51
	v_mfma_f32_16x16x32_bf16 v[16:19], v[0:3], v[16:19], 0
	s_nop 3
	v_add_f32_e32 v55, v23, v26
	v_mul_f32_e64 v26, |v55|, s80
	v_exp_f32_e32 v26, v26
	v_add_f32_e32 v27, v23, v27
	v_mul_f32_e64 v54, |v27|, s80
	v_exp_f32_e32 v54, v54
	v_add_f32_e32 v26, 1.0, v26
	v_cmp_gt_f32_e32 vcc, s81, v26
	v_add_f32_e32 v28, v23, v28
	v_min_f32_e32 v27, 0, v27
	v_cndmask_b32_e64 v53, 0, 32, vcc
	v_ldexp_f32 v26, v26, v53
	v_log_f32_e32 v53, v26
	v_add_u32_e32 v26, 0x2400, v111
	ds_write2_b32 v26, v49, v51 offset0:18 offset1:147
	v_min_f32_e32 v49, 0, v55
	v_mul_f32_e32 v51, 0x3f317217, v53
	v_fma_f32 v51, v53, s82, -v51
	v_fmac_f32_e32 v51, 0x3377d1cf, v53
	v_fmac_f32_e32 v51, 0x3f317217, v53
	v_cmp_lt_f32_e64 s[0:1], |v53|, s83
	v_add_f32_e32 v29, v23, v29
	v_add_f32_e32 v16, v23, v16
	v_cndmask_b32_e64 v51, v53, v51, s[0:1]
	v_cndmask_b32_e32 v53, 0, v110, vcc
	v_sub_f32_e32 v51, v51, v53
	v_add_f32_e32 v53, 1.0, v54
	v_sub_f32_e32 v49, v49, v51
	v_mul_f32_e32 v49, 0x3d800000, v49
	v_log_f32_e32 v53, v53
	v_mul_f32_e64 v54, |v28|, s80
	v_exp_f32_e32 v54, v54
	v_min_f32_e32 v28, 0, v28
	v_add_f32_e32 v17, v23, v17
	v_add_f32_e32 v18, v23, v18
	v_fma_f32 v27, -v53, s82, v27
	v_mul_f32_e32 v51, 0x3d800000, v27
	v_add_f32_e32 v27, 1.0, v54
	s_nop 1
	v_log_f32_e32 v53, v27
	v_add_u32_e32 v27, 0x4000, v111
	ds_write2_b32 v27, v49, v51 offset0:32 offset1:161
	v_mul_f32_e64 v51, |v29|, s80
	v_exp_f32_e32 v51, v51
	s_nop 0
	v_add_f32_e32 v51, 1.0, v51
	s_nop 0
	v_fma_f32 v28, -v53, s82, v28
	v_log_f32_e32 v51, v51
	v_mul_f32_e32 v49, 0x3d800000, v28
	v_min_f32_e32 v28, 0, v29
	v_mul_f32_e64 v53, |v16|, s80
	v_exp_f32_e32 v53, v53
	v_min_f32_e32 v16, 0, v16
	v_fma_f32 v28, -v51, s82, v28
	v_mul_f32_e32 v29, 0x3d800000, v28
	v_add_f32_e32 v28, 1.0, v53
	s_nop 1
	v_log_f32_e32 v51, v28
	v_add_u32_e32 v28, 0x4400, v111
	ds_write2_b32 v28, v49, v29 offset0:34 offset1:163
	v_mul_f32_e64 v49, |v17|, s80
	v_exp_f32_e32 v49, v49
	s_nop 0
	v_add_f32_e32 v49, 1.0, v49
	v_min_f32_e32 v17, 0, v17
	v_fma_f32 v16, -v51, s82, v16
	v_log_f32_e32 v49, v49
	v_mul_f32_e64 v51, |v18|, s80
	v_exp_f32_e32 v51, v51
	v_mul_f32_e32 v16, 0x3d800000, v16
	s_nop 1
	v_fma_f32 v17, -v49, s82, v17
	v_add_f32_e32 v29, 1.0, v51
	v_mul_f32_e32 v17, 0x3d800000, v17
	s_nop 0
	v_log_f32_e32 v49, v29
	v_add_u32_e32 v29, 0x6000, v111
	ds_write2_b32 v29, v16, v17 offset0:48 offset1:177
	v_min_f32_e32 v16, 0, v18
	v_add_f32_e32 v18, v23, v19
	v_mul_f32_e64 v19, |v18|, s80
	v_exp_f32_e32 v19, v19
	s_nop 0
	v_add_f32_e32 v19, 1.0, v19
	v_fma_f32 v16, -v49, s82, v16
	v_log_f32_e32 v19, v19
	v_min_f32_e32 v17, 0, v18
	v_mul_f32_e32 v16, 0x3d800000, v16
	v_add_u32_e32 v49, 0x6400, v111
	s_nop 1
	v_fma_f32 v17, -v19, s82, v17
	v_mul_f32_e32 v17, 0x3d800000, v17
	ds_write2_b32 v49, v16, v17 offset0:50 offset1:179
	v_mov_b32_e32 v16, 0
	v_mov_b32_e32 v17, 0
	v_mov_b32_e32 v18, 0
	v_mov_b32_e32 v19, 0
	s_and_saveexec_b64 s[0:1], s[2:3]
	s_cbranch_execz .LBB0_824
	v_mov_b32_e32 v23, v31
	v_lshl_add_u64 v[16:17], v[20:21], 0, v[22:23]
	v_add_co_u32_e32 v18, vcc, 0x1000, v16
	s_nop 1
	v_addc_co_u32_e32 v19, vcc, 0, v17, vcc
	v_add_co_u32_e32 v20, vcc, 0x2000, v16
	s_nop 1
	v_addc_co_u32_e32 v21, vcc, 0, v17, vcc
	v_add_co_u32_e32 v22, vcc, 0x3000, v16
	s_nop 1
	v_addc_co_u32_e32 v23, vcc, 0, v17, vcc
	global_load_dword v51, v[16:17], off offset:64
	s_nop 0
	global_load_dword v16, v[16:17], off offset:2112
	s_nop 0
	global_load_dword v17, v[18:19], off offset:64
	s_nop 0
	global_load_dword v18, v[18:19], off offset:2112
	s_nop 0
	global_load_dword v19, v[20:21], off offset:64
	s_nop 0
	global_load_dword v20, v[20:21], off offset:2112
	s_nop 0
	global_load_dword v21, v[22:23], off offset:64
	s_nop 0
	global_load_dword v22, v[22:23], off offset:2112
	s_waitcnt vmcnt(6)
	v_cvt_pk_bf16_f32 v16, v51, v16
	s_waitcnt vmcnt(4)
	v_cvt_pk_bf16_f32 v17, v17, v18
	s_waitcnt vmcnt(2)
	v_cvt_pk_bf16_f32 v18, v19, v20
	s_waitcnt vmcnt(0)
	v_cvt_pk_bf16_f32 v19, v21, v22
.LBB0_824:
	s_or_b64 exec, exec, s[0:1]
	v_add_u32_e32 v20, s60, v34
	v_mov_b32_e32 v21, v31
	v_lshl_add_u64 v[20:21], v[20:21], 2, s[90:91]
	global_load_dword v20, v[20:21], off offset:64
	v_mfma_f32_16x16x32_bf16 v[12:15], v[12:15], v[16:19], 0
	v_add_u32_e32 v114, 0x1000, v112
	v_add_u32_e32 v117, 0x1400, v112
	v_add_u32_e32 v120, 0x1800, v112
	v_mfma_f32_16x16x32_bf16 v[8:11], v[8:11], v[16:19], 0
	v_add_u32_e32 v115, 0x1c00, v112
	v_add_u32_e32 v118, 0x2000, v112
	v_add_u32_e32 v121, 0x2400, v112
	v_mfma_f32_16x16x32_bf16 v[4:7], v[4:7], v[16:19], 0
	v_add_u32_e32 v123, 0x2800, v112
	v_add_u32_e32 v124, 0x2c00, v112
	v_add_u32_e32 v122, 0x3000, v112
	v_mfma_f32_16x16x32_bf16 v[0:3], v[0:3], v[16:19], 0
	v_add_u32_e32 v119, 0x3400, v112
	v_add_u32_e32 v116, 0x3800, v112
	v_add_u32_e32 v113, 0x3c00, v112
	s_waitcnt vmcnt(0)
	v_readlane_b32 s98, v244, 4
	s_nop 1
	s_add_i32 s98, s84, s98
	s_cmpk_lt_i32 s98, 0x800
	s_cbranch_scc0 .Lpf_c_skip
	s_lshr_b32 s99, s98, 8
	s_bfe_u32 s100, s98, 0x20006
	s_and_b32 s101, s98, 63
	s_lshl_b32 s98, s99, 2
	s_add_i32 s98, s98, s100
	s_lshl_b32 s98, s98, 7
	s_add_i32 s98, s98, s101
	s_lshl_b32 s98, s98, 15
	v_lshlrev_b32_e32 v246, 6, v145
	v_add_u32_e32 v246, s98, v246
	global_load_dword v240, v246, s[52:53]
	v_add_u32_e32 v246, 0x200000, v246
	global_load_dword v240, v246, s[52:53]
	s_lshl_b32 s99, s99, 12
	s_lshl_b32 s101, s101, 6
	s_add_i32 s99, s99, s101
	s_lshl_b32 s100, s100, 8
	v_add_u32_e32 v245, s99, v144
	v_mul_u32_u24_e32 v245, 0x2600, v245
	v_lshrrev_b32_e32 v246, 6, v145
	v_lshlrev_b32_e32 v247, 6, v246
	v_lshrrev_b32_e32 v246, 2, v246
	v_mul_u32_u24_e32 v246, 0x300, v246
	v_add3_u32 v247, v247, v246, s100
	v_add_u32_e32 v247, v247, v245
	s_add_u32 s98, s54, 0x6800000
	s_addc_u32 s99, s55, 0
	global_load_dword v240, v247, s[98:99] offset:1344
	global_load_dword v240, v247, s[98:99] offset:3392
	v_add_u32_e32 v245, 0x1540, v245
	global_load_dword v240, v245, s[98:99]
.Lpf_c_skip:
	v_add_f32_e32 v12, v20, v12
	v_add_f32_e32 v13, v20, v13
	v_min_f32_e32 v21, 0, v12
	v_mul_f32_e64 v12, |v12|, s80
	v_add_f32_e32 v14, v20, v14
	v_min_f32_e32 v22, 0, v13
	v_mul_f32_e64 v13, |v13|, s80
	v_exp_f32_e32 v12, v12
	v_add_f32_e32 v15, v20, v15
	v_min_f32_e32 v23, 0, v14
	v_mul_f32_e64 v14, |v14|, s80
	v_exp_f32_e32 v13, v13
	v_min_f32_e32 v51, 0, v15
	v_mul_f32_e64 v15, |v15|, s80
	v_exp_f32_e32 v14, v14
	v_exp_f32_e32 v15, v15
	v_add_f32_e32 v12, 1.0, v12
	v_add_f32_e32 v8, v20, v8
	v_add_f32_e32 v13, 1.0, v13
	v_min_f32_e32 v53, 0, v8
	v_mul_f32_e64 v8, |v8|, s80
	v_add_f32_e32 v14, 1.0, v14
	v_exp_f32_e32 v8, v8
	v_add_f32_e32 v15, 1.0, v15
	v_log_f32_e32 v12, v12
	v_log_f32_e32 v13, v13
	v_log_f32_e32 v14, v14
	v_add_f32_e32 v8, 1.0, v8
	v_log_f32_e32 v15, v15
	v_log_f32_e32 v8, v8
	v_add_f32_e32 v9, v20, v9
	v_mul_f32_e64 v54, |v9|, s80
	v_exp_f32_e32 v54, v54
	v_fma_f32 v12, -v12, s82, v21
	v_fma_f32 v13, -v13, s82, v22
	v_fma_f32 v14, -v14, s82, v23
	v_fma_f32 v15, -v15, s82, v51
	v_mul_f32_e32 v12, 0x3d800000, v12
	v_mul_f32_e32 v13, 0x3d800000, v13
	v_mul_f32_e32 v14, 0x3d800000, v14
	v_mul_f32_e32 v15, 0x3d800000, v15
	ds_write2_b32 v111, v12, v13 offset0:16 offset1:145
	ds_write2_b32 v24, v14, v15 offset0:18 offset1:147
	v_add_f32_e32 v12, 1.0, v54
	v_add_f32_e32 v10, v20, v10
	v_min_f32_e32 v9, 0, v9
	v_log_f32_e32 v12, v12
	v_fma_f32 v8, -v8, s82, v53
	v_mul_f32_e32 v8, 0x3d800000, v8
	v_mul_f32_e64 v13, |v10|, s80
	v_exp_f32_e32 v13, v13
	v_fma_f32 v9, -v12, s82, v9
	v_mul_f32_e32 v9, 0x3d800000, v9
	v_add_f32_e32 v12, 1.0, v13
	ds_write2_b32 v25, v8, v9 offset0:32 offset1:161
	v_min_f32_e32 v8, 0, v10
	v_log_f32_e32 v12, v12
	v_add_f32_e32 v10, v20, v11
	v_mul_f32_e64 v11, |v10|, s80
	v_exp_f32_e32 v11, v11
	s_nop 0
	v_add_f32_e32 v11, 1.0, v11
	v_add_f32_e32 v4, v20, v4
	v_cmp_gt_f32_e32 vcc, s81, v11
	v_fma_f32 v8, -v12, s82, v8
	v_cndmask_b32_e64 v12, 0, 32, vcc
	v_ldexp_f32 v11, v11, v12
	v_log_f32_e32 v11, v11
	v_min_f32_e32 v9, 0, v10
	v_cndmask_b32_e32 v12, 0, v110, vcc
	v_mul_f32_e32 v8, 0x3d800000, v8
	v_mul_f32_e32 v10, 0x3f317217, v11
	v_fma_f32 v10, v11, s82, -v10
	v_fmac_f32_e32 v10, 0x3377d1cf, v11
	v_fmac_f32_e32 v10, 0x3f317217, v11
	v_cmp_lt_f32_e64 s[0:1], |v11|, s83
	v_add_f32_e32 v5, v20, v5
	v_add_f32_e32 v6, v20, v6
	v_cndmask_b32_e64 v10, v11, v10, s[0:1]
	v_mul_f32_e64 v11, |v4|, s80
	v_exp_f32_e32 v11, v11
	v_sub_f32_e32 v10, v10, v12
	v_sub_f32_e32 v9, v9, v10
	v_mul_f32_e32 v9, 0x3d800000, v9
	v_add_f32_e32 v10, 1.0, v11
	ds_write2_b32 v26, v8, v9 offset0:34 offset1:163
	v_mul_f32_e64 v9, |v5|, s80
	v_log_f32_e32 v10, v10
	v_exp_f32_e32 v9, v9
	v_min_f32_e32 v4, 0, v4
	v_min_f32_e32 v5, 0, v5
	v_add_f32_e32 v9, 1.0, v9
	v_add_f32_e32 v0, v20, v0
	v_cmp_gt_f32_e32 vcc, s81, v9
	v_fma_f32 v4, -v10, s82, v4
	v_cndmask_b32_e64 v10, 0, 32, vcc
	v_ldexp_f32 v9, v9, v10
	v_log_f32_e32 v9, v9
	v_cndmask_b32_e32 v10, 0, v110, vcc
	v_mul_f32_e32 v4, 0x3d800000, v4
	v_add_f32_e32 v1, v20, v1
	v_mul_f32_e32 v8, 0x3f317217, v9
	v_fma_f32 v8, v9, s82, -v8
	v_fmac_f32_e32 v8, 0x3377d1cf, v9
	v_fmac_f32_e32 v8, 0x3f317217, v9
	v_cmp_lt_f32_e64 s[0:1], |v9|, s83
	v_add_f32_e32 v2, v20, v2
	v_add_u32_e32 v51, 0x800, v112
	v_cndmask_b32_e64 v8, v9, v8, s[0:1]
	v_mul_f32_e64 v9, |v6|, s80
	v_exp_f32_e32 v9, v9
	v_sub_f32_e32 v8, v8, v10
	v_sub_f32_e32 v5, v5, v8
	v_mul_f32_e32 v5, 0x3d800000, v5
	v_add_f32_e32 v8, 1.0, v9
	ds_write2_b32 v27, v4, v5 offset0:48 offset1:177
	v_min_f32_e32 v4, 0, v6
	v_log_f32_e32 v8, v8
	v_add_f32_e32 v6, v20, v7
	v_mul_f32_e64 v7, |v6|, s80
	v_exp_f32_e32 v7, v7
	s_nop 0
	v_add_f32_e32 v7, 1.0, v7
	v_add_u32_e32 v53, 0xc00, v112
	v_cmp_gt_f32_e32 vcc, s81, v7
	v_fma_f32 v4, -v8, s82, v4
	v_cndmask_b32_e64 v8, 0, 32, vcc
	v_ldexp_f32 v7, v7, v8
	v_log_f32_e32 v7, v7
	v_min_f32_e32 v5, 0, v6
	v_cndmask_b32_e32 v8, 0, v110, vcc
	v_mul_f32_e32 v4, 0x3d800000, v4
	v_mul_f32_e32 v6, 0x3f317217, v7
	v_fma_f32 v6, v7, s82, -v6
	v_fmac_f32_e32 v6, 0x3377d1cf, v7
	v_fmac_f32_e32 v6, 0x3f317217, v7
	v_cmp_lt_f32_e64 s[0:1], |v7|, s83
	s_nop 1
	v_cndmask_b32_e64 v6, v7, v6, s[0:1]
	v_mul_f32_e64 v7, |v0|, s80
	v_exp_f32_e32 v7, v7
	v_sub_f32_e32 v6, v6, v8
	v_sub_f32_e32 v5, v5, v6
	v_mul_f32_e32 v5, 0x3d800000, v5
	v_add_f32_e32 v6, 1.0, v7
	ds_write2_b32 v28, v4, v5 offset0:50 offset1:179
	v_mul_f32_e64 v5, |v1|, s80
	v_log_f32_e32 v6, v6
	v_exp_f32_e32 v5, v5
	v_min_f32_e32 v0, 0, v0
	v_min_f32_e32 v1, 0, v1
	v_add_f32_e32 v5, 1.0, v5
	s_nop 0
	v_cmp_gt_f32_e32 vcc, s81, v5
	v_fma_f32 v0, -v6, s82, v0
	v_cndmask_b32_e64 v6, 0, 32, vcc
	v_ldexp_f32 v5, v5, v6
	v_log_f32_e32 v5, v5
	v_cndmask_b32_e32 v6, 0, v110, vcc
	v_mul_f32_e32 v0, 0x3d800000, v0
	v_mul_f32_e32 v4, 0x3f317217, v5
	v_fma_f32 v4, v5, s82, -v4
	v_fmac_f32_e32 v4, 0x3377d1cf, v5
	v_fmac_f32_e32 v4, 0x3f317217, v5
	v_cmp_lt_f32_e64 s[0:1], |v5|, s83
	s_nop 1
	v_cndmask_b32_e64 v4, v5, v4, s[0:1]
	v_mul_f32_e64 v5, |v2|, s80
	v_exp_f32_e32 v5, v5
	v_sub_f32_e32 v4, v4, v6
	v_sub_f32_e32 v1, v1, v4
	v_mul_f32_e32 v1, 0x3d800000, v1
	v_add_f32_e32 v4, 1.0, v5
	ds_write2_b32 v29, v0, v1 offset0:64 offset1:193
	v_min_f32_e32 v0, 0, v2
	v_log_f32_e32 v4, v4
	v_add_f32_e32 v2, v20, v3
	v_mul_f32_e64 v3, |v2|, s80
	v_exp_f32_e32 v3, v3
	s_nop 0
	v_add_f32_e32 v3, 1.0, v3
	s_nop 0
	v_fma_f32 v0, -v4, s82, v0
	v_log_f32_e32 v3, v3
	v_min_f32_e32 v1, 0, v2
	v_mul_f32_e32 v0, 0x3d800000, v0
	s_nop 1
	v_fma_f32 v1, -v3, s82, v1
	v_mul_f32_e32 v1, 0x3d800000, v1
	ds_write2_b32 v49, v0, v1 offset0:66 offset1:195
	v_add_u32_e32 v49, 0x400, v112
	s_waitcnt lgkmcnt(0)
	s_barrier
	ds_read2_b32 v[0:1], v112 offset1:129
	ds_read2_b32 v[82:83], v49 offset0:2 offset1:131
	ds_read2_b32 v[80:81], v51 offset0:4 offset1:133
	ds_read2_b32 v[78:79], v53 offset0:6 offset1:135
	ds_read2_b32 v[76:77], v114 offset0:8 offset1:137
	ds_read2_b32 v[74:75], v117 offset0:10 offset1:139
	ds_read2_b32 v[72:73], v120 offset0:12 offset1:141
	ds_read2_b32 v[70:71], v115 offset0:14 offset1:143
	ds_read2_b32 v[68:69], v118 offset0:16 offset1:145
	ds_read2_b32 v[66:67], v121 offset0:18 offset1:147
	ds_read2_b32 v[64:65], v123 offset0:20 offset1:149
	ds_read2_b32 v[62:63], v124 offset0:22 offset1:151
	ds_read2_b32 v[60:61], v122 offset0:24 offset1:153
	ds_read2_b32 v[58:59], v119 offset0:26 offset1:155
	ds_read2_b32 v[56:57], v116 offset0:28 offset1:157
	ds_read2_b32 v[54:55], v113 offset0:30 offset1:159
	s_mov_b64 s[0:1], exec
	s_and_b64 s[46:47], s[0:1], s[6:7]
	s_xor_b64 s[0:1], s[46:47], s[0:1]
	s_mov_b64 exec, s[46:47]
	s_cbranch_execz .LBB0_826
	s_waitcnt lgkmcnt(0)
	v_add_f32_e32 v54, v54, v55
	v_add_f32_e32 v29, v57, v54
	v_add_f32_e32 v28, v56, v29
	v_add_f32_e32 v27, v59, v28
	v_add_f32_e32 v26, v58, v27
	v_add_f32_e32 v25, v61, v26
	v_add_f32_e32 v24, v60, v25
	v_add_f32_e32 v23, v63, v24
	v_add_f32_e32 v22, v62, v23
	v_add_f32_e32 v21, v65, v22
	v_add_f32_e32 v20, v64, v21
	v_add_f32_e32 v19, v67, v20
	v_add_f32_e32 v18, v66, v19
	v_add_f32_e32 v17, v69, v18
	v_add_f32_e32 v16, v68, v17
	v_add_f32_e32 v15, v71, v16
	v_add_f32_e32 v14, v70, v15
	v_add_f32_e32 v13, v73, v14
	v_add_f32_e32 v12, v72, v13
	v_add_f32_e32 v11, v75, v12
	v_add_f32_e32 v10, v74, v11
	v_add_f32_e32 v9, v77, v10
	v_add_f32_e32 v8, v76, v9
	v_add_f32_e32 v7, v79, v8
	v_add_f32_e32 v6, v78, v7
	v_add_f32_e32 v5, v81, v6
	v_add_f32_e32 v4, v80, v5
	v_add_f32_e32 v3, v83, v4
	v_add_f32_e32 v2, v82, v3
	v_add_f32_e32 v1, v1, v2
	v_add_f32_e32 v0, v0, v1
	v_mov_b32_e32 v125, v0

.LBB0_852:
	s_lshl_b32 s21, s0, 8
	v_lshl_or_b32 v130, s1, 8, v165
	v_add_u32_e32 v156, s21, v160
	v_mov_b64_e32 v[158:159], s[18:19]
	v_ashrrev_i32_e32 v131, 31, v130
	v_mad_i64_i32 v[128:129], s[4:5], v156, s49, v[158:159]
	v_lshlrev_b64 v[154:155], 1, v[130:131]
	v_lshl_add_u64 v[128:129], v[128:129], 0, v[154:155]
	global_load_dwordx4 v[132:135], v[128:129], off
	v_ashrrev_i32_e32 v157, 31, v156
	global_load_dwordx4 v[128:131], v[128:129], off offset:256
	v_lshlrev_b64 v[170:171], 11, v[156:157]
	v_lshl_add_u64 v[170:171], s[16:17], 0, v[170:171]
	s_waitcnt vmcnt(0)
	v_lshlrev_b32_e32 v157, 16, v132
	v_and_b32_e32 v132, 0xffff0000, v132
	v_lshlrev_b32_e32 v169, 16, v133
	v_and_b32_e32 v133, 0xffff0000, v133
	v_mul_f32_e32 v157, 0xbfb8aa3b, v157
	v_mul_f32_e32 v173, 0xbfb8aa3b, v132
	v_mul_f32_e32 v174, 0xbfb8aa3b, v133
	v_exp_f32_e32 v132, v157
	v_exp_f32_e32 v133, v173
	v_lshlrev_b32_e32 v172, 16, v134
	v_mul_f32_e32 v169, 0xbfb8aa3b, v169
	v_mul_f32_e32 v175, 0xbfb8aa3b, v172
	v_exp_f32_e32 v172, v169
	v_exp_f32_e32 v173, v174
	v_and_b32_e32 v134, 0xffff0000, v134
	v_mul_f32_e32 v134, 0xbfb8aa3b, v134
	v_pk_add_f32 v[132:133], v[132:133], 1.0 op_sel_hi:[1,0]
	v_exp_f32_e32 v174, v175
	v_exp_f32_e32 v175, v134
	v_pk_add_f32 v[172:173], v[172:173], 1.0 op_sel_hi:[1,0]
	v_pk_add_f32 v[174:175], v[174:175], 1.0 op_sel_hi:[1,0]
	s_mov_b64 vcc, s[0:1]
	v_rcp_f32_e32 v133, v133
	s_mov_b64 vcc, s[4:5]
	v_rcp_f32_e32 v132, v132
	s_mov_b64 vcc, s[6:7]
	v_pk_mul_f32 v[132:133], v[124:125], v[132:133]
	v_rcp_f32_e32 v125, v173
	v_lshlrev_b32_e32 v134, 16, v135
	v_and_b32_e32 v135, 0xffff0000, v135
	v_rcp_f32_e32 v124, v172
	s_mov_b64 vcc, s[8:9]
	v_mul_f32_e32 v134, 0xbfb8aa3b, v134
	v_mul_f32_e32 v135, 0xbfb8aa3b, v135
	v_pk_mul_f32 v[126:127], v[126:127], v[124:125]
	v_exp_f32_e32 v134, v134
	v_exp_f32_e32 v135, v135
	v_rcp_f32_e32 v125, v175
	v_pk_add_f32 v[134:135], v[134:135], 1.0 op_sel_hi:[1,0]
	v_rcp_f32_e32 v124, v174
	s_nop 0
	v_pk_mul_f32 v[172:173], v[120:121], v[124:125]
	v_rcp_f32_e32 v121, v135
	s_nop 0
	v_rcp_f32_e32 v120, v134
	s_nop 0
	v_pk_mul_f32 v[134:135], v[122:123], v[120:121]
	v_lshlrev_b32_e32 v120, 16, v128
	v_mul_f32_e32 v120, 0xbfb8aa3b, v120
	v_exp_f32_e32 v122, v120
	v_and_b32_e32 v120, 0xffff0000, v128
	v_mul_f32_e32 v120, 0xbfb8aa3b, v120
	v_exp_f32_e32 v123, v120
	v_cvt_pk_bf16_f32 v121, v126, v127
	v_cvt_pk_bf16_f32 v120, v132, v133
	v_lshl_add_u64 v[124:125], v[170:171], 0, v[154:155]
	v_pk_add_f32 v[126:127], v[122:123], 1.0 op_sel_hi:[1,0]
	v_cvt_pk_bf16_f32 v122, v172, v173
	v_cvt_pk_bf16_f32 v123, v134, v135
	global_store_dwordx4 v[124:125], v[120:123], off
	s_nop 1
	v_lshlrev_b32_e32 v122, 16, v129
	v_and_b32_e32 v123, 0xffff0000, v129
	v_rcp_f32_e32 v121, v127
	v_mul_f32_e32 v122, 0xbfb8aa3b, v122
	v_mul_f32_e32 v123, 0xbfb8aa3b, v123
	v_exp_f32_e32 v122, v122
	v_exp_f32_e32 v123, v123
	s_nop 0
	v_pk_add_f32 v[128:129], v[122:123], 1.0 op_sel_hi:[1,0]
	v_rcp_f32_e32 v120, v126
	s_nop 0
	v_pk_mul_f32 v[126:127], v[116:117], v[120:121]
	v_rcp_f32_e32 v129, v129
	v_lshlrev_b32_e32 v116, 16, v130
	v_mul_f32_e32 v116, 0xbfb8aa3b, v116
	v_exp_f32_e32 v132, v116
	v_add_u32_e32 v116, s21, v162
	v_mad_i64_i32 v[120:121], s[0:1], v116, s49, v[158:159]
	v_lshl_add_u64 v[134:135], v[120:121], 0, v[154:155]
	global_load_dwordx4 v[120:123], v[134:135], off
	v_and_b32_e32 v130, 0xffff0000, v130
	v_mul_f32_e32 v130, 0xbfb8aa3b, v130
	v_exp_f32_e32 v133, v130
	s_nop 0
	v_pk_add_f32 v[132:133], v[132:133], 1.0 op_sel_hi:[1,0]
	v_rcp_f32_e32 v128, v128
	s_nop 0
	v_pk_mul_f32 v[118:119], v[118:119], v[128:129]
	v_lshlrev_b32_e32 v130, 16, v131
	v_and_b32_e32 v131, 0xffff0000, v131
	v_mul_f32_e32 v130, 0xbfb8aa3b, v130
	v_mul_f32_e32 v131, 0xbfb8aa3b, v131
	v_exp_f32_e32 v130, v130
	v_exp_f32_e32 v131, v131
	v_rcp_f32_e32 v129, v133
	v_pk_add_f32 v[130:131], v[130:131], 1.0 op_sel_hi:[1,0]
	v_rcp_f32_e32 v128, v132
	s_nop 0
	v_pk_mul_f32 v[128:129], v[112:113], v[128:129]
	v_rcp_f32_e32 v113, v131
	s_nop 0
	v_rcp_f32_e32 v112, v130
	s_nop 0
	v_pk_mul_f32 v[130:131], v[114:115], v[112:113]
	global_load_dwordx4 v[112:115], v[134:135], off offset:256
	v_cvt_pk_bf16_f32 v126, v126, v127
	v_cvt_pk_bf16_f32 v127, v118, v119
	v_cvt_pk_bf16_f32 v128, v128, v129
	v_cvt_pk_bf16_f32 v129, v130, v131
	s_waitcnt vmcnt(1)
	v_lshlrev_b32_e32 v117, 16, v120
	v_mul_f32_e32 v117, 0xbfb8aa3b, v117
	v_exp_f32_e32 v118, v117
	v_and_b32_e32 v117, 0xffff0000, v120
	v_mul_f32_e32 v117, 0xbfb8aa3b, v117
	v_exp_f32_e32 v119, v117
	global_store_dwordx4 v[124:125], v[126:129], off offset:256
	v_ashrrev_i32_e32 v117, 31, v116
	v_lshlrev_b64 v[116:117], 11, v[116:117]
	v_pk_add_f32 v[118:119], v[118:119], 1.0 op_sel_hi:[1,0]
	v_lshl_add_u64 v[116:117], s[16:17], 0, v[116:117]
	s_nop 0
	v_rcp_f32_e32 v119, v119
	v_lshlrev_b32_e32 v120, 16, v121
	v_and_b32_e32 v121, 0xffff0000, v121
	v_mul_f32_e32 v120, 0xbfb8aa3b, v120
	v_mul_f32_e32 v121, 0xbfb8aa3b, v121
	v_exp_f32_e32 v120, v120
	v_exp_f32_e32 v121, v121
	s_nop 0
	v_pk_add_f32 v[120:121], v[120:121], 1.0 op_sel_hi:[1,0]
	v_rcp_f32_e32 v118, v118
	s_nop 0
	v_pk_mul_f32 v[118:119], v[108:109], v[118:119]
	v_lshlrev_b32_e32 v124, 16, v122
	v_and_b32_e32 v122, 0xffff0000, v122
	v_mul_f32_e32 v124, 0xbfb8aa3b, v124
	v_mul_f32_e32 v122, 0xbfb8aa3b, v122
	v_exp_f32_e32 v124, v124
	v_exp_f32_e32 v125, v122
	v_rcp_f32_e32 v109, v121
	v_pk_add_f32 v[124:125], v[124:125], 1.0 op_sel_hi:[1,0]
	v_rcp_f32_e32 v108, v120
	s_nop 0
	v_pk_mul_f32 v[110:111], v[110:111], v[108:109]
	v_lshlrev_b32_e32 v120, 16, v123
	v_and_b32_e32 v121, 0xffff0000, v123
	v_mul_f32_e32 v120, 0xbfb8aa3b, v120
	v_mul_f32_e32 v121, 0xbfb8aa3b, v121
	v_exp_f32_e32 v120, v120
	v_exp_f32_e32 v121, v121
	v_rcp_f32_e32 v109, v125
	v_pk_add_f32 v[120:121], v[120:121], 1.0 op_sel_hi:[1,0]
	v_rcp_f32_e32 v108, v124
	s_nop 0
	v_pk_mul_f32 v[122:123], v[104:105], v[108:109]
	v_rcp_f32_e32 v105, v121
	s_nop 0
	v_rcp_f32_e32 v104, v120
	s_nop 0
	v_pk_mul_f32 v[120:121], v[106:107], v[104:105]
	s_waitcnt vmcnt(1)
	v_lshlrev_b32_e32 v104, 16, v112
	v_mul_f32_e32 v104, 0xbfb8aa3b, v104
	v_exp_f32_e32 v106, v104
	v_and_b32_e32 v104, 0xffff0000, v112
	v_mul_f32_e32 v104, 0xbfb8aa3b, v104
	v_exp_f32_e32 v107, v104
	v_cvt_pk_bf16_f32 v105, v110, v111
	v_lshl_add_u64 v[108:109], v[116:117], 0, v[154:155]
	v_cvt_pk_bf16_f32 v104, v118, v119
	v_pk_add_f32 v[110:111], v[106:107], 1.0 op_sel_hi:[1,0]
	v_cvt_pk_bf16_f32 v106, v122, v123
	v_cvt_pk_bf16_f32 v107, v120, v121
	global_store_dwordx4 v[108:109], v[104:107], off
	s_nop 1
	v_lshlrev_b32_e32 v106, 16, v113
	v_and_b32_e32 v107, 0xffff0000, v113
	v_rcp_f32_e32 v105, v111
	v_mul_f32_e32 v106, 0xbfb8aa3b, v106
	v_mul_f32_e32 v107, 0xbfb8aa3b, v107
	v_exp_f32_e32 v106, v106
	v_exp_f32_e32 v107, v107
	s_nop 0
	v_pk_add_f32 v[112:113], v[106:107], 1.0 op_sel_hi:[1,0]
	v_rcp_f32_e32 v104, v110
	s_nop 0
	v_pk_mul_f32 v[110:111], v[100:101], v[104:105]
	v_rcp_f32_e32 v113, v113
	v_lshlrev_b32_e32 v100, 16, v114
	v_mul_f32_e32 v100, 0xbfb8aa3b, v100
	v_exp_f32_e32 v116, v100
	v_add_u32_e32 v100, s21, v163
	v_mad_i64_i32 v[104:105], s[0:1], v100, s49, v[158:159]
	v_lshl_add_u64 v[118:119], v[104:105], 0, v[154:155]
	global_load_dwordx4 v[104:107], v[118:119], off
	v_and_b32_e32 v114, 0xffff0000, v114
	v_mul_f32_e32 v114, 0xbfb8aa3b, v114
	v_exp_f32_e32 v117, v114
	s_nop 0
	v_pk_add_f32 v[116:117], v[116:117], 1.0 op_sel_hi:[1,0]
	v_rcp_f32_e32 v112, v112
	s_nop 0
	v_pk_mul_f32 v[102:103], v[102:103], v[112:113]
	v_lshlrev_b32_e32 v114, 16, v115
	v_and_b32_e32 v115, 0xffff0000, v115
	v_mul_f32_e32 v114, 0xbfb8aa3b, v114
	v_mul_f32_e32 v115, 0xbfb8aa3b, v115
	v_exp_f32_e32 v114, v114
	v_exp_f32_e32 v115, v115
	v_rcp_f32_e32 v113, v117
	v_pk_add_f32 v[114:115], v[114:115], 1.0 op_sel_hi:[1,0]
	v_rcp_f32_e32 v112, v116
	s_nop 0
	v_pk_mul_f32 v[112:113], v[96:97], v[112:113]
	v_rcp_f32_e32 v97, v115
	s_nop 0
	v_rcp_f32_e32 v96, v114
	s_nop 0
	v_pk_mul_f32 v[114:115], v[98:99], v[96:97]
	global_load_dwordx4 v[96:99], v[118:119], off offset:256
	v_cvt_pk_bf16_f32 v110, v110, v111
	v_cvt_pk_bf16_f32 v111, v102, v103
	v_cvt_pk_bf16_f32 v112, v112, v113
	v_cvt_pk_bf16_f32 v113, v114, v115
	s_waitcnt vmcnt(1)
	v_lshlrev_b32_e32 v101, 16, v104
	v_mul_f32_e32 v101, 0xbfb8aa3b, v101
	v_exp_f32_e32 v102, v101
	v_and_b32_e32 v101, 0xffff0000, v104
	v_mul_f32_e32 v101, 0xbfb8aa3b, v101
	v_exp_f32_e32 v103, v101
	global_store_dwordx4 v[108:109], v[110:113], off offset:256
	v_ashrrev_i32_e32 v101, 31, v100
	v_lshlrev_b64 v[100:101], 11, v[100:101]
	v_pk_add_f32 v[102:103], v[102:103], 1.0 op_sel_hi:[1,0]
	v_lshl_add_u64 v[100:101], s[16:17], 0, v[100:101]
	s_nop 0
	v_rcp_f32_e32 v103, v103
	v_lshlrev_b32_e32 v104, 16, v105
	v_and_b32_e32 v105, 0xffff0000, v105
	v_mul_f32_e32 v104, 0xbfb8aa3b, v104
	v_mul_f32_e32 v105, 0xbfb8aa3b, v105
	v_exp_f32_e32 v104, v104
	v_exp_f32_e32 v105, v105
	s_nop 0
	v_pk_add_f32 v[104:105], v[104:105], 1.0 op_sel_hi:[1,0]
	v_rcp_f32_e32 v102, v102
	s_nop 0
	v_pk_mul_f32 v[102:103], v[92:93], v[102:103]
	v_lshlrev_b32_e32 v108, 16, v106
	v_and_b32_e32 v106, 0xffff0000, v106
	v_mul_f32_e32 v108, 0xbfb8aa3b, v108
	v_mul_f32_e32 v106, 0xbfb8aa3b, v106
	v_exp_f32_e32 v108, v108
	v_exp_f32_e32 v109, v106
	v_rcp_f32_e32 v93, v105
	v_pk_add_f32 v[108:109], v[108:109], 1.0 op_sel_hi:[1,0]
	v_rcp_f32_e32 v92, v104
	s_nop 0
	v_pk_mul_f32 v[94:95], v[94:95], v[92:93]
	v_lshlrev_b32_e32 v104, 16, v107
	v_and_b32_e32 v105, 0xffff0000, v107
	v_mul_f32_e32 v104, 0xbfb8aa3b, v104
	v_mul_f32_e32 v105, 0xbfb8aa3b, v105
	v_exp_f32_e32 v104, v104
	v_exp_f32_e32 v105, v105
	v_rcp_f32_e32 v93, v109
	v_pk_add_f32 v[104:105], v[104:105], 1.0 op_sel_hi:[1,0]
	v_rcp_f32_e32 v92, v108
	s_nop 0
	v_pk_mul_f32 v[106:107], v[88:89], v[92:93]
	v_rcp_f32_e32 v89, v105
	s_nop 0
	v_rcp_f32_e32 v88, v104
	s_nop 0
	v_pk_mul_f32 v[104:105], v[90:91], v[88:89]
	s_waitcnt vmcnt(1)
	v_lshlrev_b32_e32 v88, 16, v96
	v_mul_f32_e32 v88, 0xbfb8aa3b, v88
	v_exp_f32_e32 v90, v88
	v_and_b32_e32 v88, 0xffff0000, v96
	v_mul_f32_e32 v88, 0xbfb8aa3b, v88
	v_exp_f32_e32 v91, v88
	v_cvt_pk_bf16_f32 v89, v94, v95
	v_lshl_add_u64 v[92:93], v[100:101], 0, v[154:155]
	v_cvt_pk_bf16_f32 v88, v102, v103
	v_pk_add_f32 v[94:95], v[90:91], 1.0 op_sel_hi:[1,0]
	v_cvt_pk_bf16_f32 v90, v106, v107
	v_cvt_pk_bf16_f32 v91, v104, v105
	global_store_dwordx4 v[92:93], v[88:91], off
	s_nop 1
	v_lshlrev_b32_e32 v90, 16, v97
	v_and_b32_e32 v91, 0xffff0000, v97
	v_rcp_f32_e32 v89, v95
	v_mul_f32_e32 v90, 0xbfb8aa3b, v90
	v_mul_f32_e32 v91, 0xbfb8aa3b, v91
	v_exp_f32_e32 v90, v90
	v_exp_f32_e32 v91, v91
	s_nop 0
	v_pk_add_f32 v[96:97], v[90:91], 1.0 op_sel_hi:[1,0]
	v_rcp_f32_e32 v88, v94
	s_nop 0
	v_pk_mul_f32 v[94:95], v[84:85], v[88:89]
	v_rcp_f32_e32 v97, v97
	v_lshlrev_b32_e32 v84, 16, v98
	v_mul_f32_e32 v84, 0xbfb8aa3b, v84
	v_exp_f32_e32 v100, v84
	v_add_u32_e32 v84, s21, v164
	v_mad_i64_i32 v[88:89], s[0:1], v84, s49, v[158:159]
	v_lshl_add_u64 v[102:103], v[88:89], 0, v[154:155]
	global_load_dwordx4 v[88:91], v[102:103], off
	v_and_b32_e32 v98, 0xffff0000, v98
	v_mul_f32_e32 v98, 0xbfb8aa3b, v98
	v_exp_f32_e32 v101, v98
	s_nop 0
	v_pk_add_f32 v[100:101], v[100:101], 1.0 op_sel_hi:[1,0]
	v_rcp_f32_e32 v96, v96
	s_nop 0
	v_pk_mul_f32 v[86:87], v[86:87], v[96:97]
	v_lshlrev_b32_e32 v98, 16, v99
	v_and_b32_e32 v99, 0xffff0000, v99
	v_mul_f32_e32 v98, 0xbfb8aa3b, v98
	v_mul_f32_e32 v99, 0xbfb8aa3b, v99
	v_exp_f32_e32 v98, v98
	v_exp_f32_e32 v99, v99
	v_rcp_f32_e32 v97, v101
	v_pk_add_f32 v[98:99], v[98:99], 1.0 op_sel_hi:[1,0]
	v_rcp_f32_e32 v96, v100
	s_nop 0
	v_pk_mul_f32 v[96:97], v[80:81], v[96:97]
	v_rcp_f32_e32 v81, v99
	s_nop 0
	v_rcp_f32_e32 v80, v98
	s_nop 0
	v_pk_mul_f32 v[98:99], v[82:83], v[80:81]
	global_load_dwordx4 v[80:83], v[102:103], off offset:256
	v_cvt_pk_bf16_f32 v94, v94, v95
	v_cvt_pk_bf16_f32 v95, v86, v87
	v_cvt_pk_bf16_f32 v96, v96, v97
	v_cvt_pk_bf16_f32 v97, v98, v99
	s_waitcnt vmcnt(1)
	v_lshlrev_b32_e32 v85, 16, v88
	v_mul_f32_e32 v85, 0xbfb8aa3b, v85
	v_exp_f32_e32 v86, v85
	v_and_b32_e32 v85, 0xffff0000, v88
	v_mul_f32_e32 v85, 0xbfb8aa3b, v85
	v_exp_f32_e32 v87, v85
	global_store_dwordx4 v[92:93], v[94:97], off offset:256
	v_ashrrev_i32_e32 v85, 31, v84
	v_lshlrev_b64 v[84:85], 11, v[84:85]
	v_pk_add_f32 v[86:87], v[86:87], 1.0 op_sel_hi:[1,0]
	v_lshl_add_u64 v[84:85], s[16:17], 0, v[84:85]
	s_nop 0
	v_rcp_f32_e32 v87, v87
	v_lshlrev_b32_e32 v88, 16, v89
	v_and_b32_e32 v89, 0xffff0000, v89
	v_mul_f32_e32 v88, 0xbfb8aa3b, v88
	v_mul_f32_e32 v89, 0xbfb8aa3b, v89
	v_exp_f32_e32 v88, v88
	v_exp_f32_e32 v89, v89
	s_nop 0
	v_pk_add_f32 v[88:89], v[88:89], 1.0 op_sel_hi:[1,0]
	v_rcp_f32_e32 v86, v86
	s_nop 0
	v_pk_mul_f32 v[86:87], v[76:77], v[86:87]
	v_lshlrev_b32_e32 v92, 16, v90
	v_and_b32_e32 v90, 0xffff0000, v90
	v_mul_f32_e32 v92, 0xbfb8aa3b, v92
	v_mul_f32_e32 v90, 0xbfb8aa3b, v90
	v_exp_f32_e32 v92, v92
	v_exp_f32_e32 v93, v90
	v_rcp_f32_e32 v77, v89
	v_pk_add_f32 v[92:93], v[92:93], 1.0 op_sel_hi:[1,0]
	v_rcp_f32_e32 v76, v88
	s_nop 0
	v_pk_mul_f32 v[78:79], v[78:79], v[76:77]
	v_lshlrev_b32_e32 v88, 16, v91
	v_and_b32_e32 v89, 0xffff0000, v91
	v_mul_f32_e32 v88, 0xbfb8aa3b, v88
	v_mul_f32_e32 v89, 0xbfb8aa3b, v89
	v_exp_f32_e32 v88, v88
	v_exp_f32_e32 v89, v89
	v_rcp_f32_e32 v77, v93
	v_pk_add_f32 v[88:89], v[88:89], 1.0 op_sel_hi:[1,0]
	v_rcp_f32_e32 v76, v92
	s_nop 0
	v_pk_mul_f32 v[90:91], v[72:73], v[76:77]
	v_rcp_f32_e32 v73, v89
	s_nop 0
	v_rcp_f32_e32 v72, v88
	s_nop 0
	v_pk_mul_f32 v[88:89], v[74:75], v[72:73]
	s_waitcnt vmcnt(1)
	v_lshlrev_b32_e32 v72, 16, v80
	v_mul_f32_e32 v72, 0xbfb8aa3b, v72
	v_exp_f32_e32 v74, v72
	v_and_b32_e32 v72, 0xffff0000, v80
	v_mul_f32_e32 v72, 0xbfb8aa3b, v72
	v_exp_f32_e32 v75, v72
	v_cvt_pk_bf16_f32 v73, v78, v79
	v_lshl_add_u64 v[76:77], v[84:85], 0, v[154:155]
	v_cvt_pk_bf16_f32 v72, v86, v87
	v_pk_add_f32 v[78:79], v[74:75], 1.0 op_sel_hi:[1,0]
	v_cvt_pk_bf16_f32 v74, v90, v91
	v_cvt_pk_bf16_f32 v75, v88, v89
	global_store_dwordx4 v[76:77], v[72:75], off
	s_nop 1
	v_lshlrev_b32_e32 v74, 16, v81
	v_and_b32_e32 v75, 0xffff0000, v81
	v_rcp_f32_e32 v73, v79
	v_mul_f32_e32 v74, 0xbfb8aa3b, v74
	v_mul_f32_e32 v75, 0xbfb8aa3b, v75
	v_exp_f32_e32 v74, v74
	v_exp_f32_e32 v75, v75
	s_nop 0
	v_pk_add_f32 v[80:81], v[74:75], 1.0 op_sel_hi:[1,0]
	v_rcp_f32_e32 v72, v78
	s_nop 0
	v_pk_mul_f32 v[78:79], v[68:69], v[72:73]
	v_rcp_f32_e32 v81, v81
	v_lshlrev_b32_e32 v68, 16, v82
	v_mul_f32_e32 v68, 0xbfb8aa3b, v68
	v_exp_f32_e32 v84, v68
	v_add_u32_e32 v68, 0x80, v156
	v_mad_i64_i32 v[72:73], s[0:1], v68, s49, v[158:159]
	v_lshl_add_u64 v[86:87], v[72:73], 0, v[154:155]
	global_load_dwordx4 v[72:75], v[86:87], off
	v_and_b32_e32 v82, 0xffff0000, v82
	v_mul_f32_e32 v82, 0xbfb8aa3b, v82
	v_exp_f32_e32 v85, v82
	s_nop 0
	v_pk_add_f32 v[84:85], v[84:85], 1.0 op_sel_hi:[1,0]
	v_rcp_f32_e32 v80, v80
	s_nop 0
	v_pk_mul_f32 v[70:71], v[70:71], v[80:81]
	v_lshlrev_b32_e32 v82, 16, v83
	v_and_b32_e32 v83, 0xffff0000, v83
	v_mul_f32_e32 v82, 0xbfb8aa3b, v82
	v_mul_f32_e32 v83, 0xbfb8aa3b, v83
	v_exp_f32_e32 v82, v82
	v_exp_f32_e32 v83, v83
	v_rcp_f32_e32 v81, v85
	v_pk_add_f32 v[82:83], v[82:83], 1.0 op_sel_hi:[1,0]
	v_rcp_f32_e32 v80, v84
	s_nop 0
	v_pk_mul_f32 v[80:81], v[64:65], v[80:81]
	v_rcp_f32_e32 v65, v83
	s_nop 0
	v_rcp_f32_e32 v64, v82
	s_nop 0
	v_pk_mul_f32 v[82:83], v[66:67], v[64:65]
	global_load_dwordx4 v[64:67], v[86:87], off offset:256
	v_cvt_pk_bf16_f32 v78, v78, v79
	v_cvt_pk_bf16_f32 v79, v70, v71
	v_cvt_pk_bf16_f32 v80, v80, v81
	v_cvt_pk_bf16_f32 v81, v82, v83
	s_waitcnt vmcnt(1)
	v_lshlrev_b32_e32 v69, 16, v72
	v_mul_f32_e32 v69, 0xbfb8aa3b, v69
	v_exp_f32_e32 v70, v69
	v_and_b32_e32 v69, 0xffff0000, v72
	v_mul_f32_e32 v69, 0xbfb8aa3b, v69
	v_exp_f32_e32 v71, v69
	global_store_dwordx4 v[76:77], v[78:81], off offset:256
	v_ashrrev_i32_e32 v69, 31, v68
	v_lshlrev_b64 v[68:69], 11, v[68:69]
	v_pk_add_f32 v[70:71], v[70:71], 1.0 op_sel_hi:[1,0]
	v_lshl_add_u64 v[68:69], s[16:17], 0, v[68:69]
	s_nop 0
	v_rcp_f32_e32 v71, v71
	v_lshlrev_b32_e32 v72, 16, v73
	v_and_b32_e32 v73, 0xffff0000, v73
	v_mul_f32_e32 v72, 0xbfb8aa3b, v72
	v_mul_f32_e32 v73, 0xbfb8aa3b, v73
	v_exp_f32_e32 v72, v72
	v_exp_f32_e32 v73, v73
	s_nop 0
	v_pk_add_f32 v[72:73], v[72:73], 1.0 op_sel_hi:[1,0]
	v_rcp_f32_e32 v70, v70
	s_nop 0
	v_pk_mul_f32 v[70:71], v[60:61], v[70:71]
	v_lshlrev_b32_e32 v76, 16, v74
	v_and_b32_e32 v74, 0xffff0000, v74
	v_mul_f32_e32 v76, 0xbfb8aa3b, v76
	v_mul_f32_e32 v74, 0xbfb8aa3b, v74
	v_exp_f32_e32 v76, v76
	v_exp_f32_e32 v77, v74
	v_rcp_f32_e32 v61, v73
	v_pk_add_f32 v[76:77], v[76:77], 1.0 op_sel_hi:[1,0]
	v_rcp_f32_e32 v60, v72
	s_nop 0
	v_pk_mul_f32 v[62:63], v[62:63], v[60:61]
	v_lshlrev_b32_e32 v72, 16, v75
	v_and_b32_e32 v73, 0xffff0000, v75
	v_mul_f32_e32 v72, 0xbfb8aa3b, v72
	v_mul_f32_e32 v73, 0xbfb8aa3b, v73
	v_exp_f32_e32 v72, v72
	v_exp_f32_e32 v73, v73
	v_rcp_f32_e32 v61, v77
	v_pk_add_f32 v[72:73], v[72:73], 1.0 op_sel_hi:[1,0]
	v_rcp_f32_e32 v60, v76
	s_nop 0
	v_pk_mul_f32 v[74:75], v[56:57], v[60:61]
	v_rcp_f32_e32 v57, v73
	s_nop 0
	v_rcp_f32_e32 v56, v72
	s_nop 0
	v_pk_mul_f32 v[72:73], v[58:59], v[56:57]
	s_waitcnt vmcnt(1)
	v_lshlrev_b32_e32 v56, 16, v64
	v_mul_f32_e32 v56, 0xbfb8aa3b, v56
	v_exp_f32_e32 v58, v56
	v_and_b32_e32 v56, 0xffff0000, v64
	v_mul_f32_e32 v56, 0xbfb8aa3b, v56
	v_exp_f32_e32 v59, v56
	v_cvt_pk_bf16_f32 v57, v62, v63
	v_lshl_add_u64 v[60:61], v[68:69], 0, v[154:155]
	v_cvt_pk_bf16_f32 v56, v70, v71
	v_pk_add_f32 v[62:63], v[58:59], 1.0 op_sel_hi:[1,0]
	v_cvt_pk_bf16_f32 v58, v74, v75
	v_cvt_pk_bf16_f32 v59, v72, v73
	global_store_dwordx4 v[60:61], v[56:59], off
	s_nop 1
	v_lshlrev_b32_e32 v58, 16, v65
	v_and_b32_e32 v59, 0xffff0000, v65
	v_rcp_f32_e32 v57, v63
	v_mul_f32_e32 v58, 0xbfb8aa3b, v58
	v_mul_f32_e32 v59, 0xbfb8aa3b, v59
	v_exp_f32_e32 v58, v58
	v_exp_f32_e32 v59, v59
	s_nop 0
	v_pk_add_f32 v[64:65], v[58:59], 1.0 op_sel_hi:[1,0]
	v_rcp_f32_e32 v56, v62
	s_nop 0
	v_pk_mul_f32 v[62:63], v[52:53], v[56:57]
	v_rcp_f32_e32 v65, v65
	v_lshlrev_b32_e32 v52, 16, v66
	v_mul_f32_e32 v52, 0xbfb8aa3b, v52
	v_exp_f32_e32 v68, v52
	v_add_u32_e32 v52, 0x90, v156
	v_mad_i64_i32 v[56:57], s[0:1], v52, s49, v[158:159]
	v_lshl_add_u64 v[70:71], v[56:57], 0, v[154:155]
	global_load_dwordx4 v[56:59], v[70:71], off
	v_and_b32_e32 v66, 0xffff0000, v66
	v_mul_f32_e32 v66, 0xbfb8aa3b, v66
	v_exp_f32_e32 v69, v66
	s_nop 0
	v_pk_add_f32 v[68:69], v[68:69], 1.0 op_sel_hi:[1,0]
	v_rcp_f32_e32 v64, v64
	s_nop 0
	v_pk_mul_f32 v[54:55], v[54:55], v[64:65]
	v_lshlrev_b32_e32 v66, 16, v67
	v_and_b32_e32 v67, 0xffff0000, v67
	v_mul_f32_e32 v66, 0xbfb8aa3b, v66
	v_mul_f32_e32 v67, 0xbfb8aa3b, v67
	v_exp_f32_e32 v66, v66
	v_exp_f32_e32 v67, v67
	v_rcp_f32_e32 v65, v69
	v_pk_add_f32 v[66:67], v[66:67], 1.0 op_sel_hi:[1,0]
	v_rcp_f32_e32 v64, v68
	s_nop 0
	v_pk_mul_f32 v[64:65], v[48:49], v[64:65]
	v_rcp_f32_e32 v49, v67
	s_nop 0
	v_rcp_f32_e32 v48, v66
	s_nop 0
	v_pk_mul_f32 v[66:67], v[50:51], v[48:49]
	global_load_dwordx4 v[48:51], v[70:71], off offset:256
	v_cvt_pk_bf16_f32 v62, v62, v63
	v_cvt_pk_bf16_f32 v63, v54, v55
	v_cvt_pk_bf16_f32 v64, v64, v65
	v_cvt_pk_bf16_f32 v65, v66, v67
	s_waitcnt vmcnt(1)
	v_lshlrev_b32_e32 v53, 16, v56
	v_mul_f32_e32 v53, 0xbfb8aa3b, v53
	v_exp_f32_e32 v54, v53
	v_and_b32_e32 v53, 0xffff0000, v56
	v_mul_f32_e32 v53, 0xbfb8aa3b, v53
	v_exp_f32_e32 v55, v53
	global_store_dwordx4 v[60:61], v[62:65], off offset:256
	v_ashrrev_i32_e32 v53, 31, v52
	v_lshlrev_b64 v[52:53], 11, v[52:53]
	v_pk_add_f32 v[54:55], v[54:55], 1.0 op_sel_hi:[1,0]
	v_lshl_add_u64 v[52:53], s[16:17], 0, v[52:53]
	s_nop 0
	v_rcp_f32_e32 v55, v55
	v_lshlrev_b32_e32 v56, 16, v57
	v_and_b32_e32 v57, 0xffff0000, v57
	v_mul_f32_e32 v56, 0xbfb8aa3b, v56
	v_mul_f32_e32 v57, 0xbfb8aa3b, v57
	v_exp_f32_e32 v56, v56
	v_exp_f32_e32 v57, v57
	s_nop 0
	v_pk_add_f32 v[56:57], v[56:57], 1.0 op_sel_hi:[1,0]
	v_rcp_f32_e32 v54, v54
	s_nop 0
	v_pk_mul_f32 v[54:55], v[44:45], v[54:55]
	v_lshlrev_b32_e32 v60, 16, v58
	v_and_b32_e32 v58, 0xffff0000, v58
	v_mul_f32_e32 v60, 0xbfb8aa3b, v60
	v_mul_f32_e32 v58, 0xbfb8aa3b, v58
	v_exp_f32_e32 v60, v60
	v_exp_f32_e32 v61, v58
	v_rcp_f32_e32 v45, v57
	v_pk_add_f32 v[60:61], v[60:61], 1.0 op_sel_hi:[1,0]
	v_rcp_f32_e32 v44, v56
	s_nop 0
	v_pk_mul_f32 v[46:47], v[46:47], v[44:45]
	v_lshlrev_b32_e32 v56, 16, v59
	v_and_b32_e32 v57, 0xffff0000, v59
	v_mul_f32_e32 v56, 0xbfb8aa3b, v56
	v_mul_f32_e32 v57, 0xbfb8aa3b, v57
	v_exp_f32_e32 v56, v56
	v_exp_f32_e32 v57, v57
	v_rcp_f32_e32 v45, v61
	v_pk_add_f32 v[56:57], v[56:57], 1.0 op_sel_hi:[1,0]
	v_rcp_f32_e32 v44, v60
	s_nop 0
	v_pk_mul_f32 v[58:59], v[40:41], v[44:45]
	v_rcp_f32_e32 v41, v57
	s_nop 0
	v_rcp_f32_e32 v40, v56
	s_nop 0
	v_pk_mul_f32 v[56:57], v[42:43], v[40:41]
	s_waitcnt vmcnt(1)
	v_lshlrev_b32_e32 v40, 16, v48
	v_mul_f32_e32 v40, 0xbfb8aa3b, v40
	v_exp_f32_e32 v42, v40
	v_and_b32_e32 v40, 0xffff0000, v48
	v_mul_f32_e32 v40, 0xbfb8aa3b, v40
	v_exp_f32_e32 v43, v40
	v_cvt_pk_bf16_f32 v41, v46, v47
	v_lshl_add_u64 v[44:45], v[52:53], 0, v[154:155]
	v_cvt_pk_bf16_f32 v40, v54, v55
	v_pk_add_f32 v[46:47], v[42:43], 1.0 op_sel_hi:[1,0]
	v_cvt_pk_bf16_f32 v42, v58, v59
	v_cvt_pk_bf16_f32 v43, v56, v57
	global_store_dwordx4 v[44:45], v[40:43], off
	s_nop 1
	v_lshlrev_b32_e32 v42, 16, v49
	v_and_b32_e32 v43, 0xffff0000, v49
	v_rcp_f32_e32 v41, v47
	v_mul_f32_e32 v42, 0xbfb8aa3b, v42
	v_mul_f32_e32 v43, 0xbfb8aa3b, v43
	v_exp_f32_e32 v42, v42
	v_exp_f32_e32 v43, v43
	s_nop 0
	v_pk_add_f32 v[48:49], v[42:43], 1.0 op_sel_hi:[1,0]
	v_rcp_f32_e32 v40, v46
	s_nop 0
	v_pk_mul_f32 v[46:47], v[36:37], v[40:41]
	v_rcp_f32_e32 v49, v49
	v_lshlrev_b32_e32 v36, 16, v50
	v_mul_f32_e32 v36, 0xbfb8aa3b, v36
	v_exp_f32_e32 v52, v36
	v_add_u32_e32 v36, 0xa0, v156
	v_mad_i64_i32 v[40:41], s[0:1], v36, s49, v[158:159]
	v_lshl_add_u64 v[54:55], v[40:41], 0, v[154:155]
	global_load_dwordx4 v[40:43], v[54:55], off
	v_and_b32_e32 v50, 0xffff0000, v50
	v_mul_f32_e32 v50, 0xbfb8aa3b, v50
	v_exp_f32_e32 v53, v50
	s_nop 0
	v_pk_add_f32 v[52:53], v[52:53], 1.0 op_sel_hi:[1,0]
	v_rcp_f32_e32 v48, v48
	s_nop 0
	v_pk_mul_f32 v[38:39], v[38:39], v[48:49]
	v_lshlrev_b32_e32 v50, 16, v51
	v_and_b32_e32 v51, 0xffff0000, v51
	v_mul_f32_e32 v50, 0xbfb8aa3b, v50
	v_mul_f32_e32 v51, 0xbfb8aa3b, v51
	v_exp_f32_e32 v50, v50
	v_exp_f32_e32 v51, v51
	v_rcp_f32_e32 v49, v53
	v_pk_add_f32 v[50:51], v[50:51], 1.0 op_sel_hi:[1,0]
	v_rcp_f32_e32 v48, v52
	s_nop 0
	v_pk_mul_f32 v[48:49], v[32:33], v[48:49]
	v_rcp_f32_e32 v33, v51
	s_nop 0
	v_rcp_f32_e32 v32, v50
	s_nop 0
	v_pk_mul_f32 v[50:51], v[34:35], v[32:33]
	global_load_dwordx4 v[32:35], v[54:55], off offset:256
	v_cvt_pk_bf16_f32 v46, v46, v47
	v_cvt_pk_bf16_f32 v47, v38, v39
	v_cvt_pk_bf16_f32 v48, v48, v49
	v_cvt_pk_bf16_f32 v49, v50, v51
	s_waitcnt vmcnt(1)
	v_lshlrev_b32_e32 v37, 16, v40
	v_mul_f32_e32 v37, 0xbfb8aa3b, v37
	v_exp_f32_e32 v38, v37
	v_and_b32_e32 v37, 0xffff0000, v40
	v_mul_f32_e32 v37, 0xbfb8aa3b, v37
	v_exp_f32_e32 v39, v37
	global_store_dwordx4 v[44:45], v[46:49], off offset:256
	v_ashrrev_i32_e32 v37, 31, v36
	v_lshlrev_b64 v[36:37], 11, v[36:37]
	v_pk_add_f32 v[38:39], v[38:39], 1.0 op_sel_hi:[1,0]
	v_lshl_add_u64 v[36:37], s[16:17], 0, v[36:37]
	s_nop 0
	v_rcp_f32_e32 v39, v39
	v_lshlrev_b32_e32 v40, 16, v41
	v_and_b32_e32 v41, 0xffff0000, v41
	v_mul_f32_e32 v40, 0xbfb8aa3b, v40
	v_mul_f32_e32 v41, 0xbfb8aa3b, v41
	v_exp_f32_e32 v40, v40
	v_exp_f32_e32 v41, v41
	s_nop 0
	v_pk_add_f32 v[40:41], v[40:41], 1.0 op_sel_hi:[1,0]
	v_rcp_f32_e32 v38, v38
	s_nop 0
	v_pk_mul_f32 v[38:39], v[28:29], v[38:39]
	v_lshlrev_b32_e32 v44, 16, v42
	v_and_b32_e32 v42, 0xffff0000, v42
	v_mul_f32_e32 v44, 0xbfb8aa3b, v44
	v_mul_f32_e32 v42, 0xbfb8aa3b, v42
	v_exp_f32_e32 v44, v44
	v_exp_f32_e32 v45, v42
	v_rcp_f32_e32 v29, v41
	v_pk_add_f32 v[44:45], v[44:45], 1.0 op_sel_hi:[1,0]
	v_rcp_f32_e32 v28, v40
	s_nop 0
	v_pk_mul_f32 v[30:31], v[30:31], v[28:29]
	v_lshlrev_b32_e32 v40, 16, v43
	v_and_b32_e32 v41, 0xffff0000, v43
	v_mul_f32_e32 v40, 0xbfb8aa3b, v40
	v_mul_f32_e32 v41, 0xbfb8aa3b, v41
	v_exp_f32_e32 v40, v40
	v_exp_f32_e32 v41, v41
	v_rcp_f32_e32 v29, v45
	v_pk_add_f32 v[40:41], v[40:41], 1.0 op_sel_hi:[1,0]
	v_rcp_f32_e32 v28, v44
	s_nop 0
	v_pk_mul_f32 v[42:43], v[24:25], v[28:29]
	v_rcp_f32_e32 v25, v41
	s_nop 0
	v_rcp_f32_e32 v24, v40
	s_nop 0
	v_pk_mul_f32 v[40:41], v[26:27], v[24:25]
	s_waitcnt vmcnt(1)
	v_lshlrev_b32_e32 v24, 16, v32
	v_mul_f32_e32 v24, 0xbfb8aa3b, v24
	v_exp_f32_e32 v26, v24
	v_and_b32_e32 v24, 0xffff0000, v32
	v_mul_f32_e32 v24, 0xbfb8aa3b, v24
	v_exp_f32_e32 v27, v24
	v_cvt_pk_bf16_f32 v25, v30, v31
	v_lshl_add_u64 v[28:29], v[36:37], 0, v[154:155]
	v_cvt_pk_bf16_f32 v24, v38, v39
	v_pk_add_f32 v[30:31], v[26:27], 1.0 op_sel_hi:[1,0]
	v_cvt_pk_bf16_f32 v26, v42, v43
	v_cvt_pk_bf16_f32 v27, v40, v41
	global_store_dwordx4 v[28:29], v[24:27], off
	s_nop 1
	v_lshlrev_b32_e32 v26, 16, v33
	v_and_b32_e32 v27, 0xffff0000, v33
	v_rcp_f32_e32 v25, v31
	v_mul_f32_e32 v26, 0xbfb8aa3b, v26
	v_mul_f32_e32 v27, 0xbfb8aa3b, v27
	v_exp_f32_e32 v26, v26
	v_exp_f32_e32 v27, v27
	s_nop 0
	v_pk_add_f32 v[32:33], v[26:27], 1.0 op_sel_hi:[1,0]
	v_rcp_f32_e32 v24, v30
	s_nop 0
	v_pk_mul_f32 v[30:31], v[20:21], v[24:25]
	v_rcp_f32_e32 v33, v33
	v_lshlrev_b32_e32 v20, 16, v34
	v_mul_f32_e32 v20, 0xbfb8aa3b, v20
	v_exp_f32_e32 v36, v20
	v_add_u32_e32 v20, 0xb0, v156
	v_mad_i64_i32 v[24:25], s[0:1], v20, s49, v[158:159]
	v_lshl_add_u64 v[38:39], v[24:25], 0, v[154:155]
	global_load_dwordx4 v[24:27], v[38:39], off
	v_and_b32_e32 v34, 0xffff0000, v34
	v_mul_f32_e32 v34, 0xbfb8aa3b, v34
	v_exp_f32_e32 v37, v34
	s_nop 0
	v_pk_add_f32 v[36:37], v[36:37], 1.0 op_sel_hi:[1,0]
	v_rcp_f32_e32 v32, v32
	s_nop 0
	v_pk_mul_f32 v[22:23], v[22:23], v[32:33]
	v_lshlrev_b32_e32 v34, 16, v35
	v_and_b32_e32 v35, 0xffff0000, v35
	v_mul_f32_e32 v34, 0xbfb8aa3b, v34
	v_mul_f32_e32 v35, 0xbfb8aa3b, v35
	v_exp_f32_e32 v34, v34
	v_exp_f32_e32 v35, v35
	v_rcp_f32_e32 v33, v37
	v_pk_add_f32 v[34:35], v[34:35], 1.0 op_sel_hi:[1,0]
	v_rcp_f32_e32 v32, v36
	s_nop 0
	v_pk_mul_f32 v[32:33], v[16:17], v[32:33]
	v_rcp_f32_e32 v17, v35
	s_nop 0
	v_rcp_f32_e32 v16, v34
	s_nop 0
	v_pk_mul_f32 v[34:35], v[18:19], v[16:17]
	global_load_dwordx4 v[16:19], v[38:39], off offset:256
	v_cvt_pk_bf16_f32 v30, v30, v31
	v_cvt_pk_bf16_f32 v31, v22, v23
	v_cvt_pk_bf16_f32 v32, v32, v33
	v_cvt_pk_bf16_f32 v33, v34, v35
	s_waitcnt vmcnt(1)
	v_lshlrev_b32_e32 v21, 16, v24
	v_mul_f32_e32 v21, 0xbfb8aa3b, v21
	v_exp_f32_e32 v22, v21
	v_and_b32_e32 v21, 0xffff0000, v24
	v_mul_f32_e32 v21, 0xbfb8aa3b, v21
	v_exp_f32_e32 v23, v21
	global_store_dwordx4 v[28:29], v[30:33], off offset:256
	v_ashrrev_i32_e32 v21, 31, v20
	v_lshlrev_b64 v[20:21], 11, v[20:21]
	v_pk_add_f32 v[22:23], v[22:23], 1.0 op_sel_hi:[1,0]
	v_lshl_add_u64 v[20:21], s[16:17], 0, v[20:21]
	v_lshl_add_u64 v[20:21], v[20:21], 0, v[154:155]
	v_rcp_f32_e32 v23, v23
	v_lshlrev_b32_e32 v24, 16, v25
	v_and_b32_e32 v25, 0xffff0000, v25
	v_mul_f32_e32 v24, 0xbfb8aa3b, v24
	v_mul_f32_e32 v25, 0xbfb8aa3b, v25
	v_exp_f32_e32 v24, v24
	v_exp_f32_e32 v25, v25
	s_nop 0
	v_pk_add_f32 v[24:25], v[24:25], 1.0 op_sel_hi:[1,0]
	v_rcp_f32_e32 v22, v22
	s_nop 0
	v_pk_mul_f32 v[12:13], v[12:13], v[22:23]
	v_lshlrev_b32_e32 v28, 16, v26
	v_and_b32_e32 v26, 0xffff0000, v26
	v_mul_f32_e32 v28, 0xbfb8aa3b, v28
	v_mul_f32_e32 v26, 0xbfb8aa3b, v26
	v_exp_f32_e32 v28, v28
	v_exp_f32_e32 v29, v26
	v_rcp_f32_e32 v23, v25
	v_pk_add_f32 v[28:29], v[28:29], 1.0 op_sel_hi:[1,0]
	v_rcp_f32_e32 v22, v24
	s_nop 0
	v_pk_mul_f32 v[14:15], v[14:15], v[22:23]
	v_lshlrev_b32_e32 v24, 16, v27
	v_and_b32_e32 v25, 0xffff0000, v27
	v_mul_f32_e32 v24, 0xbfb8aa3b, v24
	v_mul_f32_e32 v25, 0xbfb8aa3b, v25
	v_rcp_f32_e32 v23, v29
	v_exp_f32_e32 v24, v24
	v_exp_f32_e32 v25, v25
	s_nop 0
	v_pk_add_f32 v[24:25], v[24:25], 1.0 op_sel_hi:[1,0]
	v_rcp_f32_e32 v22, v28
	s_nop 0
	v_pk_mul_f32 v[22:23], v[8:9], v[22:23]
	v_rcp_f32_e32 v9, v25
	s_nop 0
	v_rcp_f32_e32 v8, v24
	s_nop 0
	v_pk_mul_f32 v[24:25], v[10:11], v[8:9]
	s_waitcnt vmcnt(1)
	v_lshlrev_b32_e32 v8, 16, v16
	v_mul_f32_e32 v8, 0xbfb8aa3b, v8
	v_exp_f32_e32 v10, v8
	v_and_b32_e32 v8, 0xffff0000, v16
	v_mul_f32_e32 v8, 0xbfb8aa3b, v8
	v_exp_f32_e32 v11, v8
	v_cvt_pk_bf16_f32 v8, v12, v13
	v_cvt_pk_bf16_f32 v9, v14, v15
	v_pk_add_f32 v[12:13], v[10:11], 1.0 op_sel_hi:[1,0]
	s_nop 0
	v_cvt_pk_bf16_f32 v10, v22, v23
	v_cvt_pk_bf16_f32 v11, v24, v25
	global_store_dwordx4 v[20:21], v[8:11], off
	s_nop 1
	v_lshlrev_b32_e32 v10, 16, v17
	v_and_b32_e32 v11, 0xffff0000, v17
	v_mul_f32_e32 v10, 0xbfb8aa3b, v10
	v_mul_f32_e32 v11, 0xbfb8aa3b, v11
	v_rcp_f32_e32 v9, v13
	v_exp_f32_e32 v10, v10
	v_exp_f32_e32 v11, v11
	s_nop 0
	v_pk_add_f32 v[10:11], v[10:11], 1.0 op_sel_hi:[1,0]
	v_rcp_f32_e32 v8, v12
	s_nop 0
	v_pk_mul_f32 v[4:5], v[4:5], v[8:9]
	v_lshlrev_b32_e32 v12, 16, v18
	v_and_b32_e32 v13, 0xffff0000, v18
	v_mul_f32_e32 v12, 0xbfb8aa3b, v12
	v_mul_f32_e32 v13, 0xbfb8aa3b, v13
	v_rcp_f32_e32 v9, v11
	v_exp_f32_e32 v12, v12
	v_exp_f32_e32 v13, v13
	s_nop 0
	v_pk_add_f32 v[12:13], v[12:13], 1.0 op_sel_hi:[1,0]
	v_rcp_f32_e32 v8, v10
	s_nop 0
	v_pk_mul_f32 v[6:7], v[6:7], v[8:9]
	v_lshlrev_b32_e32 v10, 16, v19
	v_and_b32_e32 v11, 0xffff0000, v19
	v_mul_f32_e32 v10, 0xbfb8aa3b, v10
	v_mul_f32_e32 v11, 0xbfb8aa3b, v11
	v_rcp_f32_e32 v9, v13
	v_exp_f32_e32 v10, v10
	v_exp_f32_e32 v11, v11
	s_nop 0
	v_pk_add_f32 v[10:11], v[10:11], 1.0 op_sel_hi:[1,0]
	v_rcp_f32_e32 v8, v12
	s_nop 0
	v_pk_mul_f32 v[8:9], v[0:1], v[8:9]
	v_rcp_f32_e32 v1, v11
	s_nop 0
	v_rcp_f32_e32 v0, v10
	s_nop 0
	v_pk_mul_f32 v[10:11], v[2:3], v[0:1]
	v_cvt_pk_bf16_f32 v0, v4, v5
	v_cvt_pk_bf16_f32 v1, v6, v7
	v_cvt_pk_bf16_f32 v2, v8, v9
	v_cvt_pk_bf16_f32 v3, v10, v11
	s_andn2_b64 vcc, exec, s[2:3]
	s_mov_b64 s[0:1], -1
	global_store_dwordx4 v[20:21], v[0:3], off offset:256
	s_cbranch_vccnz .LBB0_841
	s_andn2_b64 vcc, exec, s[10:11]
	s_cbranch_vccnz .LBB0_840
	s_barrier
	s_branch .LBB0_840

.LBB0_931:
	s_lshl_b32 s21, s0, 8
	v_lshl_or_b32 v130, s1, 8, v167
	v_add_u32_e32 v156, s21, v162
	v_mov_b64_e32 v[158:159], s[18:19]
	v_ashrrev_i32_e32 v131, 31, v130
	v_mad_i64_i32 v[128:129], s[4:5], v156, s51, v[158:159]
	v_lshlrev_b64 v[154:155], 1, v[130:131]
	v_lshl_add_u64 v[128:129], v[128:129], 0, v[154:155]
	global_load_dwordx4 v[172:175], v[128:129], off
	v_ashrrev_i32_e32 v157, 31, v156
	v_lshlrev_b64 v[130:131], 11, v[156:157]
	v_lshl_add_u64 v[130:131], s[16:17], 0, v[130:131]
	v_lshl_add_u64 v[160:161], v[130:131], 0, v[154:155]
	global_load_dwordx4 v[132:135], v[160:161], off
	global_load_dwordx4 v[176:179], v[128:129], off offset:256
	s_nop 0
	global_load_dwordx4 v[128:131], v[160:161], off offset:256
	s_waitcnt vmcnt(0)
	v_lshlrev_b32_e32 v157, 16, v172
	v_and_b32_e32 v171, 0xffff0000, v172
	v_lshlrev_b32_e32 v172, 16, v173
	v_and_b32_e32 v173, 0xffff0000, v173
	v_mul_f32_e32 v157, 0xbfb8aa3b, v157
	v_mul_f32_e32 v171, 0xbfb8aa3b, v171
	v_mul_f32_e32 v182, 0xbfb8aa3b, v172
	v_mul_f32_e32 v183, 0xbfb8aa3b, v173
	v_exp_f32_e32 v172, v157
	v_exp_f32_e32 v173, v171
	v_lshlrev_b32_e32 v180, 16, v174
	v_and_b32_e32 v174, 0xffff0000, v174
	v_lshlrev_b32_e32 v181, 16, v175
	v_and_b32_e32 v175, 0xffff0000, v175
	v_mul_f32_e32 v185, 0xbfb8aa3b, v174
	v_mul_f32_e32 v187, 0xbfb8aa3b, v175
	v_exp_f32_e32 v174, v182
	v_exp_f32_e32 v175, v183
	v_pk_add_f32 v[172:173], v[172:173], 1.0 op_sel_hi:[1,0]
	v_mul_f32_e32 v186, 0xbfb8aa3b, v181
	v_exp_f32_e32 v181, v185
	v_pk_add_f32 v[174:175], v[174:175], 1.0 op_sel_hi:[1,0]
	v_mul_f32_e32 v180, 0xbfb8aa3b, v180
	v_exp_f32_e32 v180, v180
	s_nop 0
	v_pk_add_f32 v[180:181], v[180:181], 1.0 op_sel_hi:[1,0]
	s_mov_b64 vcc, s[0:1]
	v_rcp_f32_e32 v173, v173
	s_mov_b64 vcc, s[4:5]
	v_exp_f32_e32 v182, v186
	v_exp_f32_e32 v183, v187
	v_lshlrev_b32_e32 v186, 16, v132
	v_and_b32_e32 v187, 0xffff0000, v132
	v_rcp_f32_e32 v172, v172
	s_mov_b64 vcc, s[6:7]
	v_pk_fma_f32 v[124:125], v[124:125], v[172:173], v[186:187]
	v_rcp_f32_e32 v173, v175
	v_lshlrev_b32_e32 v132, 16, v133
	v_rcp_f32_e32 v172, v174
	v_and_b32_e32 v133, 0xffff0000, v133
	v_pk_fma_f32 v[126:127], v[126:127], v[172:173], v[132:133]
	v_rcp_f32_e32 v133, v181
	v_pk_add_f32 v[172:173], v[182:183], 1.0 op_sel_hi:[1,0]
	v_rcp_f32_e32 v132, v180
	v_lshlrev_b32_e32 v174, 16, v134
	v_and_b32_e32 v175, 0xffff0000, v134
	v_pk_fma_f32 v[132:133], v[120:121], v[132:133], v[174:175]
	v_rcp_f32_e32 v121, v173
	s_nop 0
	v_rcp_f32_e32 v120, v172
	v_lshlrev_b32_e32 v134, 16, v135
	v_and_b32_e32 v135, 0xffff0000, v135
	v_pk_fma_f32 v[134:135], v[122:123], v[120:121], v[134:135]
	v_cvt_pk_bf16_f32 v120, v124, v125
	v_cvt_pk_bf16_f32 v121, v126, v127
	v_cvt_pk_bf16_f32 v122, v132, v133
	v_cvt_pk_bf16_f32 v123, v134, v135
	global_store_dwordx4 v[160:161], v[120:123], off
	v_lshlrev_b32_e32 v126, 16, v179
	v_mul_f32_e32 v126, 0xbfb8aa3b, v126
	v_lshlrev_b32_e32 v120, 16, v176
	v_and_b32_e32 v121, 0xffff0000, v176
	v_mul_f32_e32 v120, 0xbfb8aa3b, v120
	v_mul_f32_e32 v121, 0xbfb8aa3b, v121
	v_exp_f32_e32 v120, v120
	v_exp_f32_e32 v121, v121
	v_exp_f32_e32 v132, v126
	v_lshlrev_b32_e32 v122, 16, v177
	v_and_b32_e32 v123, 0xffff0000, v177
	v_pk_add_f32 v[120:121], v[120:121], 1.0 op_sel_hi:[1,0]
	v_mul_f32_e32 v122, 0xbfb8aa3b, v122
	v_mul_f32_e32 v123, 0xbfb8aa3b, v123
	v_exp_f32_e32 v122, v122
	v_exp_f32_e32 v123, v123
	v_rcp_f32_e32 v121, v121
	v_lshlrev_b32_e32 v124, 16, v178
	v_pk_add_f32 v[134:135], v[122:123], 1.0 op_sel_hi:[1,0]
	v_rcp_f32_e32 v120, v120
	v_lshlrev_b32_e32 v122, 16, v128
	v_and_b32_e32 v123, 0xffff0000, v128
	v_pk_fma_f32 v[172:173], v[116:117], v[120:121], v[122:123]
	v_and_b32_e32 v125, 0xffff0000, v178
	v_mul_f32_e32 v124, 0xbfb8aa3b, v124
	v_mul_f32_e32 v125, 0xbfb8aa3b, v125
	v_rcp_f32_e32 v117, v135
	v_exp_f32_e32 v124, v124
	v_exp_f32_e32 v125, v125
	v_add_u32_e32 v128, s21, v164
	v_pk_add_f32 v[124:125], v[124:125], 1.0 op_sel_hi:[1,0]
	v_mad_i64_i32 v[120:121], s[0:1], v128, s51, v[158:159]
	v_lshl_add_u64 v[126:127], v[120:121], 0, v[154:155]
	global_load_dwordx4 v[120:123], v[126:127], off
	v_rcp_f32_e32 v116, v134
	v_lshlrev_b32_e32 v134, 16, v129
	v_and_b32_e32 v135, 0xffff0000, v129
	v_pk_fma_f32 v[134:135], v[118:119], v[116:117], v[134:135]
	v_and_b32_e32 v133, 0xffff0000, v179
	v_rcp_f32_e32 v117, v125
	v_mul_f32_e32 v133, 0xbfb8aa3b, v133
	v_exp_f32_e32 v133, v133
	s_nop 0
	v_pk_add_f32 v[132:133], v[132:133], 1.0 op_sel_hi:[1,0]
	v_rcp_f32_e32 v116, v124
	v_lshlrev_b32_e32 v118, 16, v130
	v_and_b32_e32 v119, 0xffff0000, v130
	v_pk_fma_f32 v[174:175], v[112:113], v[116:117], v[118:119]
	v_ashrrev_i32_e32 v129, 31, v128
	v_lshlrev_b64 v[112:113], 11, v[128:129]
	v_lshl_add_u64 v[112:113], s[16:17], 0, v[112:113]
	v_lshl_add_u64 v[124:125], v[112:113], 0, v[154:155]
	global_load_dwordx4 v[116:119], v[124:125], off
	v_rcp_f32_e32 v113, v133
	s_nop 0
	v_rcp_f32_e32 v112, v132
	v_lshlrev_b32_e32 v128, 16, v131
	v_and_b32_e32 v129, 0xffff0000, v131
	v_pk_fma_f32 v[128:129], v[114:115], v[112:113], v[128:129]
	v_cvt_pk_bf16_f32 v112, v172, v173
	v_cvt_pk_bf16_f32 v113, v134, v135
	v_cvt_pk_bf16_f32 v114, v174, v175
	v_cvt_pk_bf16_f32 v115, v128, v129
	global_store_dwordx4 v[160:161], v[112:115], off offset:256
	global_load_dwordx4 v[126:129], v[126:127], off offset:256
	s_waitcnt vmcnt(3)
	v_lshlrev_b32_e32 v112, 16, v120
	v_and_b32_e32 v113, 0xffff0000, v120
	v_mul_f32_e32 v112, 0xbfb8aa3b, v112
	v_mul_f32_e32 v113, 0xbfb8aa3b, v113
	v_exp_f32_e32 v112, v112
	v_exp_f32_e32 v113, v113
	v_lshlrev_b32_e32 v114, 16, v121
	v_and_b32_e32 v115, 0xffff0000, v121
	v_mul_f32_e32 v114, 0xbfb8aa3b, v114
	v_pk_add_f32 v[112:113], v[112:113], 1.0 op_sel_hi:[1,0]
	v_mul_f32_e32 v115, 0xbfb8aa3b, v115
	v_exp_f32_e32 v114, v114
	v_exp_f32_e32 v115, v115
	v_lshlrev_b32_e32 v120, 16, v122
	v_rcp_f32_e32 v131, v113
	v_and_b32_e32 v121, 0xffff0000, v122
	v_pk_add_f32 v[132:133], v[114:115], 1.0 op_sel_hi:[1,0]
	v_rcp_f32_e32 v130, v112
	global_load_dwordx4 v[112:115], v[124:125], off offset:256
	v_mul_f32_e32 v120, 0xbfb8aa3b, v120
	v_mul_f32_e32 v121, 0xbfb8aa3b, v121
	v_exp_f32_e32 v120, v120
	v_exp_f32_e32 v121, v121
	v_lshlrev_b32_e32 v122, 16, v123
	s_waitcnt vmcnt(3)
	v_lshlrev_b32_e32 v134, 16, v116
	v_and_b32_e32 v135, 0xffff0000, v116
	v_pk_fma_f32 v[108:109], v[108:109], v[130:131], v[134:135]
	v_rcp_f32_e32 v131, v133
	v_pk_add_f32 v[120:121], v[120:121], 1.0 op_sel_hi:[1,0]
	v_rcp_f32_e32 v130, v132
	v_lshlrev_b32_e32 v116, 16, v117
	v_and_b32_e32 v117, 0xffff0000, v117
	v_pk_fma_f32 v[110:111], v[110:111], v[130:131], v[116:117]
	v_rcp_f32_e32 v117, v121
	v_and_b32_e32 v123, 0xffff0000, v123
	v_mul_f32_e32 v122, 0xbfb8aa3b, v122
	v_mul_f32_e32 v123, 0xbfb8aa3b, v123
	v_exp_f32_e32 v122, v122
	v_exp_f32_e32 v123, v123
	v_rcp_f32_e32 v116, v120
	v_pk_add_f32 v[120:121], v[122:123], 1.0 op_sel_hi:[1,0]
	v_lshlrev_b32_e32 v122, 16, v118
	v_and_b32_e32 v123, 0xffff0000, v118
	v_pk_fma_f32 v[116:117], v[104:105], v[116:117], v[122:123]
	v_rcp_f32_e32 v105, v121
	s_nop 0
	v_rcp_f32_e32 v104, v120
	v_lshlrev_b32_e32 v118, 16, v119
	v_and_b32_e32 v119, 0xffff0000, v119
	v_pk_fma_f32 v[118:119], v[106:107], v[104:105], v[118:119]
	v_cvt_pk_bf16_f32 v104, v108, v109
	v_cvt_pk_bf16_f32 v105, v110, v111
	v_cvt_pk_bf16_f32 v106, v116, v117
	v_cvt_pk_bf16_f32 v107, v118, v119
	global_store_dwordx4 v[124:125], v[104:107], off
	s_waitcnt vmcnt(2)
	v_lshlrev_b32_e32 v110, 16, v129
	v_mul_f32_e32 v110, 0xbfb8aa3b, v110
	v_lshlrev_b32_e32 v104, 16, v126
	v_and_b32_e32 v105, 0xffff0000, v126
	v_mul_f32_e32 v104, 0xbfb8aa3b, v104
	v_mul_f32_e32 v105, 0xbfb8aa3b, v105
	v_exp_f32_e32 v104, v104
	v_exp_f32_e32 v105, v105
	v_exp_f32_e32 v116, v110
	v_lshlrev_b32_e32 v106, 16, v127
	v_and_b32_e32 v107, 0xffff0000, v127
	v_pk_add_f32 v[104:105], v[104:105], 1.0 op_sel_hi:[1,0]
	v_mul_f32_e32 v106, 0xbfb8aa3b, v106
	v_mul_f32_e32 v107, 0xbfb8aa3b, v107
	v_exp_f32_e32 v106, v106
	v_exp_f32_e32 v107, v107
	v_rcp_f32_e32 v105, v105
	v_lshlrev_b32_e32 v108, 16, v128
	v_pk_add_f32 v[118:119], v[106:107], 1.0 op_sel_hi:[1,0]
	v_rcp_f32_e32 v104, v104
	s_waitcnt vmcnt(1)
	v_lshlrev_b32_e32 v106, 16, v112
	v_and_b32_e32 v107, 0xffff0000, v112
	v_pk_fma_f32 v[120:121], v[100:101], v[104:105], v[106:107]
	v_and_b32_e32 v109, 0xffff0000, v128
	v_mul_f32_e32 v108, 0xbfb8aa3b, v108
	v_mul_f32_e32 v109, 0xbfb8aa3b, v109
	v_rcp_f32_e32 v101, v119
	v_exp_f32_e32 v108, v108
	v_exp_f32_e32 v109, v109
	v_add_u32_e32 v112, s21, v165
	v_pk_add_f32 v[108:109], v[108:109], 1.0 op_sel_hi:[1,0]
	v_mad_i64_i32 v[104:105], s[0:1], v112, s51, v[158:159]
	v_lshl_add_u64 v[110:111], v[104:105], 0, v[154:155]
	global_load_dwordx4 v[104:107], v[110:111], off
	v_rcp_f32_e32 v100, v118
	v_lshlrev_b32_e32 v118, 16, v113
	v_and_b32_e32 v119, 0xffff0000, v113
	v_pk_fma_f32 v[118:119], v[102:103], v[100:101], v[118:119]
	v_and_b32_e32 v117, 0xffff0000, v129
	v_rcp_f32_e32 v101, v109
	v_mul_f32_e32 v117, 0xbfb8aa3b, v117
	v_exp_f32_e32 v117, v117
	s_nop 0
	v_pk_add_f32 v[116:117], v[116:117], 1.0 op_sel_hi:[1,0]
	v_rcp_f32_e32 v100, v108
	v_lshlrev_b32_e32 v102, 16, v114
	v_and_b32_e32 v103, 0xffff0000, v114
	v_pk_fma_f32 v[122:123], v[96:97], v[100:101], v[102:103]
	v_ashrrev_i32_e32 v113, 31, v112
	v_lshlrev_b64 v[96:97], 11, v[112:113]
	v_lshl_add_u64 v[96:97], s[16:17], 0, v[96:97]
	v_lshl_add_u64 v[108:109], v[96:97], 0, v[154:155]
	global_load_dwordx4 v[100:103], v[108:109], off
	v_rcp_f32_e32 v97, v117
	s_nop 0
	v_rcp_f32_e32 v96, v116
	v_lshlrev_b32_e32 v112, 16, v115
	v_and_b32_e32 v113, 0xffff0000, v115
	v_pk_fma_f32 v[112:113], v[98:99], v[96:97], v[112:113]
	v_cvt_pk_bf16_f32 v96, v120, v121
	v_cvt_pk_bf16_f32 v97, v118, v119
	v_cvt_pk_bf16_f32 v98, v122, v123
	v_cvt_pk_bf16_f32 v99, v112, v113
	global_store_dwordx4 v[124:125], v[96:99], off offset:256
	global_load_dwordx4 v[110:113], v[110:111], off offset:256
	s_waitcnt vmcnt(3)
	v_lshlrev_b32_e32 v96, 16, v104
	v_and_b32_e32 v97, 0xffff0000, v104
	v_mul_f32_e32 v96, 0xbfb8aa3b, v96
	v_mul_f32_e32 v97, 0xbfb8aa3b, v97
	v_exp_f32_e32 v96, v96
	v_exp_f32_e32 v97, v97
	v_lshlrev_b32_e32 v98, 16, v105
	v_and_b32_e32 v99, 0xffff0000, v105
	v_mul_f32_e32 v98, 0xbfb8aa3b, v98
	v_pk_add_f32 v[96:97], v[96:97], 1.0 op_sel_hi:[1,0]
	v_mul_f32_e32 v99, 0xbfb8aa3b, v99
	v_exp_f32_e32 v98, v98
	v_exp_f32_e32 v99, v99
	v_lshlrev_b32_e32 v104, 16, v106
	v_rcp_f32_e32 v115, v97
	v_and_b32_e32 v105, 0xffff0000, v106
	v_pk_add_f32 v[116:117], v[98:99], 1.0 op_sel_hi:[1,0]
	v_rcp_f32_e32 v114, v96
	global_load_dwordx4 v[96:99], v[108:109], off offset:256
	v_mul_f32_e32 v104, 0xbfb8aa3b, v104
	v_mul_f32_e32 v105, 0xbfb8aa3b, v105
	v_exp_f32_e32 v104, v104
	v_exp_f32_e32 v105, v105
	v_lshlrev_b32_e32 v106, 16, v107
	s_waitcnt vmcnt(3)
	v_lshlrev_b32_e32 v118, 16, v100
	v_and_b32_e32 v119, 0xffff0000, v100
	v_pk_fma_f32 v[92:93], v[92:93], v[114:115], v[118:119]
	v_rcp_f32_e32 v115, v117
	v_pk_add_f32 v[104:105], v[104:105], 1.0 op_sel_hi:[1,0]
	v_rcp_f32_e32 v114, v116
	v_lshlrev_b32_e32 v100, 16, v101
	v_and_b32_e32 v101, 0xffff0000, v101
	v_pk_fma_f32 v[94:95], v[94:95], v[114:115], v[100:101]
	v_rcp_f32_e32 v101, v105
	v_and_b32_e32 v107, 0xffff0000, v107
	v_mul_f32_e32 v106, 0xbfb8aa3b, v106
	v_mul_f32_e32 v107, 0xbfb8aa3b, v107
	v_exp_f32_e32 v106, v106
	v_exp_f32_e32 v107, v107
	v_rcp_f32_e32 v100, v104
	v_pk_add_f32 v[104:105], v[106:107], 1.0 op_sel_hi:[1,0]
	v_lshlrev_b32_e32 v106, 16, v102
	v_and_b32_e32 v107, 0xffff0000, v102
	v_pk_fma_f32 v[100:101], v[88:89], v[100:101], v[106:107]
	v_rcp_f32_e32 v89, v105
	s_nop 0
	v_rcp_f32_e32 v88, v104
	v_lshlrev_b32_e32 v102, 16, v103
	v_and_b32_e32 v103, 0xffff0000, v103
	v_pk_fma_f32 v[102:103], v[90:91], v[88:89], v[102:103]
	v_cvt_pk_bf16_f32 v88, v92, v93
	v_cvt_pk_bf16_f32 v89, v94, v95
	v_cvt_pk_bf16_f32 v90, v100, v101
	v_cvt_pk_bf16_f32 v91, v102, v103
	global_store_dwordx4 v[108:109], v[88:91], off
	s_waitcnt vmcnt(2)
	v_lshlrev_b32_e32 v94, 16, v113
	v_mul_f32_e32 v94, 0xbfb8aa3b, v94
	v_lshlrev_b32_e32 v88, 16, v110
	v_and_b32_e32 v89, 0xffff0000, v110
	v_mul_f32_e32 v88, 0xbfb8aa3b, v88
	v_mul_f32_e32 v89, 0xbfb8aa3b, v89
	v_exp_f32_e32 v88, v88
	v_exp_f32_e32 v89, v89
	v_exp_f32_e32 v100, v94
	v_lshlrev_b32_e32 v90, 16, v111
	v_and_b32_e32 v91, 0xffff0000, v111
	v_pk_add_f32 v[88:89], v[88:89], 1.0 op_sel_hi:[1,0]
	v_mul_f32_e32 v90, 0xbfb8aa3b, v90
	v_mul_f32_e32 v91, 0xbfb8aa3b, v91
	v_exp_f32_e32 v90, v90
	v_exp_f32_e32 v91, v91
	v_rcp_f32_e32 v89, v89
	v_lshlrev_b32_e32 v92, 16, v112
	v_pk_add_f32 v[102:103], v[90:91], 1.0 op_sel_hi:[1,0]
	v_rcp_f32_e32 v88, v88
	s_waitcnt vmcnt(1)
	v_lshlrev_b32_e32 v90, 16, v96
	v_and_b32_e32 v91, 0xffff0000, v96
	v_pk_fma_f32 v[104:105], v[84:85], v[88:89], v[90:91]
	v_and_b32_e32 v93, 0xffff0000, v112
	v_mul_f32_e32 v92, 0xbfb8aa3b, v92
	v_mul_f32_e32 v93, 0xbfb8aa3b, v93
	v_rcp_f32_e32 v85, v103
	v_exp_f32_e32 v92, v92
	v_exp_f32_e32 v93, v93
	v_add_u32_e32 v96, s21, v166
	v_pk_add_f32 v[92:93], v[92:93], 1.0 op_sel_hi:[1,0]
	v_mad_i64_i32 v[88:89], s[0:1], v96, s51, v[158:159]
	v_lshl_add_u64 v[94:95], v[88:89], 0, v[154:155]
	global_load_dwordx4 v[88:91], v[94:95], off
	v_rcp_f32_e32 v84, v102
	v_lshlrev_b32_e32 v102, 16, v97
	v_and_b32_e32 v103, 0xffff0000, v97
	v_pk_fma_f32 v[102:103], v[86:87], v[84:85], v[102:103]
	v_and_b32_e32 v101, 0xffff0000, v113
	v_rcp_f32_e32 v85, v93
	v_mul_f32_e32 v101, 0xbfb8aa3b, v101
	v_exp_f32_e32 v101, v101
	s_nop 0
	v_pk_add_f32 v[100:101], v[100:101], 1.0 op_sel_hi:[1,0]
	v_rcp_f32_e32 v84, v92
	v_lshlrev_b32_e32 v86, 16, v98
	v_and_b32_e32 v87, 0xffff0000, v98
	v_pk_fma_f32 v[106:107], v[80:81], v[84:85], v[86:87]
	v_ashrrev_i32_e32 v97, 31, v96
	v_lshlrev_b64 v[80:81], 11, v[96:97]
	v_lshl_add_u64 v[80:81], s[16:17], 0, v[80:81]
	v_lshl_add_u64 v[92:93], v[80:81], 0, v[154:155]
	global_load_dwordx4 v[84:87], v[92:93], off
	v_rcp_f32_e32 v81, v101
	s_nop 0
	v_rcp_f32_e32 v80, v100
	v_lshlrev_b32_e32 v96, 16, v99
	v_and_b32_e32 v97, 0xffff0000, v99
	v_pk_fma_f32 v[96:97], v[82:83], v[80:81], v[96:97]
	v_cvt_pk_bf16_f32 v80, v104, v105
	v_cvt_pk_bf16_f32 v81, v102, v103
	v_cvt_pk_bf16_f32 v82, v106, v107
	v_cvt_pk_bf16_f32 v83, v96, v97
	global_store_dwordx4 v[108:109], v[80:83], off offset:256
	global_load_dwordx4 v[94:97], v[94:95], off offset:256
	s_waitcnt vmcnt(3)
	v_lshlrev_b32_e32 v80, 16, v88
	v_and_b32_e32 v81, 0xffff0000, v88
	v_mul_f32_e32 v80, 0xbfb8aa3b, v80
	v_mul_f32_e32 v81, 0xbfb8aa3b, v81
	v_exp_f32_e32 v80, v80
	v_exp_f32_e32 v81, v81
	v_lshlrev_b32_e32 v82, 16, v89
	v_and_b32_e32 v83, 0xffff0000, v89
	v_mul_f32_e32 v82, 0xbfb8aa3b, v82
	v_pk_add_f32 v[80:81], v[80:81], 1.0 op_sel_hi:[1,0]
	v_mul_f32_e32 v83, 0xbfb8aa3b, v83
	v_exp_f32_e32 v82, v82
	v_exp_f32_e32 v83, v83
	v_lshlrev_b32_e32 v88, 16, v90
	v_rcp_f32_e32 v99, v81
	v_and_b32_e32 v89, 0xffff0000, v90
	v_pk_add_f32 v[100:101], v[82:83], 1.0 op_sel_hi:[1,0]
	v_rcp_f32_e32 v98, v80
	global_load_dwordx4 v[80:83], v[92:93], off offset:256
	v_mul_f32_e32 v88, 0xbfb8aa3b, v88
	v_mul_f32_e32 v89, 0xbfb8aa3b, v89
	v_exp_f32_e32 v88, v88
	v_exp_f32_e32 v89, v89
	v_lshlrev_b32_e32 v90, 16, v91
	s_waitcnt vmcnt(3)
	v_lshlrev_b32_e32 v102, 16, v84
	v_and_b32_e32 v103, 0xffff0000, v84
	v_pk_fma_f32 v[76:77], v[76:77], v[98:99], v[102:103]
	v_rcp_f32_e32 v99, v101
	v_pk_add_f32 v[88:89], v[88:89], 1.0 op_sel_hi:[1,0]
	v_rcp_f32_e32 v98, v100
	v_lshlrev_b32_e32 v84, 16, v85
	v_and_b32_e32 v85, 0xffff0000, v85
	v_pk_fma_f32 v[78:79], v[78:79], v[98:99], v[84:85]
	v_rcp_f32_e32 v85, v89
	v_and_b32_e32 v91, 0xffff0000, v91
	v_mul_f32_e32 v90, 0xbfb8aa3b, v90
	v_mul_f32_e32 v91, 0xbfb8aa3b, v91
	v_exp_f32_e32 v90, v90
	v_exp_f32_e32 v91, v91
	v_rcp_f32_e32 v84, v88
	v_pk_add_f32 v[88:89], v[90:91], 1.0 op_sel_hi:[1,0]
	v_lshlrev_b32_e32 v90, 16, v86
	v_and_b32_e32 v91, 0xffff0000, v86
	v_pk_fma_f32 v[84:85], v[72:73], v[84:85], v[90:91]
	v_rcp_f32_e32 v73, v89
	s_nop 0
	v_rcp_f32_e32 v72, v88
	v_lshlrev_b32_e32 v86, 16, v87
	v_and_b32_e32 v87, 0xffff0000, v87
	v_pk_fma_f32 v[86:87], v[74:75], v[72:73], v[86:87]
	v_cvt_pk_bf16_f32 v72, v76, v77
	v_cvt_pk_bf16_f32 v73, v78, v79
	v_cvt_pk_bf16_f32 v74, v84, v85
	v_cvt_pk_bf16_f32 v75, v86, v87
	global_store_dwordx4 v[92:93], v[72:75], off
	s_waitcnt vmcnt(2)
	v_lshlrev_b32_e32 v78, 16, v97
	v_mul_f32_e32 v78, 0xbfb8aa3b, v78
	v_lshlrev_b32_e32 v72, 16, v94
	v_and_b32_e32 v73, 0xffff0000, v94
	v_mul_f32_e32 v72, 0xbfb8aa3b, v72
	v_mul_f32_e32 v73, 0xbfb8aa3b, v73
	v_exp_f32_e32 v72, v72
	v_exp_f32_e32 v73, v73
	v_exp_f32_e32 v84, v78
	v_lshlrev_b32_e32 v74, 16, v95
	v_and_b32_e32 v75, 0xffff0000, v95
	v_pk_add_f32 v[72:73], v[72:73], 1.0 op_sel_hi:[1,0]
	v_mul_f32_e32 v74, 0xbfb8aa3b, v74
	v_mul_f32_e32 v75, 0xbfb8aa3b, v75
	v_exp_f32_e32 v74, v74
	v_exp_f32_e32 v75, v75
	v_rcp_f32_e32 v73, v73
	v_lshlrev_b32_e32 v76, 16, v96
	v_pk_add_f32 v[86:87], v[74:75], 1.0 op_sel_hi:[1,0]
	v_rcp_f32_e32 v72, v72
	s_waitcnt vmcnt(1)
	v_lshlrev_b32_e32 v74, 16, v80
	v_and_b32_e32 v75, 0xffff0000, v80
	v_pk_fma_f32 v[88:89], v[68:69], v[72:73], v[74:75]
	v_and_b32_e32 v77, 0xffff0000, v96
	v_mul_f32_e32 v76, 0xbfb8aa3b, v76
	v_mul_f32_e32 v77, 0xbfb8aa3b, v77
	v_rcp_f32_e32 v69, v87
	v_exp_f32_e32 v76, v76
	v_exp_f32_e32 v77, v77
	v_add_u32_e32 v80, 0x80, v156
	v_pk_add_f32 v[76:77], v[76:77], 1.0 op_sel_hi:[1,0]
	v_mad_i64_i32 v[72:73], s[0:1], v80, s51, v[158:159]
	v_lshl_add_u64 v[78:79], v[72:73], 0, v[154:155]
	global_load_dwordx4 v[72:75], v[78:79], off
	v_rcp_f32_e32 v68, v86
	v_lshlrev_b32_e32 v86, 16, v81
	v_and_b32_e32 v87, 0xffff0000, v81
	v_pk_fma_f32 v[86:87], v[70:71], v[68:69], v[86:87]
	v_and_b32_e32 v85, 0xffff0000, v97
	v_rcp_f32_e32 v69, v77
	v_mul_f32_e32 v85, 0xbfb8aa3b, v85
	v_exp_f32_e32 v85, v85
	s_nop 0
	v_pk_add_f32 v[84:85], v[84:85], 1.0 op_sel_hi:[1,0]
	v_rcp_f32_e32 v68, v76
	v_lshlrev_b32_e32 v70, 16, v82
	v_and_b32_e32 v71, 0xffff0000, v82
	v_pk_fma_f32 v[90:91], v[64:65], v[68:69], v[70:71]
	v_ashrrev_i32_e32 v81, 31, v80
	v_lshlrev_b64 v[64:65], 11, v[80:81]
	v_lshl_add_u64 v[64:65], s[16:17], 0, v[64:65]
	v_lshl_add_u64 v[76:77], v[64:65], 0, v[154:155]
	global_load_dwordx4 v[68:71], v[76:77], off
	v_rcp_f32_e32 v65, v85
	s_nop 0
	v_rcp_f32_e32 v64, v84
	v_lshlrev_b32_e32 v80, 16, v83
	v_and_b32_e32 v81, 0xffff0000, v83
	v_pk_fma_f32 v[80:81], v[66:67], v[64:65], v[80:81]
	v_cvt_pk_bf16_f32 v64, v88, v89
	v_cvt_pk_bf16_f32 v65, v86, v87
	v_cvt_pk_bf16_f32 v66, v90, v91
	v_cvt_pk_bf16_f32 v67, v80, v81
	global_store_dwordx4 v[92:93], v[64:67], off offset:256
	global_load_dwordx4 v[78:81], v[78:79], off offset:256
	s_waitcnt vmcnt(3)
	v_lshlrev_b32_e32 v64, 16, v72
	v_and_b32_e32 v65, 0xffff0000, v72
	v_mul_f32_e32 v64, 0xbfb8aa3b, v64
	v_mul_f32_e32 v65, 0xbfb8aa3b, v65
	v_exp_f32_e32 v64, v64
	v_exp_f32_e32 v65, v65
	v_lshlrev_b32_e32 v66, 16, v73
	v_and_b32_e32 v67, 0xffff0000, v73
	v_mul_f32_e32 v66, 0xbfb8aa3b, v66
	v_pk_add_f32 v[64:65], v[64:65], 1.0 op_sel_hi:[1,0]
	v_mul_f32_e32 v67, 0xbfb8aa3b, v67
	v_exp_f32_e32 v66, v66
	v_exp_f32_e32 v67, v67
	v_lshlrev_b32_e32 v72, 16, v74
	v_rcp_f32_e32 v83, v65
	v_and_b32_e32 v73, 0xffff0000, v74
	v_pk_add_f32 v[84:85], v[66:67], 1.0 op_sel_hi:[1,0]
	v_rcp_f32_e32 v82, v64
	global_load_dwordx4 v[64:67], v[76:77], off offset:256
	v_mul_f32_e32 v72, 0xbfb8aa3b, v72
	v_mul_f32_e32 v73, 0xbfb8aa3b, v73
	v_exp_f32_e32 v72, v72
	v_exp_f32_e32 v73, v73
	v_lshlrev_b32_e32 v74, 16, v75
	s_waitcnt vmcnt(3)
	v_lshlrev_b32_e32 v86, 16, v68
	v_and_b32_e32 v87, 0xffff0000, v68
	v_pk_fma_f32 v[60:61], v[60:61], v[82:83], v[86:87]
	v_rcp_f32_e32 v83, v85
	v_pk_add_f32 v[72:73], v[72:73], 1.0 op_sel_hi:[1,0]
	v_rcp_f32_e32 v82, v84
	v_lshlrev_b32_e32 v68, 16, v69
	v_and_b32_e32 v69, 0xffff0000, v69
	v_pk_fma_f32 v[62:63], v[62:63], v[82:83], v[68:69]
	v_rcp_f32_e32 v69, v73
	v_and_b32_e32 v75, 0xffff0000, v75
	v_mul_f32_e32 v74, 0xbfb8aa3b, v74
	v_mul_f32_e32 v75, 0xbfb8aa3b, v75
	v_exp_f32_e32 v74, v74
	v_exp_f32_e32 v75, v75
	v_rcp_f32_e32 v68, v72
	v_pk_add_f32 v[72:73], v[74:75], 1.0 op_sel_hi:[1,0]
	v_lshlrev_b32_e32 v74, 16, v70
	v_and_b32_e32 v75, 0xffff0000, v70
	v_pk_fma_f32 v[68:69], v[56:57], v[68:69], v[74:75]
	v_rcp_f32_e32 v57, v73
	s_nop 0
	v_rcp_f32_e32 v56, v72
	v_lshlrev_b32_e32 v70, 16, v71
	v_and_b32_e32 v71, 0xffff0000, v71
	v_pk_fma_f32 v[70:71], v[58:59], v[56:57], v[70:71]
	v_cvt_pk_bf16_f32 v56, v60, v61
	v_cvt_pk_bf16_f32 v57, v62, v63
	v_cvt_pk_bf16_f32 v58, v68, v69
	v_cvt_pk_bf16_f32 v59, v70, v71
	global_store_dwordx4 v[76:77], v[56:59], off
	s_waitcnt vmcnt(2)
	v_lshlrev_b32_e32 v62, 16, v81
	v_mul_f32_e32 v62, 0xbfb8aa3b, v62
	v_lshlrev_b32_e32 v56, 16, v78
	v_and_b32_e32 v57, 0xffff0000, v78
	v_mul_f32_e32 v56, 0xbfb8aa3b, v56
	v_mul_f32_e32 v57, 0xbfb8aa3b, v57
	v_exp_f32_e32 v56, v56
	v_exp_f32_e32 v57, v57
	v_exp_f32_e32 v68, v62
	v_lshlrev_b32_e32 v58, 16, v79
	v_and_b32_e32 v59, 0xffff0000, v79
	v_pk_add_f32 v[56:57], v[56:57], 1.0 op_sel_hi:[1,0]
	v_mul_f32_e32 v58, 0xbfb8aa3b, v58
	v_mul_f32_e32 v59, 0xbfb8aa3b, v59
	v_exp_f32_e32 v58, v58
	v_exp_f32_e32 v59, v59
	v_rcp_f32_e32 v57, v57
	v_lshlrev_b32_e32 v60, 16, v80
	v_pk_add_f32 v[70:71], v[58:59], 1.0 op_sel_hi:[1,0]
	v_rcp_f32_e32 v56, v56
	s_waitcnt vmcnt(1)
	v_lshlrev_b32_e32 v58, 16, v64
	v_and_b32_e32 v59, 0xffff0000, v64
	v_pk_fma_f32 v[72:73], v[52:53], v[56:57], v[58:59]
	v_and_b32_e32 v61, 0xffff0000, v80
	v_mul_f32_e32 v60, 0xbfb8aa3b, v60
	v_mul_f32_e32 v61, 0xbfb8aa3b, v61
	v_rcp_f32_e32 v53, v71
	v_exp_f32_e32 v60, v60
	v_exp_f32_e32 v61, v61
	v_add_u32_e32 v64, 0x90, v156
	v_pk_add_f32 v[60:61], v[60:61], 1.0 op_sel_hi:[1,0]
	v_mad_i64_i32 v[56:57], s[0:1], v64, s51, v[158:159]
	v_lshl_add_u64 v[62:63], v[56:57], 0, v[154:155]
	global_load_dwordx4 v[56:59], v[62:63], off
	v_rcp_f32_e32 v52, v70
	v_lshlrev_b32_e32 v70, 16, v65
	v_and_b32_e32 v71, 0xffff0000, v65
	v_pk_fma_f32 v[70:71], v[54:55], v[52:53], v[70:71]
	v_and_b32_e32 v69, 0xffff0000, v81
	v_rcp_f32_e32 v53, v61
	v_mul_f32_e32 v69, 0xbfb8aa3b, v69
	v_exp_f32_e32 v69, v69
	s_nop 0
	v_pk_add_f32 v[68:69], v[68:69], 1.0 op_sel_hi:[1,0]
	v_rcp_f32_e32 v52, v60
	v_lshlrev_b32_e32 v54, 16, v66
	v_and_b32_e32 v55, 0xffff0000, v66
	v_pk_fma_f32 v[74:75], v[48:49], v[52:53], v[54:55]
	v_ashrrev_i32_e32 v65, 31, v64
	v_lshlrev_b64 v[48:49], 11, v[64:65]
	v_lshl_add_u64 v[48:49], s[16:17], 0, v[48:49]
	v_lshl_add_u64 v[60:61], v[48:49], 0, v[154:155]
	global_load_dwordx4 v[52:55], v[60:61], off
	v_rcp_f32_e32 v49, v69
	s_nop 0
	v_rcp_f32_e32 v48, v68
	v_lshlrev_b32_e32 v64, 16, v67
	v_and_b32_e32 v65, 0xffff0000, v67
	v_pk_fma_f32 v[64:65], v[50:51], v[48:49], v[64:65]
	v_cvt_pk_bf16_f32 v48, v72, v73
	v_cvt_pk_bf16_f32 v49, v70, v71
	v_cvt_pk_bf16_f32 v50, v74, v75
	v_cvt_pk_bf16_f32 v51, v64, v65
	global_store_dwordx4 v[76:77], v[48:51], off offset:256
	global_load_dwordx4 v[62:65], v[62:63], off offset:256
	s_waitcnt vmcnt(3)
	v_lshlrev_b32_e32 v48, 16, v56
	v_and_b32_e32 v49, 0xffff0000, v56
	v_mul_f32_e32 v48, 0xbfb8aa3b, v48
	v_mul_f32_e32 v49, 0xbfb8aa3b, v49
	v_exp_f32_e32 v48, v48
	v_exp_f32_e32 v49, v49
	v_lshlrev_b32_e32 v50, 16, v57
	v_and_b32_e32 v51, 0xffff0000, v57
	v_mul_f32_e32 v50, 0xbfb8aa3b, v50
	v_pk_add_f32 v[48:49], v[48:49], 1.0 op_sel_hi:[1,0]
	v_mul_f32_e32 v51, 0xbfb8aa3b, v51
	v_exp_f32_e32 v50, v50
	v_exp_f32_e32 v51, v51
	v_lshlrev_b32_e32 v56, 16, v58
	v_rcp_f32_e32 v67, v49
	v_and_b32_e32 v57, 0xffff0000, v58
	v_pk_add_f32 v[68:69], v[50:51], 1.0 op_sel_hi:[1,0]
	v_rcp_f32_e32 v66, v48
	global_load_dwordx4 v[48:51], v[60:61], off offset:256
	v_mul_f32_e32 v56, 0xbfb8aa3b, v56
	v_mul_f32_e32 v57, 0xbfb8aa3b, v57
	v_exp_f32_e32 v56, v56
	v_exp_f32_e32 v57, v57
	v_lshlrev_b32_e32 v58, 16, v59
	s_waitcnt vmcnt(3)
	v_lshlrev_b32_e32 v70, 16, v52
	v_and_b32_e32 v71, 0xffff0000, v52
	v_pk_fma_f32 v[44:45], v[44:45], v[66:67], v[70:71]
	v_rcp_f32_e32 v67, v69
	v_pk_add_f32 v[56:57], v[56:57], 1.0 op_sel_hi:[1,0]
	v_rcp_f32_e32 v66, v68
	v_lshlrev_b32_e32 v52, 16, v53
	v_and_b32_e32 v53, 0xffff0000, v53
	v_pk_fma_f32 v[46:47], v[46:47], v[66:67], v[52:53]
	v_rcp_f32_e32 v53, v57
	v_and_b32_e32 v59, 0xffff0000, v59
	v_mul_f32_e32 v58, 0xbfb8aa3b, v58
	v_mul_f32_e32 v59, 0xbfb8aa3b, v59
	v_exp_f32_e32 v58, v58
	v_exp_f32_e32 v59, v59
	v_rcp_f32_e32 v52, v56
	v_pk_add_f32 v[56:57], v[58:59], 1.0 op_sel_hi:[1,0]
	v_lshlrev_b32_e32 v58, 16, v54
	v_and_b32_e32 v59, 0xffff0000, v54
	v_pk_fma_f32 v[52:53], v[40:41], v[52:53], v[58:59]
	v_rcp_f32_e32 v41, v57
	s_nop 0
	v_rcp_f32_e32 v40, v56
	v_lshlrev_b32_e32 v54, 16, v55
	v_and_b32_e32 v55, 0xffff0000, v55
	v_pk_fma_f32 v[54:55], v[42:43], v[40:41], v[54:55]
	v_cvt_pk_bf16_f32 v40, v44, v45
	v_cvt_pk_bf16_f32 v41, v46, v47
	v_cvt_pk_bf16_f32 v42, v52, v53
	v_cvt_pk_bf16_f32 v43, v54, v55
	global_store_dwordx4 v[60:61], v[40:43], off
	s_waitcnt vmcnt(2)
	v_lshlrev_b32_e32 v46, 16, v65
	v_mul_f32_e32 v46, 0xbfb8aa3b, v46
	v_lshlrev_b32_e32 v40, 16, v62
	v_and_b32_e32 v41, 0xffff0000, v62
	v_mul_f32_e32 v40, 0xbfb8aa3b, v40
	v_mul_f32_e32 v41, 0xbfb8aa3b, v41
	v_exp_f32_e32 v40, v40
	v_exp_f32_e32 v41, v41
	v_exp_f32_e32 v52, v46
	v_lshlrev_b32_e32 v42, 16, v63
	v_and_b32_e32 v43, 0xffff0000, v63
	v_pk_add_f32 v[40:41], v[40:41], 1.0 op_sel_hi:[1,0]
	v_mul_f32_e32 v42, 0xbfb8aa3b, v42
	v_mul_f32_e32 v43, 0xbfb8aa3b, v43
	v_exp_f32_e32 v42, v42
	v_exp_f32_e32 v43, v43
	v_rcp_f32_e32 v41, v41
	v_lshlrev_b32_e32 v44, 16, v64
	v_pk_add_f32 v[54:55], v[42:43], 1.0 op_sel_hi:[1,0]
	v_rcp_f32_e32 v40, v40
	s_waitcnt vmcnt(1)
	v_lshlrev_b32_e32 v42, 16, v48
	v_and_b32_e32 v43, 0xffff0000, v48
	v_pk_fma_f32 v[56:57], v[36:37], v[40:41], v[42:43]
	v_and_b32_e32 v45, 0xffff0000, v64
	v_mul_f32_e32 v44, 0xbfb8aa3b, v44
	v_mul_f32_e32 v45, 0xbfb8aa3b, v45
	v_rcp_f32_e32 v37, v55
	v_exp_f32_e32 v44, v44
	v_exp_f32_e32 v45, v45
	v_add_u32_e32 v48, 0xa0, v156
	v_pk_add_f32 v[44:45], v[44:45], 1.0 op_sel_hi:[1,0]
	v_mad_i64_i32 v[40:41], s[0:1], v48, s51, v[158:159]
	v_lshl_add_u64 v[46:47], v[40:41], 0, v[154:155]
	global_load_dwordx4 v[40:43], v[46:47], off
	v_rcp_f32_e32 v36, v54
	v_lshlrev_b32_e32 v54, 16, v49
	v_and_b32_e32 v55, 0xffff0000, v49
	v_pk_fma_f32 v[54:55], v[38:39], v[36:37], v[54:55]
	v_and_b32_e32 v53, 0xffff0000, v65
	v_rcp_f32_e32 v37, v45
	v_mul_f32_e32 v53, 0xbfb8aa3b, v53
	v_exp_f32_e32 v53, v53
	s_nop 0
	v_pk_add_f32 v[52:53], v[52:53], 1.0 op_sel_hi:[1,0]
	v_rcp_f32_e32 v36, v44
	v_lshlrev_b32_e32 v38, 16, v50
	v_and_b32_e32 v39, 0xffff0000, v50
	v_pk_fma_f32 v[58:59], v[32:33], v[36:37], v[38:39]
	v_ashrrev_i32_e32 v49, 31, v48
	v_lshlrev_b64 v[32:33], 11, v[48:49]
	v_lshl_add_u64 v[32:33], s[16:17], 0, v[32:33]
	v_lshl_add_u64 v[44:45], v[32:33], 0, v[154:155]
	global_load_dwordx4 v[36:39], v[44:45], off
	v_rcp_f32_e32 v33, v53
	s_nop 0
	v_rcp_f32_e32 v32, v52
	v_lshlrev_b32_e32 v48, 16, v51
	v_and_b32_e32 v49, 0xffff0000, v51
	v_pk_fma_f32 v[48:49], v[34:35], v[32:33], v[48:49]
	v_cvt_pk_bf16_f32 v32, v56, v57
	v_cvt_pk_bf16_f32 v33, v54, v55
	v_cvt_pk_bf16_f32 v34, v58, v59
	v_cvt_pk_bf16_f32 v35, v48, v49
	global_store_dwordx4 v[60:61], v[32:35], off offset:256
	global_load_dwordx4 v[46:49], v[46:47], off offset:256
	s_waitcnt vmcnt(3)
	v_lshlrev_b32_e32 v32, 16, v40
	v_and_b32_e32 v33, 0xffff0000, v40
	v_mul_f32_e32 v32, 0xbfb8aa3b, v32
	v_mul_f32_e32 v33, 0xbfb8aa3b, v33
	v_exp_f32_e32 v32, v32
	v_exp_f32_e32 v33, v33
	v_lshlrev_b32_e32 v34, 16, v41
	v_and_b32_e32 v35, 0xffff0000, v41
	v_mul_f32_e32 v34, 0xbfb8aa3b, v34
	v_pk_add_f32 v[32:33], v[32:33], 1.0 op_sel_hi:[1,0]
	v_mul_f32_e32 v35, 0xbfb8aa3b, v35
	v_exp_f32_e32 v34, v34
	v_exp_f32_e32 v35, v35
	v_lshlrev_b32_e32 v40, 16, v42
	v_rcp_f32_e32 v51, v33
	v_and_b32_e32 v41, 0xffff0000, v42
	v_pk_add_f32 v[52:53], v[34:35], 1.0 op_sel_hi:[1,0]
	v_rcp_f32_e32 v50, v32
	global_load_dwordx4 v[32:35], v[44:45], off offset:256
	v_mul_f32_e32 v40, 0xbfb8aa3b, v40
	v_mul_f32_e32 v41, 0xbfb8aa3b, v41
	v_exp_f32_e32 v40, v40
	v_exp_f32_e32 v41, v41
	v_lshlrev_b32_e32 v42, 16, v43
	s_waitcnt vmcnt(3)
	v_lshlrev_b32_e32 v54, 16, v36
	v_and_b32_e32 v55, 0xffff0000, v36
	v_pk_fma_f32 v[28:29], v[28:29], v[50:51], v[54:55]
	v_rcp_f32_e32 v51, v53
	v_pk_add_f32 v[40:41], v[40:41], 1.0 op_sel_hi:[1,0]
	v_rcp_f32_e32 v50, v52
	v_lshlrev_b32_e32 v36, 16, v37
	v_and_b32_e32 v37, 0xffff0000, v37
	v_pk_fma_f32 v[30:31], v[30:31], v[50:51], v[36:37]
	v_rcp_f32_e32 v37, v41
	v_and_b32_e32 v43, 0xffff0000, v43
	v_mul_f32_e32 v42, 0xbfb8aa3b, v42
	v_mul_f32_e32 v43, 0xbfb8aa3b, v43
	v_exp_f32_e32 v42, v42
	v_exp_f32_e32 v43, v43
	v_rcp_f32_e32 v36, v40
	v_pk_add_f32 v[40:41], v[42:43], 1.0 op_sel_hi:[1,0]
	v_lshlrev_b32_e32 v42, 16, v38
	v_and_b32_e32 v43, 0xffff0000, v38
	v_pk_fma_f32 v[36:37], v[24:25], v[36:37], v[42:43]
	v_rcp_f32_e32 v25, v41
	s_nop 0
	v_rcp_f32_e32 v24, v40
	v_lshlrev_b32_e32 v38, 16, v39
	v_and_b32_e32 v39, 0xffff0000, v39
	v_pk_fma_f32 v[38:39], v[26:27], v[24:25], v[38:39]
	v_cvt_pk_bf16_f32 v24, v28, v29
	v_cvt_pk_bf16_f32 v25, v30, v31
	v_cvt_pk_bf16_f32 v26, v36, v37
	v_cvt_pk_bf16_f32 v27, v38, v39
	global_store_dwordx4 v[44:45], v[24:27], off
	s_waitcnt vmcnt(2)
	v_lshlrev_b32_e32 v30, 16, v49
	v_mul_f32_e32 v30, 0xbfb8aa3b, v30
	v_lshlrev_b32_e32 v24, 16, v46
	v_and_b32_e32 v25, 0xffff0000, v46
	v_mul_f32_e32 v24, 0xbfb8aa3b, v24
	v_mul_f32_e32 v25, 0xbfb8aa3b, v25
	v_exp_f32_e32 v24, v24
	v_exp_f32_e32 v25, v25
	v_exp_f32_e32 v36, v30
	v_lshlrev_b32_e32 v26, 16, v47
	v_and_b32_e32 v27, 0xffff0000, v47
	v_pk_add_f32 v[24:25], v[24:25], 1.0 op_sel_hi:[1,0]
	v_mul_f32_e32 v26, 0xbfb8aa3b, v26
	v_mul_f32_e32 v27, 0xbfb8aa3b, v27
	v_exp_f32_e32 v26, v26
	v_exp_f32_e32 v27, v27
	v_rcp_f32_e32 v25, v25
	v_lshlrev_b32_e32 v28, 16, v48
	v_pk_add_f32 v[38:39], v[26:27], 1.0 op_sel_hi:[1,0]
	v_rcp_f32_e32 v24, v24
	s_waitcnt vmcnt(1)
	v_lshlrev_b32_e32 v26, 16, v32
	v_and_b32_e32 v27, 0xffff0000, v32
	v_pk_fma_f32 v[40:41], v[20:21], v[24:25], v[26:27]
	v_and_b32_e32 v29, 0xffff0000, v48
	v_mul_f32_e32 v28, 0xbfb8aa3b, v28
	v_mul_f32_e32 v29, 0xbfb8aa3b, v29
	v_rcp_f32_e32 v21, v39
	v_exp_f32_e32 v28, v28
	v_exp_f32_e32 v29, v29
	v_add_u32_e32 v32, 0xb0, v156
	v_pk_add_f32 v[28:29], v[28:29], 1.0 op_sel_hi:[1,0]
	v_mad_i64_i32 v[24:25], s[0:1], v32, s51, v[158:159]
	v_lshl_add_u64 v[30:31], v[24:25], 0, v[154:155]
	global_load_dwordx4 v[24:27], v[30:31], off
	v_rcp_f32_e32 v20, v38
	v_lshlrev_b32_e32 v38, 16, v33
	v_and_b32_e32 v39, 0xffff0000, v33
	v_pk_fma_f32 v[38:39], v[22:23], v[20:21], v[38:39]
	v_and_b32_e32 v37, 0xffff0000, v49
	v_rcp_f32_e32 v21, v29
	v_mul_f32_e32 v37, 0xbfb8aa3b, v37
	v_exp_f32_e32 v37, v37
	s_nop 0
	v_pk_add_f32 v[36:37], v[36:37], 1.0 op_sel_hi:[1,0]
	v_rcp_f32_e32 v20, v28
	v_lshlrev_b32_e32 v22, 16, v34
	v_and_b32_e32 v23, 0xffff0000, v34
	v_pk_fma_f32 v[42:43], v[16:17], v[20:21], v[22:23]
	v_ashrrev_i32_e32 v33, 31, v32
	v_lshlrev_b64 v[16:17], 11, v[32:33]
	v_lshl_add_u64 v[16:17], s[16:17], 0, v[16:17]
	v_lshl_add_u64 v[28:29], v[16:17], 0, v[154:155]
	global_load_dwordx4 v[20:23], v[28:29], off
	v_rcp_f32_e32 v17, v37
	s_nop 0
	v_rcp_f32_e32 v16, v36
	v_lshlrev_b32_e32 v32, 16, v35
	v_and_b32_e32 v33, 0xffff0000, v35
	v_pk_fma_f32 v[32:33], v[18:19], v[16:17], v[32:33]
	v_cvt_pk_bf16_f32 v16, v40, v41
	v_cvt_pk_bf16_f32 v17, v38, v39
	v_cvt_pk_bf16_f32 v18, v42, v43
	v_cvt_pk_bf16_f32 v19, v32, v33
	global_store_dwordx4 v[44:45], v[16:19], off offset:256
	global_load_dwordx4 v[30:33], v[30:31], off offset:256
	s_waitcnt vmcnt(3)
	v_lshlrev_b32_e32 v16, 16, v24
	v_and_b32_e32 v17, 0xffff0000, v24
	v_mul_f32_e32 v16, 0xbfb8aa3b, v16
	v_mul_f32_e32 v17, 0xbfb8aa3b, v17
	v_exp_f32_e32 v16, v16
	v_exp_f32_e32 v17, v17
	v_lshlrev_b32_e32 v18, 16, v25
	v_and_b32_e32 v19, 0xffff0000, v25
	v_mul_f32_e32 v18, 0xbfb8aa3b, v18
	v_pk_add_f32 v[16:17], v[16:17], 1.0 op_sel_hi:[1,0]
	v_mul_f32_e32 v19, 0xbfb8aa3b, v19
	v_exp_f32_e32 v18, v18
	v_exp_f32_e32 v19, v19
	v_lshlrev_b32_e32 v24, 16, v26
	v_rcp_f32_e32 v35, v17
	v_and_b32_e32 v25, 0xffff0000, v26
	v_pk_add_f32 v[36:37], v[18:19], 1.0 op_sel_hi:[1,0]
	v_rcp_f32_e32 v34, v16
	global_load_dwordx4 v[16:19], v[28:29], off offset:256
	v_mul_f32_e32 v24, 0xbfb8aa3b, v24
	v_mul_f32_e32 v25, 0xbfb8aa3b, v25
	v_exp_f32_e32 v24, v24
	v_exp_f32_e32 v25, v25
	v_lshlrev_b32_e32 v26, 16, v27
	s_waitcnt vmcnt(3)
	v_lshlrev_b32_e32 v38, 16, v20
	v_and_b32_e32 v39, 0xffff0000, v20
	v_pk_fma_f32 v[12:13], v[12:13], v[34:35], v[38:39]
	v_rcp_f32_e32 v35, v37
	v_pk_add_f32 v[24:25], v[24:25], 1.0 op_sel_hi:[1,0]
	v_rcp_f32_e32 v34, v36
	v_lshlrev_b32_e32 v20, 16, v21
	v_and_b32_e32 v21, 0xffff0000, v21
	v_pk_fma_f32 v[14:15], v[14:15], v[34:35], v[20:21]
	v_rcp_f32_e32 v21, v25
	v_and_b32_e32 v27, 0xffff0000, v27
	v_mul_f32_e32 v26, 0xbfb8aa3b, v26
	v_mul_f32_e32 v27, 0xbfb8aa3b, v27
	v_exp_f32_e32 v26, v26
	v_exp_f32_e32 v27, v27
	v_rcp_f32_e32 v20, v24
	v_pk_add_f32 v[24:25], v[26:27], 1.0 op_sel_hi:[1,0]
	v_lshlrev_b32_e32 v26, 16, v22
	v_and_b32_e32 v27, 0xffff0000, v22
	v_pk_fma_f32 v[20:21], v[8:9], v[20:21], v[26:27]
	v_rcp_f32_e32 v9, v25
	s_nop 0
	v_rcp_f32_e32 v8, v24
	v_lshlrev_b32_e32 v22, 16, v23
	v_and_b32_e32 v23, 0xffff0000, v23
	v_pk_fma_f32 v[22:23], v[10:11], v[8:9], v[22:23]
	v_cvt_pk_bf16_f32 v8, v12, v13
	v_cvt_pk_bf16_f32 v9, v14, v15
	v_cvt_pk_bf16_f32 v10, v20, v21
	v_cvt_pk_bf16_f32 v11, v22, v23
	global_store_dwordx4 v[28:29], v[8:11], off
	s_waitcnt vmcnt(2)
	v_lshlrev_b32_e32 v12, 16, v32
	v_and_b32_e32 v13, 0xffff0000, v32
	v_lshlrev_b32_e32 v8, 16, v30
	v_and_b32_e32 v9, 0xffff0000, v30
	v_mul_f32_e32 v8, 0xbfb8aa3b, v8
	v_mul_f32_e32 v9, 0xbfb8aa3b, v9
	v_exp_f32_e32 v8, v8
	v_exp_f32_e32 v9, v9
	v_lshlrev_b32_e32 v10, 16, v31
	v_and_b32_e32 v11, 0xffff0000, v31
	v_mul_f32_e32 v10, 0xbfb8aa3b, v10
	v_pk_add_f32 v[8:9], v[8:9], 1.0 op_sel_hi:[1,0]
	v_mul_f32_e32 v11, 0xbfb8aa3b, v11
	v_exp_f32_e32 v10, v10
	v_exp_f32_e32 v11, v11
	v_mul_f32_e32 v12, 0xbfb8aa3b, v12
	v_rcp_f32_e32 v9, v9
	v_pk_add_f32 v[10:11], v[10:11], 1.0 op_sel_hi:[1,0]
	v_rcp_f32_e32 v8, v8
	s_waitcnt vmcnt(1)
	v_lshlrev_b32_e32 v20, 16, v16
	v_and_b32_e32 v21, 0xffff0000, v16
	v_pk_fma_f32 v[4:5], v[4:5], v[8:9], v[20:21]
	v_rcp_f32_e32 v9, v11
	v_mul_f32_e32 v13, 0xbfb8aa3b, v13
	v_exp_f32_e32 v12, v12
	v_exp_f32_e32 v13, v13
	v_rcp_f32_e32 v8, v10
	v_pk_add_f32 v[10:11], v[12:13], 1.0 op_sel_hi:[1,0]
	v_lshlrev_b32_e32 v12, 16, v17
	v_and_b32_e32 v13, 0xffff0000, v17
	v_pk_fma_f32 v[6:7], v[6:7], v[8:9], v[12:13]
	v_lshlrev_b32_e32 v14, 16, v33
	v_rcp_f32_e32 v9, v11
	v_and_b32_e32 v15, 0xffff0000, v33
	v_mul_f32_e32 v14, 0xbfb8aa3b, v14
	v_mul_f32_e32 v15, 0xbfb8aa3b, v15
	v_exp_f32_e32 v14, v14
	v_exp_f32_e32 v15, v15
	v_rcp_f32_e32 v8, v10
	v_pk_add_f32 v[10:11], v[14:15], 1.0 op_sel_hi:[1,0]
	v_lshlrev_b32_e32 v12, 16, v18
	v_and_b32_e32 v13, 0xffff0000, v18
	v_pk_fma_f32 v[8:9], v[0:1], v[8:9], v[12:13]
	v_rcp_f32_e32 v1, v11
	s_nop 0
	v_rcp_f32_e32 v0, v10
	v_lshlrev_b32_e32 v10, 16, v19
	v_and_b32_e32 v11, 0xffff0000, v19
	v_pk_fma_f32 v[10:11], v[2:3], v[0:1], v[10:11]
	v_cvt_pk_bf16_f32 v0, v4, v5
	v_cvt_pk_bf16_f32 v1, v6, v7
	v_cvt_pk_bf16_f32 v2, v8, v9
	v_cvt_pk_bf16_f32 v3, v10, v11
	s_andn2_b64 vcc, exec, s[2:3]
	s_mov_b64 s[0:1], -1
	global_store_dwordx4 v[28:29], v[0:3], off offset:256
	s_cbranch_vccnz .LBB0_920
	s_andn2_b64 vcc, exec, s[10:11]
	s_cbranch_vccnz .LBB0_919
	s_barrier
	s_branch .LBB0_919

	.amdhsa_kernel _Z6mk_fwd4Args
		.amdhsa_group_segment_fixed_size 0
		.amdhsa_private_segment_fixed_size 0
		.amdhsa_kernarg_size 480
		.amdhsa_user_sgpr_count 2
		.amdhsa_user_sgpr_dispatch_ptr 0
		.amdhsa_user_sgpr_queue_ptr 0
		.amdhsa_user_sgpr_kernarg_segment_ptr 1
		.amdhsa_user_sgpr_dispatch_id 0
		.amdhsa_user_sgpr_kernarg_preload_length 0
		.amdhsa_user_sgpr_kernarg_preload_offset 0
		.amdhsa_user_sgpr_private_segment_size 0
		.amdhsa_uses_dynamic_stack 0
		.amdhsa_enable_private_segment 0
		.amdhsa_system_sgpr_workgroup_id_x 1
		.amdhsa_system_sgpr_workgroup_id_y 0
		.amdhsa_system_sgpr_workgroup_id_z 0
		.amdhsa_system_sgpr_workgroup_info 0
		.amdhsa_system_vgpr_workitem_id 2
		.amdhsa_next_free_vgpr 248
		.amdhsa_next_free_sgpr 102
		.amdhsa_accum_offset 248
		.amdhsa_reserve_vcc 1
		.amdhsa_float_round_mode_32 0
		.amdhsa_float_round_mode_16_64 0
		.amdhsa_float_denorm_mode_32 3
		.amdhsa_float_denorm_mode_16_64 3
		.amdhsa_dx10_clamp 1
		.amdhsa_ieee_mode 1
		.amdhsa_fp16_overflow 0
		.amdhsa_tg_split 0
		.amdhsa_exception_fp_ieee_invalid_op 0
		.amdhsa_exception_fp_denorm_src 0
		.amdhsa_exception_fp_ieee_div_zero 0
		.amdhsa_exception_fp_ieee_overflow 0
		.amdhsa_exception_fp_ieee_underflow 0
		.amdhsa_exception_fp_ieee_inexact 0
		.amdhsa_exception_int_div_zero 0
	.end_amdhsa_kernel

amdhsa.kernels:
  - .agpr_count:     0
    .args:
      - .offset:         0
        .size:           224
        .value_kind:     by_value
      - .offset:         224
        .size:           4
        .value_kind:     hidden_block_count_x
      - .offset:         228
        .size:           4
        .value_kind:     hidden_block_count_y
      - .offset:         232
        .size:           4
        .value_kind:     hidden_block_count_z
      - .offset:         236
        .size:           2
        .value_kind:     hidden_group_size_x
      - .offset:         238
        .size:           2
        .value_kind:     hidden_group_size_y
      - .offset:         240
        .size:           2
        .value_kind:     hidden_group_size_z
      - .offset:         242
        .size:           2
        .value_kind:     hidden_remainder_x
      - .offset:         244
        .size:           2
        .value_kind:     hidden_remainder_y
      - .offset:         246
        .size:           2
        .value_kind:     hidden_remainder_z
      - .offset:         264
        .size:           8
        .value_kind:     hidden_global_offset_x
      - .offset:         272
        .size:           8
        .value_kind:     hidden_global_offset_y
      - .offset:         280
        .size:           8
        .value_kind:     hidden_global_offset_z
      - .offset:         288
        .size:           2
        .value_kind:     hidden_grid_dims
      - .offset:         312
        .size:           8
        .value_kind:     hidden_multigrid_sync_arg
      - .offset:         344
        .size:           4
        .value_kind:     hidden_dynamic_lds_size
    .group_segment_fixed_size: 0
    .kernarg_segment_align: 8
    .kernarg_segment_size: 480
    .language:       OpenCL C
    .language_version:
      - 2
      - 0
    .max_flat_workgroup_size: 512
    .name:           _Z6mk_fwd4Args
    .private_segment_fixed_size: 0
    .sgpr_count:     108
    .sgpr_spill_count: 30
    .symbol:         _Z6mk_fwd4Args.kd
    .uniform_work_group_size: 1
    .uses_dynamic_stack: false
    .vgpr_count:     248
    .vgpr_spill_count: 0
    .wavefront_size: 64
